# GEMM loops: B-fragment LDS read addresses use one precomputed base VGPR + immediate offsets; last in-loop DMA load converted to SGPR-base form
# baseline (speedup 1.0000x reference)
; #define PG8_STAGE(bufoff, gbase, voff) do { _Pragma("unroll") for (int _i = 0; _i < 2; ++_i) \
;         __builtin_amdgcn_global_load_lds((const unsigned*)((const char*)(gbase) + (voff)[_i]), (LAS unsigned*)(lds + (bufoff) + ldsw + _i * 8192), 16, 0, 0); } while (0)
; #define PG8_WAIT_V(n) asm volatile("s_waitcnt vmcnt(" #n ")" ::: "memory")
; #define PG8_BAR __builtin_amdgcn_s_barrier()
; template <class Epi>
; __device__ __forceinline__ void gemm_phase(LAS unsigned char* lds, const Gemm g, const StaticOrder S, const Epi E) {
;     ...
;     const int aoff = lds_byte(wr * 64 + fr, fq * 8), boff = lds_byte(wc * 32 + fr, fq * 8);
;     ...
;     PG8_STAGE(PG8_SB(0, 0), cB, voffB); PG8_STAGE(PG8_SB(0, 1), cB + hstepB, voffB); PG8_STAGE(PG8_SA(0, 0), cA, voffA); PG8_STAGE(PG8_SA(0, 1), cA + hstepA, voffA);
;     if (wr == 1) PG8_BAR;
;     PG8_WAIT_V(2); PG8_BAR;
;     PG8_STAGE(PG8_SB(1, 0), cB + ksc, voffB); PG8_STAGE(PG8_SA(1, 0), cA + ksc, voffA); PG8_STAGE(PG8_SB(1, 1), cB + hstepB + ksc, voffB);
;     PG8_WAIT_V(6); PG8_BAR;
.LBB0_115:
	s_lshl_b32 s9, s9, 5
	s_mov_b64 s[26:27], 0x80
	s_and_b32 s14, s9, 0x60
	s_add_i32 m0, s21, 0x18000
	v_lshl_add_u64 v[6:7], v[6:7], 0, s[26:27]
	s_lshl_b32 s10, s8, 13
	s_lshl_b32 s9, s14, 7
	s_waitcnt vmcnt(2)
	s_barrier
	global_load_lds_dwordx4 v[6:7], off
	v_lshl_add_u64 v[4:5], v[4:5], 0, s[26:27]
	s_add_i32 m0, s21, 0x1a000
	s_add_i32 s53, s21, 0x8000
	s_add_i32 s54, s21, 0xa000
	global_load_lds_dwordx4 v[4:5], off
	v_lshl_add_u64 v[0:1], v[0:1], 0, s[26:27]
	s_mov_b32 m0, s53
	s_add_u32 s12, s22, 0x80080
	global_load_lds_dwordx4 v[0:1], off
	v_lshl_add_u64 v[0:1], v[2:3], 0, s[26:27]
	s_mov_b32 m0, s54
	s_addc_u32 s13, s23, 0
	global_load_lds_dwordx4 v[0:1], off
	s_add_i32 m0, s21, 0x1c000
	s_nop 0
	global_load_lds_dwordx4 v132, s[12:13]
	s_add_i32 m0, s21, 0x1e000
	v_lshlrev_b32_e32 v2, 2, v224
	global_load_lds_dwordx4 v128, s[12:13]
	v_and_b32_e32 v0, 15, v224
	v_lshlrev_b32_e32 v1, 1, v8
	s_sext_i32_i16 s61, s0
	v_lshl_or_b32 v142, s8, 6, v0
	v_lshl_or_b32 v0, v0, 6, v1
	v_and_b32_e32 v2, 32, v2
	v_lshlrev_b32_e32 v3, 6, v224
	s_movk_i32 s0, 0x3c0
	s_waitcnt vmcnt(6)
	s_ashr_i32 s55, s78, 31
	v_bitop3_b32 v0, v0, s10, v2 bitop3:0xde
	v_and_or_b32 v1, v3, s0, v1
	s_cmpk_lt_u32 s1, 0x100
	v_bitop3_b32 v143, s9, v1, v2 bitop3:0xf6
	v_add_u32_e32 v254, 0x10000, v143
	s_cselect_b64 s[8:9], -1, 0
	v_or_b32_e32 v144, s14, v8
	v_mov_b64_e32 v[136:137], 0xb00
	v_mov_b64_e32 v[138:139], 0xaff
	s_movk_i32 s56, 0xff80
	s_add_i32 s57, 0, 0x10000
	s_add_i32 s58, 0, 0x14000
	v_add_u32_e32 v145, 0, v0
	s_movk_i32 s59, 0x2c00
	v_mov_b32_e32 v146, 0x358637bd
	s_barrier
	s_branch .LBB0_118

; #define PG8_STAGE(bufoff, gbase, voff) do { _Pragma("unroll") for (int _i = 0; _i < 2; ++_i) \
;         __builtin_amdgcn_global_load_lds((const unsigned*)((const char*)(gbase) + (voff)[_i]), (LAS unsigned*)(lds + (bufoff) + ldsw + _i * 8192), 16, 0, 0); } while (0)
; #define PG8_LDA(dst, b, h) do { _Pragma("unroll") for (int m = 0; m < 4; ++m) _Pragma("unroll") for (int k = 0; k < 2; ++k) dst[m][k] = *(const LAS bf16x8*)(lds + PG8_SA(b, h) + aoff + m * 2048 + k * 1024); } while (0)
; #define PG8_LDB(dst, b, h) do { _Pragma("unroll") for (int n = 0; n < 2; ++n) _Pragma("unroll") for (int k = 0; k < 2; ++k) dst[n][k] = *(const LAS bf16x8*)(lds + PG8_SB(b, h) + boff + n * 2048 + k * 1024); } while (0)
; #define PG8_MMA(ai, bj, At, Bt) do { __builtin_amdgcn_s_setprio(1); _Pragma("unroll") for (int m = 0; m < 4; ++m) _Pragma("unroll") for (int n = 0; n < 2; ++n) _Pragma("unroll") for (int k = 0; k < 2; ++k) \
;         acc[ai][bj][m][n] = __builtin_amdgcn_mfma_f32_16x16x32_bf16(Bt[n][k], At[m][k], acc[ai][bj][m][n], 0, 0, 0); __builtin_amdgcn_s_setprio(0); } while (0)
; #define PG8_WAIT_V(n) asm volatile("s_waitcnt vmcnt(" #n ")" ::: "memory")
; #define PG8_WAIT_L(n) asm volatile("s_waitcnt lgkmcnt(" #n ")" ::: "memory")
; #define PG8_BAR __builtin_amdgcn_s_barrier()
; #define PG8_SCHED __builtin_amdgcn_sched_barrier(0)
; template <class Epi>
; __device__ __forceinline__ void gemm_phase(LAS unsigned char* lds, const Gemm g, const StaticOrder S, const Epi E) {
;     ...
;             const char* a1 = cA + (long)(t + 1) * ksc;
;             const char* a2 = last ? nA : cA + (long)(t + 2) * ksc; const char* b2 = last ? nB : cB + (long)(t + 2) * ksc;
;             const long ks3 = last ? ksn : ksc;
;             const char* a3 = a2 + ks3; const char* b3 = b2 + ks3;
;             PG8_LDB(B0, 0, 0); PG8_LDB(B1, 0, 1); PG8_SCHED; PG8_LDA(At, 0, 0); PG8_STAGE(PG8_SA(1, 1), a1 + hstepA, voffA);
;             PG8_WAIT_V(8); PG8_WAIT_L(0); PG8_BAR; PG8_MMA(0, 0, At, B0); PG8_MMA(0, 1, At, B1); PG8_BAR; PG8_SCHED;
;             PG8_LDA(At, 0, 1); PG8_STAGE(PG8_SB(0, 0), b2, voffB); PG8_STAGE(PG8_SB(0, 1), b2 + hstepB, voffB); PG8_STAGE(PG8_SA(0, 0), a2, voffA);
;             PG8_WAIT_V(8); PG8_WAIT_L(0); PG8_BAR; PG8_MMA(1, 0, At, B0); PG8_MMA(1, 1, At, B1); PG8_BAR; PG8_SCHED;
.LBB0_121:
	ds_read_b128 v[148:151], v254
	ds_read_b128 v[152:155], v254 offset:1024
	ds_read_b128 v[156:159], v254 offset:2048
	ds_read_b128 v[160:163], v254 offset:3072
	ds_read_b128 v[164:167], v254 offset:16384
	ds_read_b128 v[168:171], v254 offset:17408
	ds_read_b128 v[172:175], v254 offset:18432
	ds_read_b128 v[176:179], v254 offset:19456
	s_or_b32 s13, s62, 1
	s_mul_i32 s46, s27, s13
	s_mul_hi_u32 s47, s26, s13
	s_add_i32 s47, s47, s46
	s_mul_i32 s13, s26, s13
	s_add_u32 s13, s24, s13
	s_addc_u32 s63, s25, s47
	s_add_u32 s46, s44, s42
	s_addc_u32 s47, s45, s43
	s_add_u32 s64, s13, 0x80000
	s_addc_u32 s65, s63, 0
	s_add_i32 m0, s21, 0xc000
	ds_read_b128 v[180:183], v145
	ds_read_b128 v[184:187], v145 offset:1024
	ds_read_b128 v[188:191], v145 offset:2048
	ds_read_b128 v[192:195], v145 offset:3072
	ds_read_b128 v[196:199], v145 offset:4096
	ds_read_b128 v[200:203], v145 offset:5120
	ds_read_b128 v[204:207], v145 offset:6144
	ds_read_b128 v[208:211], v145 offset:7168
	global_load_lds_dwordx4 v134, s[64:65]
	s_add_i32 m0, s21, 0xe000
	s_nop 0
	global_load_lds_dwordx4 v130, s[64:65]
	s_waitcnt vmcnt(8)
	s_waitcnt lgkmcnt(0)
	s_barrier
	s_setprio 1
	s_waitcnt lgkmcnt(0)
	v_mfma_f32_16x16x32_bf16 v[116:119], v[148:151], v[180:183], v[116:119]
	v_mfma_f32_16x16x32_bf16 v[112:115], v[156:159], v[180:183], v[112:115]
	v_mfma_f32_16x16x32_bf16 v[108:111], v[148:151], v[188:191], v[108:111]
	v_mfma_f32_16x16x32_bf16 v[104:107], v[156:159], v[188:191], v[104:107]
	v_mfma_f32_16x16x32_bf16 v[92:95], v[148:151], v[196:199], v[92:95]
	v_mfma_f32_16x16x32_bf16 v[88:91], v[156:159], v[196:199], v[88:91]
	v_mfma_f32_16x16x32_bf16 v[76:79], v[148:151], v[204:207], v[76:79]
	v_mfma_f32_16x16x32_bf16 v[72:75], v[156:159], v[204:207], v[72:75]
	v_mfma_f32_16x16x32_bf16 v[116:119], v[152:155], v[184:187], v[116:119]
	v_mfma_f32_16x16x32_bf16 v[112:115], v[160:163], v[184:187], v[112:115]
	v_mfma_f32_16x16x32_bf16 v[108:111], v[152:155], v[192:195], v[108:111]
	v_mfma_f32_16x16x32_bf16 v[104:107], v[160:163], v[192:195], v[104:107]
	v_mfma_f32_16x16x32_bf16 v[92:95], v[152:155], v[200:203], v[92:95]
	v_mfma_f32_16x16x32_bf16 v[88:91], v[160:163], v[200:203], v[88:91]
	v_mfma_f32_16x16x32_bf16 v[76:79], v[152:155], v[208:211], v[76:79]
	v_mfma_f32_16x16x32_bf16 v[72:75], v[160:163], v[208:211], v[72:75]
	s_setprio 0
	s_setprio 1
	v_mfma_f32_16x16x32_bf16 v[124:127], v[164:167], v[180:183], v[124:127]
	v_mfma_f32_16x16x32_bf16 v[120:123], v[172:175], v[180:183], v[120:123]
	v_mfma_f32_16x16x32_bf16 v[100:103], v[164:167], v[188:191], v[100:103]
	v_mfma_f32_16x16x32_bf16 v[96:99], v[172:175], v[188:191], v[96:99]
	v_mfma_f32_16x16x32_bf16 v[84:87], v[164:167], v[196:199], v[84:87]
	v_mfma_f32_16x16x32_bf16 v[80:83], v[172:175], v[196:199], v[80:83]
	v_mfma_f32_16x16x32_bf16 v[68:71], v[164:167], v[204:207], v[68:71]
	v_mfma_f32_16x16x32_bf16 v[64:67], v[172:175], v[204:207], v[64:67]
	v_mfma_f32_16x16x32_bf16 v[124:127], v[168:171], v[184:187], v[124:127]
	v_mfma_f32_16x16x32_bf16 v[120:123], v[176:179], v[184:187], v[120:123]
	v_mfma_f32_16x16x32_bf16 v[100:103], v[168:171], v[192:195], v[100:103]
	v_mfma_f32_16x16x32_bf16 v[96:99], v[176:179], v[192:195], v[96:99]
	v_mfma_f32_16x16x32_bf16 v[84:87], v[168:171], v[200:203], v[84:87]
	v_mfma_f32_16x16x32_bf16 v[80:83], v[176:179], v[200:203], v[80:83]
	v_mfma_f32_16x16x32_bf16 v[68:71], v[168:171], v[208:211], v[68:71]
	v_mfma_f32_16x16x32_bf16 v[64:67], v[176:179], v[208:211], v[64:67]
	s_setprio 0
	s_barrier
	s_add_i32 s13, s57, s33
	s_mov_b32 m0, s13
	ds_read_b128 v[180:183], v145 offset:16384
	ds_read_b128 v[184:187], v145 offset:17408
	ds_read_b128 v[188:191], v145 offset:18432
	ds_read_b128 v[192:195], v145 offset:19456
	ds_read_b128 v[196:199], v145 offset:20480
	ds_read_b128 v[200:203], v145 offset:21504
	ds_read_b128 v[204:207], v145 offset:22528
	ds_read_b128 v[208:211], v145 offset:23552
	global_load_lds_dwordx4 v132, s[40:41]
	s_add_i32 m0, s13, 0x2000
	s_add_u32 s64, s40, 0x80000
	s_addc_u32 s65, s41, 0
	s_add_i32 s13, s58, s33
	global_load_lds_dwordx4 v128, s[40:41]
	s_mov_b32 m0, s13
	s_nop 0
	global_load_lds_dwordx4 v132, s[64:65]
	s_add_i32 m0, s13, 0x2000
	s_nop 0
	global_load_lds_dwordx4 v128, s[64:65]
	s_mov_b32 m0, s21
	s_nop 0
	global_load_lds_dwordx4 v134, s[44:45]
	s_mov_b32 m0, s50
	s_nop 0
	global_load_lds_dwordx4 v130, s[44:45]
	s_waitcnt vmcnt(8)
	s_waitcnt lgkmcnt(0)
	s_barrier
	s_setprio 1
	s_waitcnt lgkmcnt(0)
	v_mfma_f32_16x16x32_bf16 v[60:63], v[148:151], v[180:183], v[60:63]
	v_mfma_f32_16x16x32_bf16 v[56:59], v[156:159], v[180:183], v[56:59]
	v_mfma_f32_16x16x32_bf16 v[44:47], v[148:151], v[188:191], v[44:47]
	v_mfma_f32_16x16x32_bf16 v[40:43], v[156:159], v[188:191], v[40:43]
	v_mfma_f32_16x16x32_bf16 v[28:31], v[148:151], v[196:199], v[28:31]
	v_mfma_f32_16x16x32_bf16 v[24:27], v[156:159], v[196:199], v[24:27]
	v_mfma_f32_16x16x32_bf16 v[12:15], v[148:151], v[204:207], v[12:15]
	v_mfma_f32_16x16x32_bf16 v[8:11], v[156:159], v[204:207], v[8:11]
	v_mfma_f32_16x16x32_bf16 v[60:63], v[152:155], v[184:187], v[60:63]
	v_mfma_f32_16x16x32_bf16 v[56:59], v[160:163], v[184:187], v[56:59]
	v_mfma_f32_16x16x32_bf16 v[44:47], v[152:155], v[192:195], v[44:47]
	v_mfma_f32_16x16x32_bf16 v[40:43], v[160:163], v[192:195], v[40:43]
	v_mfma_f32_16x16x32_bf16 v[28:31], v[152:155], v[200:203], v[28:31]
	v_mfma_f32_16x16x32_bf16 v[24:27], v[160:163], v[200:203], v[24:27]
	v_mfma_f32_16x16x32_bf16 v[12:15], v[152:155], v[208:211], v[12:15]
	v_mfma_f32_16x16x32_bf16 v[8:11], v[160:163], v[208:211], v[8:11]
	s_setprio 0
	s_setprio 1
	v_mfma_f32_16x16x32_bf16 v[52:55], v[164:167], v[180:183], v[52:55]
	v_mfma_f32_16x16x32_bf16 v[48:51], v[172:175], v[180:183], v[48:51]
	v_mfma_f32_16x16x32_bf16 v[36:39], v[164:167], v[188:191], v[36:39]
	v_mfma_f32_16x16x32_bf16 v[32:35], v[172:175], v[188:191], v[32:35]
	v_mfma_f32_16x16x32_bf16 v[20:23], v[164:167], v[196:199], v[20:23]
	v_mfma_f32_16x16x32_bf16 v[16:19], v[172:175], v[196:199], v[16:19]
	v_mfma_f32_16x16x32_bf16 v[4:7], v[164:167], v[204:207], v[4:7]
	v_mfma_f32_16x16x32_bf16 v[0:3], v[172:175], v[204:207], v[0:3]
	v_mfma_f32_16x16x32_bf16 v[52:55], v[168:171], v[184:187], v[52:55]
	v_mfma_f32_16x16x32_bf16 v[48:51], v[176:179], v[184:187], v[48:51]
	v_mfma_f32_16x16x32_bf16 v[36:39], v[168:171], v[192:195], v[36:39]
	v_mfma_f32_16x16x32_bf16 v[32:35], v[176:179], v[192:195], v[32:35]
	v_mfma_f32_16x16x32_bf16 v[20:23], v[168:171], v[200:203], v[20:23]
	v_mfma_f32_16x16x32_bf16 v[16:19], v[176:179], v[200:203], v[16:19]
	v_mfma_f32_16x16x32_bf16 v[4:7], v[168:171], v[208:211], v[4:7]
	v_mfma_f32_16x16x32_bf16 v[0:3], v[176:179], v[208:211], v[0:3]
	s_setprio 0
	s_barrier
; #define PG8_STAGE(bufoff, gbase, voff) do { _Pragma("unroll") for (int _i = 0; _i < 2; ++_i) \
;         __builtin_amdgcn_global_load_lds((const unsigned*)((const char*)(gbase) + (voff)[_i]), (LAS unsigned*)(lds + (bufoff) + ldsw + _i * 8192), 16, 0, 0); } while (0)
; #define PG8_LDA(dst, b, h) do { _Pragma("unroll") for (int m = 0; m < 4; ++m) _Pragma("unroll") for (int k = 0; k < 2; ++k) dst[m][k] = *(const LAS bf16x8*)(lds + PG8_SA(b, h) + aoff + m * 2048 + k * 1024); } while (0)
; #define PG8_LDB(dst, b, h) do { _Pragma("unroll") for (int n = 0; n < 2; ++n) _Pragma("unroll") for (int k = 0; k < 2; ++k) dst[n][k] = *(const LAS bf16x8*)(lds + PG8_SB(b, h) + boff + n * 2048 + k * 1024); } while (0)
; #define PG8_MMA(ai, bj, At, Bt) do { __builtin_amdgcn_s_setprio(1); _Pragma("unroll") for (int m = 0; m < 4; ++m) _Pragma("unroll") for (int n = 0; n < 2; ++n) _Pragma("unroll") for (int k = 0; k < 2; ++k) \
;         acc[ai][bj][m][n] = __builtin_amdgcn_mfma_f32_16x16x32_bf16(Bt[n][k], At[m][k], acc[ai][bj][m][n], 0, 0, 0); __builtin_amdgcn_s_setprio(0); } while (0)
; #define PG8_WAIT_V(n) asm volatile("s_waitcnt vmcnt(" #n ")" ::: "memory")
; #define PG8_WAIT_L(n) asm volatile("s_waitcnt lgkmcnt(" #n ")" ::: "memory")
; #define PG8_BAR __builtin_amdgcn_s_barrier()
; #define PG8_SCHED __builtin_amdgcn_sched_barrier(0)
; template <class Epi>
; __device__ __forceinline__ void gemm_phase(LAS unsigned char* lds, const Gemm g, const StaticOrder S, const Epi E) {
;     ...
;             PG8_LDB(B0, 1, 0); PG8_LDB(B1, 1, 1); PG8_SCHED; PG8_LDA(At, 1, 0); PG8_STAGE(PG8_SA(0, 1), a2 + hstepA, voffA);
;             PG8_WAIT_V(8); PG8_WAIT_L(0); PG8_BAR; PG8_MMA(0, 0, At, B0); PG8_MMA(0, 1, At, B1); PG8_BAR; PG8_SCHED;
;             PG8_LDA(At, 1, 1); PG8_STAGE(PG8_SB(1, 0), b3, voffB); PG8_STAGE(PG8_SB(1, 1), b3 + hstepB, voffB); PG8_STAGE(PG8_SA(1, 0), a3, voffA);
;             PG8_WAIT_V(8); PG8_WAIT_L(0); PG8_BAR; PG8_MMA(1, 0, At, B0); PG8_MMA(1, 1, At, B1); PG8_BAR; PG8_SCHED;
	s_add_i32 s13, 0, 0x18000
	s_add_i32 s63, 0, 0x1c000
	ds_read_b128 v[148:151], v254 offset:32768
	ds_read_b128 v[152:155], v254 offset:33792
	ds_read_b128 v[156:159], v254 offset:34816
	ds_read_b128 v[160:163], v254 offset:35840
	ds_read_b128 v[164:167], v254 offset:49152
	ds_read_b128 v[168:171], v254 offset:50176
	ds_read_b128 v[172:175], v254 offset:51200
	ds_read_b128 v[176:179], v254 offset:52224
	s_add_u32 s44, s44, 0x80000
	s_addc_u32 s45, s45, 0
	s_mov_b32 m0, s51
	ds_read_b128 v[180:183], v145 offset:32768
	ds_read_b128 v[184:187], v145 offset:33792
	ds_read_b128 v[188:191], v145 offset:34816
	ds_read_b128 v[192:195], v145 offset:35840
	ds_read_b128 v[196:199], v145 offset:36864
	ds_read_b128 v[200:203], v145 offset:37888
	ds_read_b128 v[204:207], v145 offset:38912
	ds_read_b128 v[208:211], v145 offset:39936
	global_load_lds_dwordx4 v134, s[44:45]
	s_mov_b32 m0, s52
	s_nop 0
	global_load_lds_dwordx4 v130, s[44:45]
	s_waitcnt vmcnt(8)
	s_waitcnt lgkmcnt(0)
	s_barrier
	s_setprio 1
	s_waitcnt lgkmcnt(0)
	v_mfma_f32_16x16x32_bf16 v[116:119], v[148:151], v[180:183], v[116:119]
	v_mfma_f32_16x16x32_bf16 v[112:115], v[156:159], v[180:183], v[112:115]
	v_mfma_f32_16x16x32_bf16 v[108:111], v[148:151], v[188:191], v[108:111]
	v_mfma_f32_16x16x32_bf16 v[104:107], v[156:159], v[188:191], v[104:107]
	v_mfma_f32_16x16x32_bf16 v[92:95], v[148:151], v[196:199], v[92:95]
	v_mfma_f32_16x16x32_bf16 v[88:91], v[156:159], v[196:199], v[88:91]
	v_mfma_f32_16x16x32_bf16 v[76:79], v[148:151], v[204:207], v[76:79]
	v_mfma_f32_16x16x32_bf16 v[72:75], v[156:159], v[204:207], v[72:75]
	v_mfma_f32_16x16x32_bf16 v[116:119], v[152:155], v[184:187], v[116:119]
	v_mfma_f32_16x16x32_bf16 v[112:115], v[160:163], v[184:187], v[112:115]
	v_mfma_f32_16x16x32_bf16 v[108:111], v[152:155], v[192:195], v[108:111]
	v_mfma_f32_16x16x32_bf16 v[104:107], v[160:163], v[192:195], v[104:107]
	v_mfma_f32_16x16x32_bf16 v[92:95], v[152:155], v[200:203], v[92:95]
	v_mfma_f32_16x16x32_bf16 v[88:91], v[160:163], v[200:203], v[88:91]
	v_mfma_f32_16x16x32_bf16 v[76:79], v[152:155], v[208:211], v[76:79]
	v_mfma_f32_16x16x32_bf16 v[72:75], v[160:163], v[208:211], v[72:75]
	s_setprio 0
	s_setprio 1
	v_mfma_f32_16x16x32_bf16 v[124:127], v[164:167], v[180:183], v[124:127]
	v_mfma_f32_16x16x32_bf16 v[120:123], v[172:175], v[180:183], v[120:123]
	v_mfma_f32_16x16x32_bf16 v[100:103], v[164:167], v[188:191], v[100:103]
	v_mfma_f32_16x16x32_bf16 v[96:99], v[172:175], v[188:191], v[96:99]
	v_mfma_f32_16x16x32_bf16 v[84:87], v[164:167], v[196:199], v[84:87]
	v_mfma_f32_16x16x32_bf16 v[80:83], v[172:175], v[196:199], v[80:83]
	v_mfma_f32_16x16x32_bf16 v[68:71], v[164:167], v[204:207], v[68:71]
	v_mfma_f32_16x16x32_bf16 v[64:67], v[172:175], v[204:207], v[64:67]
	v_mfma_f32_16x16x32_bf16 v[124:127], v[168:171], v[184:187], v[124:127]
	v_mfma_f32_16x16x32_bf16 v[120:123], v[176:179], v[184:187], v[120:123]
	v_mfma_f32_16x16x32_bf16 v[100:103], v[168:171], v[192:195], v[100:103]
	v_mfma_f32_16x16x32_bf16 v[96:99], v[176:179], v[192:195], v[96:99]
	v_mfma_f32_16x16x32_bf16 v[84:87], v[168:171], v[200:203], v[84:87]
	v_mfma_f32_16x16x32_bf16 v[80:83], v[176:179], v[200:203], v[80:83]
	v_mfma_f32_16x16x32_bf16 v[68:71], v[168:171], v[208:211], v[68:71]
	v_mfma_f32_16x16x32_bf16 v[64:67], v[176:179], v[208:211], v[64:67]
	s_setprio 0
	s_barrier
	s_add_u32 s40, s40, s42
	s_addc_u32 s41, s41, s43
	s_add_i32 s13, s13, s33
	s_mov_b32 m0, s13
	ds_read_b128 v[180:183], v145 offset:49152
	ds_read_b128 v[184:187], v145 offset:50176
	ds_read_b128 v[188:191], v145 offset:51200
	ds_read_b128 v[192:195], v145 offset:52224
	ds_read_b128 v[196:199], v145 offset:53248
	ds_read_b128 v[200:203], v145 offset:54272
	ds_read_b128 v[204:207], v145 offset:55296
	ds_read_b128 v[208:211], v145 offset:56320
	global_load_lds_dwordx4 v132, s[40:41]
	s_add_i32 m0, s13, 0x2000
	s_nop 0
	global_load_lds_dwordx4 v128, s[40:41]
	s_add_u32 s40, s40, 0x80000
	s_addc_u32 s41, s41, 0
	s_add_i32 s13, s63, s33
	s_mov_b32 m0, s13
	s_nop 0
	global_load_lds_dwordx4 v132, s[40:41]
	s_add_i32 m0, s13, 0x2000
	s_nop 0
	global_load_lds_dwordx4 v128, s[40:41]
	s_mov_b32 m0, s53
	s_nop 0
	global_load_lds_dwordx4 v134, s[46:47]
	s_mov_b32 m0, s54
	s_nop 0
	global_load_lds_dwordx4 v130, s[46:47]
	s_waitcnt vmcnt(8)
	s_waitcnt lgkmcnt(0)
	s_barrier
	s_setprio 1
	s_waitcnt lgkmcnt(0)
	v_mfma_f32_16x16x32_bf16 v[60:63], v[148:151], v[180:183], v[60:63]
	v_mfma_f32_16x16x32_bf16 v[56:59], v[156:159], v[180:183], v[56:59]
	v_mfma_f32_16x16x32_bf16 v[44:47], v[148:151], v[188:191], v[44:47]
	v_mfma_f32_16x16x32_bf16 v[40:43], v[156:159], v[188:191], v[40:43]
	v_mfma_f32_16x16x32_bf16 v[28:31], v[148:151], v[196:199], v[28:31]
	v_mfma_f32_16x16x32_bf16 v[24:27], v[156:159], v[196:199], v[24:27]
	v_mfma_f32_16x16x32_bf16 v[12:15], v[148:151], v[204:207], v[12:15]
	v_mfma_f32_16x16x32_bf16 v[8:11], v[156:159], v[204:207], v[8:11]
	v_mfma_f32_16x16x32_bf16 v[60:63], v[152:155], v[184:187], v[60:63]
	v_mfma_f32_16x16x32_bf16 v[56:59], v[160:163], v[184:187], v[56:59]
	v_mfma_f32_16x16x32_bf16 v[44:47], v[152:155], v[192:195], v[44:47]
	v_mfma_f32_16x16x32_bf16 v[40:43], v[160:163], v[192:195], v[40:43]
	v_mfma_f32_16x16x32_bf16 v[28:31], v[152:155], v[200:203], v[28:31]
	v_mfma_f32_16x16x32_bf16 v[24:27], v[160:163], v[200:203], v[24:27]
	v_mfma_f32_16x16x32_bf16 v[12:15], v[152:155], v[208:211], v[12:15]
	v_mfma_f32_16x16x32_bf16 v[8:11], v[160:163], v[208:211], v[8:11]
	s_setprio 0
	s_setprio 1
	v_mfma_f32_16x16x32_bf16 v[52:55], v[164:167], v[180:183], v[52:55]
	v_mfma_f32_16x16x32_bf16 v[48:51], v[172:175], v[180:183], v[48:51]
	v_mfma_f32_16x16x32_bf16 v[36:39], v[164:167], v[188:191], v[36:39]
	v_mfma_f32_16x16x32_bf16 v[32:35], v[172:175], v[188:191], v[32:35]
	v_mfma_f32_16x16x32_bf16 v[20:23], v[164:167], v[196:199], v[20:23]
	v_mfma_f32_16x16x32_bf16 v[16:19], v[172:175], v[196:199], v[16:19]
	v_mfma_f32_16x16x32_bf16 v[4:7], v[164:167], v[204:207], v[4:7]
	v_mfma_f32_16x16x32_bf16 v[0:3], v[172:175], v[204:207], v[0:3]
	v_mfma_f32_16x16x32_bf16 v[52:55], v[168:171], v[184:187], v[52:55]
	v_mfma_f32_16x16x32_bf16 v[48:51], v[176:179], v[184:187], v[48:51]
	v_mfma_f32_16x16x32_bf16 v[36:39], v[168:171], v[192:195], v[36:39]
	v_mfma_f32_16x16x32_bf16 v[32:35], v[176:179], v[192:195], v[32:35]
	v_mfma_f32_16x16x32_bf16 v[20:23], v[168:171], v[200:203], v[20:23]
	v_mfma_f32_16x16x32_bf16 v[16:19], v[176:179], v[200:203], v[16:19]
	v_mfma_f32_16x16x32_bf16 v[4:7], v[168:171], v[208:211], v[4:7]
	v_mfma_f32_16x16x32_bf16 v[0:3], v[176:179], v[208:211], v[0:3]
	s_setprio 0
	s_barrier
	s_cmp_gt_u32 s62, 29
	s_mov_b32 s62, s11
	s_cbranch_scc1 .LBB0_126

; #define PG8_STAGE(bufoff, gbase, voff) do { _Pragma("unroll") for (int _i = 0; _i < 2; ++_i) \
;         __builtin_amdgcn_global_load_lds((const unsigned*)((const char*)(gbase) + (voff)[_i]), (LAS unsigned*)(lds + (bufoff) + ldsw + _i * 8192), 16, 0, 0); } while (0)
; #define PG8_LDA(dst, b, h) do { _Pragma("unroll") for (int m = 0; m < 4; ++m) _Pragma("unroll") for (int k = 0; k < 2; ++k) dst[m][k] = *(const LAS bf16x8*)(lds + PG8_SA(b, h) + aoff + m * 2048 + k * 1024); } while (0)
; #define PG8_LDB(dst, b, h) do { _Pragma("unroll") for (int n = 0; n < 2; ++n) _Pragma("unroll") for (int k = 0; k < 2; ++k) dst[n][k] = *(const LAS bf16x8*)(lds + PG8_SB(b, h) + boff + n * 2048 + k * 1024); } while (0)
; #define PG8_MMA(ai, bj, At, Bt) do { __builtin_amdgcn_s_setprio(1); _Pragma("unroll") for (int m = 0; m < 4; ++m) _Pragma("unroll") for (int n = 0; n < 2; ++n) _Pragma("unroll") for (int k = 0; k < 2; ++k) \
;         acc[ai][bj][m][n] = __builtin_amdgcn_mfma_f32_16x16x32_bf16(Bt[n][k], At[m][k], acc[ai][bj][m][n], 0, 0, 0); __builtin_amdgcn_s_setprio(0); } while (0)
; #define PG8_WAIT_V(n) asm volatile("s_waitcnt vmcnt(" #n ")" ::: "memory")
; #define PG8_WAIT_L(n) asm volatile("s_waitcnt lgkmcnt(" #n ")" ::: "memory")
; #define PG8_BAR __builtin_amdgcn_s_barrier()
; #define PG8_SCHED __builtin_amdgcn_sched_barrier(0)
; template <class Epi>
; __device__ __forceinline__ void gemm_phase(LAS unsigned char* lds, const Gemm g, const StaticOrder S, const Epi E) {
;     ...
;             const char* a1 = cA + (long)(t + 1) * ksc;
;             const char* a2 = last ? nA : cA + (long)(t + 2) * ksc; const char* b2 = last ? nB : cB + (long)(t + 2) * ksc;
;             const long ks3 = last ? ksn : ksc;
;             const char* a3 = a2 + ks3; const char* b3 = b2 + ks3;
;             PG8_LDB(B0, 0, 0); PG8_LDB(B1, 0, 1); PG8_SCHED; PG8_LDA(At, 0, 0); PG8_STAGE(PG8_SA(1, 1), a1 + hstepA, voffA);
;             PG8_WAIT_V(8); PG8_WAIT_L(0); PG8_BAR; PG8_MMA(0, 0, At, B0); PG8_MMA(0, 1, At, B1); PG8_BAR; PG8_SCHED;
;             PG8_LDA(At, 0, 1); PG8_STAGE(PG8_SB(0, 0), b2, voffB); PG8_STAGE(PG8_SB(0, 1), b2 + hstepB, voffB); PG8_STAGE(PG8_SA(0, 0), a2, voffA);
;             PG8_WAIT_V(8); PG8_WAIT_L(0); PG8_BAR; PG8_MMA(1, 0, At, B0); PG8_MMA(1, 1, At, B1); PG8_BAR; PG8_SCHED;
.LBB0_206:
	v_add_u32_e32 v152, s59, v164
	v_add_u32_e32 v176, s60, v164
	ds_read_b128 v[128:131], v152
	ds_read_b128 v[132:135], v152 offset:1024
	ds_read_b128 v[136:139], v152 offset:2048
	ds_read_b128 v[152:155], v152 offset:3072
	ds_read_b128 v[156:159], v176
	ds_read_b128 v[168:171], v176 offset:1024
	ds_read_b128 v[172:175], v176 offset:2048
	ds_read_b128 v[176:179], v176 offset:3072
	s_or_b32 s48, s70, 1
	s_mul_i32 s49, s35, s48
	s_mul_hi_u32 s72, s34, s48
	s_add_i32 s72, s72, s49
	s_mul_i32 s48, s34, s48
	s_add_u32 s73, s30, s48
	s_addc_u32 s74, s31, s72
	s_add_u32 s48, s46, s44
	s_addc_u32 s49, s47, s45
	s_add_u32 s72, s73, 0x160000
	s_addc_u32 s73, s74, 0
	s_add_i32 m0, s50, 0xc000
	ds_read_b128 v[180:183], v166
	ds_read_b128 v[184:187], v166 offset:1024
	ds_read_b128 v[188:191], v166 offset:2048
	ds_read_b128 v[192:195], v166 offset:3072
	ds_read_b128 v[196:199], v166 offset:4096
	ds_read_b128 v[200:203], v166 offset:5120
	ds_read_b128 v[204:207], v166 offset:6144
	ds_read_b128 v[208:211], v166 offset:7168
	global_load_lds_dwordx4 v140, s[72:73]
	s_add_i32 m0, s50, 0xe000
	s_nop 0
	global_load_lds_dwordx4 v144, s[72:73]
	s_waitcnt vmcnt(8)
	s_waitcnt lgkmcnt(0)
	s_barrier
	s_setprio 1
	s_waitcnt lgkmcnt(0)
	v_mfma_f32_16x16x32_bf16 v[124:127], v[128:131], v[180:183], v[124:127]
	v_mfma_f32_16x16x32_bf16 v[120:123], v[136:139], v[180:183], v[120:123]
	v_mfma_f32_16x16x32_bf16 v[108:111], v[128:131], v[188:191], v[108:111]
	v_mfma_f32_16x16x32_bf16 v[104:107], v[136:139], v[188:191], v[104:107]
	v_mfma_f32_16x16x32_bf16 v[92:95], v[128:131], v[196:199], v[92:95]
	v_mfma_f32_16x16x32_bf16 v[88:91], v[136:139], v[196:199], v[88:91]
	v_mfma_f32_16x16x32_bf16 v[76:79], v[128:131], v[204:207], v[76:79]
	v_mfma_f32_16x16x32_bf16 v[72:75], v[136:139], v[204:207], v[72:75]
	v_mfma_f32_16x16x32_bf16 v[124:127], v[132:135], v[184:187], v[124:127]
	v_mfma_f32_16x16x32_bf16 v[120:123], v[152:155], v[184:187], v[120:123]
	v_mfma_f32_16x16x32_bf16 v[108:111], v[132:135], v[192:195], v[108:111]
	v_mfma_f32_16x16x32_bf16 v[104:107], v[152:155], v[192:195], v[104:107]
	v_mfma_f32_16x16x32_bf16 v[92:95], v[132:135], v[200:203], v[92:95]
	v_mfma_f32_16x16x32_bf16 v[88:91], v[152:155], v[200:203], v[88:91]
	v_mfma_f32_16x16x32_bf16 v[76:79], v[132:135], v[208:211], v[76:79]
	v_mfma_f32_16x16x32_bf16 v[72:75], v[152:155], v[208:211], v[72:75]
	s_setprio 0
	s_setprio 1
	v_mfma_f32_16x16x32_bf16 v[116:119], v[156:159], v[180:183], v[116:119]
	v_mfma_f32_16x16x32_bf16 v[112:115], v[172:175], v[180:183], v[112:115]
	v_mfma_f32_16x16x32_bf16 v[100:103], v[156:159], v[188:191], v[100:103]
	v_mfma_f32_16x16x32_bf16 v[96:99], v[172:175], v[188:191], v[96:99]
	v_mfma_f32_16x16x32_bf16 v[84:87], v[156:159], v[196:199], v[84:87]
	v_mfma_f32_16x16x32_bf16 v[80:83], v[172:175], v[196:199], v[80:83]
	v_mfma_f32_16x16x32_bf16 v[68:71], v[156:159], v[204:207], v[68:71]
	v_mfma_f32_16x16x32_bf16 v[64:67], v[172:175], v[204:207], v[64:67]
	v_mfma_f32_16x16x32_bf16 v[116:119], v[168:171], v[184:187], v[116:119]
	v_mfma_f32_16x16x32_bf16 v[112:115], v[176:179], v[184:187], v[112:115]
	v_mfma_f32_16x16x32_bf16 v[100:103], v[168:171], v[192:195], v[100:103]
	v_mfma_f32_16x16x32_bf16 v[96:99], v[176:179], v[192:195], v[96:99]
	v_mfma_f32_16x16x32_bf16 v[84:87], v[168:171], v[200:203], v[84:87]
	v_mfma_f32_16x16x32_bf16 v[80:83], v[176:179], v[200:203], v[80:83]
	v_mfma_f32_16x16x32_bf16 v[68:71], v[168:171], v[208:211], v[68:71]
	v_mfma_f32_16x16x32_bf16 v[64:67], v[176:179], v[208:211], v[64:67]
	s_setprio 0
	s_barrier
	s_add_i32 s72, s59, s33
	s_mov_b32 m0, s72
	ds_read_b128 v[180:183], v166 offset:16384
	ds_read_b128 v[184:187], v166 offset:17408
	ds_read_b128 v[188:191], v166 offset:18432
	ds_read_b128 v[192:195], v166 offset:19456
	ds_read_b128 v[196:199], v166 offset:20480
	ds_read_b128 v[200:203], v166 offset:21504
	ds_read_b128 v[204:207], v166 offset:22528
	ds_read_b128 v[208:211], v166 offset:23552
	global_load_lds_dwordx4 v142, s[42:43]
	s_add_i32 m0, s72, 0x2000
	s_add_u32 s72, s42, 0x160000
	s_addc_u32 s73, s43, 0
	s_add_i32 s74, s60, s33
	global_load_lds_dwordx4 v146, s[42:43]
	s_mov_b32 m0, s74
	s_nop 0
	global_load_lds_dwordx4 v142, s[72:73]
	s_add_i32 m0, s74, 0x2000
	s_nop 0
	global_load_lds_dwordx4 v146, s[72:73]
	s_mov_b32 m0, s50
	s_nop 0
	global_load_lds_dwordx4 v140, s[46:47]
	s_mov_b32 m0, s51
	s_nop 0
	global_load_lds_dwordx4 v144, s[46:47]
	s_waitcnt vmcnt(8)
	s_waitcnt lgkmcnt(0)
	s_barrier
	s_setprio 1
	s_waitcnt lgkmcnt(0)
	v_mfma_f32_16x16x32_bf16 v[60:63], v[128:131], v[180:183], v[60:63]
	v_mfma_f32_16x16x32_bf16 v[56:59], v[136:139], v[180:183], v[56:59]
	v_mfma_f32_16x16x32_bf16 v[44:47], v[128:131], v[188:191], v[44:47]
	v_mfma_f32_16x16x32_bf16 v[40:43], v[136:139], v[188:191], v[40:43]
	v_mfma_f32_16x16x32_bf16 v[28:31], v[128:131], v[196:199], v[28:31]
	v_mfma_f32_16x16x32_bf16 v[24:27], v[136:139], v[196:199], v[24:27]
	v_mfma_f32_16x16x32_bf16 v[12:15], v[128:131], v[204:207], v[12:15]
	v_mfma_f32_16x16x32_bf16 v[8:11], v[136:139], v[204:207], v[8:11]
	v_mfma_f32_16x16x32_bf16 v[60:63], v[132:135], v[184:187], v[60:63]
	v_mfma_f32_16x16x32_bf16 v[56:59], v[152:155], v[184:187], v[56:59]
	v_mfma_f32_16x16x32_bf16 v[44:47], v[132:135], v[192:195], v[44:47]
	v_mfma_f32_16x16x32_bf16 v[40:43], v[152:155], v[192:195], v[40:43]
	v_mfma_f32_16x16x32_bf16 v[28:31], v[132:135], v[200:203], v[28:31]
	v_mfma_f32_16x16x32_bf16 v[24:27], v[152:155], v[200:203], v[24:27]
	v_mfma_f32_16x16x32_bf16 v[12:15], v[132:135], v[208:211], v[12:15]
	v_mfma_f32_16x16x32_bf16 v[8:11], v[152:155], v[208:211], v[8:11]
	s_setprio 0
	s_setprio 1
	v_mfma_f32_16x16x32_bf16 v[52:55], v[156:159], v[180:183], v[52:55]
	v_mfma_f32_16x16x32_bf16 v[48:51], v[172:175], v[180:183], v[48:51]
	v_mfma_f32_16x16x32_bf16 v[36:39], v[156:159], v[188:191], v[36:39]
	v_mfma_f32_16x16x32_bf16 v[32:35], v[172:175], v[188:191], v[32:35]
	v_mfma_f32_16x16x32_bf16 v[20:23], v[156:159], v[196:199], v[20:23]
	v_mfma_f32_16x16x32_bf16 v[16:19], v[172:175], v[196:199], v[16:19]
	v_mfma_f32_16x16x32_bf16 v[4:7], v[156:159], v[204:207], v[4:7]
	v_mfma_f32_16x16x32_bf16 v[0:3], v[172:175], v[204:207], v[0:3]
	v_mfma_f32_16x16x32_bf16 v[52:55], v[168:171], v[184:187], v[52:55]
	v_mfma_f32_16x16x32_bf16 v[48:51], v[176:179], v[184:187], v[48:51]
	v_mfma_f32_16x16x32_bf16 v[36:39], v[168:171], v[192:195], v[36:39]
	v_mfma_f32_16x16x32_bf16 v[32:35], v[176:179], v[192:195], v[32:35]
	v_mfma_f32_16x16x32_bf16 v[20:23], v[168:171], v[200:203], v[20:23]
	v_mfma_f32_16x16x32_bf16 v[16:19], v[176:179], v[200:203], v[16:19]
	v_mfma_f32_16x16x32_bf16 v[4:7], v[168:171], v[208:211], v[4:7]
	v_mfma_f32_16x16x32_bf16 v[0:3], v[176:179], v[208:211], v[0:3]
	s_setprio 0
	s_barrier
; #define PG8_STAGE(bufoff, gbase, voff) do { _Pragma("unroll") for (int _i = 0; _i < 2; ++_i) \
;         __builtin_amdgcn_global_load_lds((const unsigned*)((const char*)(gbase) + (voff)[_i]), (LAS unsigned*)(lds + (bufoff) + ldsw + _i * 8192), 16, 0, 0); } while (0)
; #define PG8_LDA(dst, b, h) do { _Pragma("unroll") for (int m = 0; m < 4; ++m) _Pragma("unroll") for (int k = 0; k < 2; ++k) dst[m][k] = *(const LAS bf16x8*)(lds + PG8_SA(b, h) + aoff + m * 2048 + k * 1024); } while (0)
; #define PG8_LDB(dst, b, h) do { _Pragma("unroll") for (int n = 0; n < 2; ++n) _Pragma("unroll") for (int k = 0; k < 2; ++k) dst[n][k] = *(const LAS bf16x8*)(lds + PG8_SB(b, h) + boff + n * 2048 + k * 1024); } while (0)
; #define PG8_MMA(ai, bj, At, Bt) do { __builtin_amdgcn_s_setprio(1); _Pragma("unroll") for (int m = 0; m < 4; ++m) _Pragma("unroll") for (int n = 0; n < 2; ++n) _Pragma("unroll") for (int k = 0; k < 2; ++k) \
;         acc[ai][bj][m][n] = __builtin_amdgcn_mfma_f32_16x16x32_bf16(Bt[n][k], At[m][k], acc[ai][bj][m][n], 0, 0, 0); __builtin_amdgcn_s_setprio(0); } while (0)
; #define PG8_WAIT_V(n) asm volatile("s_waitcnt vmcnt(" #n ")" ::: "memory")
; #define PG8_WAIT_L(n) asm volatile("s_waitcnt lgkmcnt(" #n ")" ::: "memory")
; #define PG8_BAR __builtin_amdgcn_s_barrier()
; #define PG8_SCHED __builtin_amdgcn_sched_barrier(0)
; template <class Epi>
; __device__ __forceinline__ void gemm_phase(LAS unsigned char* lds, const Gemm g, const StaticOrder S, const Epi E) {
;     ...
;             PG8_LDB(B0, 1, 0); PG8_LDB(B1, 1, 1); PG8_SCHED; PG8_LDA(At, 1, 0); PG8_STAGE(PG8_SA(0, 1), a2 + hstepA, voffA);
;             PG8_WAIT_V(8); PG8_WAIT_L(0); PG8_BAR; PG8_MMA(0, 0, At, B0); PG8_MMA(0, 1, At, B1); PG8_BAR; PG8_SCHED;
;             PG8_LDA(At, 1, 1); PG8_STAGE(PG8_SB(1, 0), b3, voffB); PG8_STAGE(PG8_SB(1, 1), b3 + hstepB, voffB); PG8_STAGE(PG8_SA(1, 0), a3, voffA);
;             PG8_WAIT_V(8); PG8_WAIT_L(0); PG8_BAR; PG8_MMA(1, 0, At, B0); PG8_MMA(1, 1, At, B1); PG8_BAR; PG8_SCHED;
	s_add_i32 s72, 0, 0x18000
	s_add_i32 s73, 0, 0x1c000
	v_add_u32_e32 v152, s72, v164
	v_add_u32_e32 v176, s73, v164
	ds_read_b128 v[128:131], v152
	ds_read_b128 v[132:135], v152 offset:1024
	ds_read_b128 v[136:139], v152 offset:2048
	ds_read_b128 v[152:155], v152 offset:3072
	ds_read_b128 v[156:159], v176
	ds_read_b128 v[168:171], v176 offset:1024
	ds_read_b128 v[172:175], v176 offset:2048
	ds_read_b128 v[176:179], v176 offset:3072
	s_add_u32 s46, s46, 0x160000
	s_addc_u32 s47, s47, 0
	s_mov_b32 m0, s52
	ds_read_b128 v[180:183], v166 offset:32768
	ds_read_b128 v[184:187], v166 offset:33792
	ds_read_b128 v[188:191], v166 offset:34816
	ds_read_b128 v[192:195], v166 offset:35840
	ds_read_b128 v[196:199], v166 offset:36864
	ds_read_b128 v[200:203], v166 offset:37888
	ds_read_b128 v[204:207], v166 offset:38912
	ds_read_b128 v[208:211], v166 offset:39936
	global_load_lds_dwordx4 v140, s[46:47]
	s_mov_b32 m0, s53
	s_nop 0
	global_load_lds_dwordx4 v144, s[46:47]
	s_waitcnt vmcnt(8)
	s_waitcnt lgkmcnt(0)
	s_barrier
	s_setprio 1
	s_waitcnt lgkmcnt(0)
	v_mfma_f32_16x16x32_bf16 v[124:127], v[128:131], v[180:183], v[124:127]
	v_mfma_f32_16x16x32_bf16 v[120:123], v[136:139], v[180:183], v[120:123]
	v_mfma_f32_16x16x32_bf16 v[108:111], v[128:131], v[188:191], v[108:111]
	v_mfma_f32_16x16x32_bf16 v[104:107], v[136:139], v[188:191], v[104:107]
	v_mfma_f32_16x16x32_bf16 v[92:95], v[128:131], v[196:199], v[92:95]
	v_mfma_f32_16x16x32_bf16 v[88:91], v[136:139], v[196:199], v[88:91]
	v_mfma_f32_16x16x32_bf16 v[76:79], v[128:131], v[204:207], v[76:79]
	v_mfma_f32_16x16x32_bf16 v[72:75], v[136:139], v[204:207], v[72:75]
	v_mfma_f32_16x16x32_bf16 v[124:127], v[132:135], v[184:187], v[124:127]
	v_mfma_f32_16x16x32_bf16 v[120:123], v[152:155], v[184:187], v[120:123]
	v_mfma_f32_16x16x32_bf16 v[108:111], v[132:135], v[192:195], v[108:111]
	v_mfma_f32_16x16x32_bf16 v[104:107], v[152:155], v[192:195], v[104:107]
	v_mfma_f32_16x16x32_bf16 v[92:95], v[132:135], v[200:203], v[92:95]
	v_mfma_f32_16x16x32_bf16 v[88:91], v[152:155], v[200:203], v[88:91]
	v_mfma_f32_16x16x32_bf16 v[76:79], v[132:135], v[208:211], v[76:79]
	v_mfma_f32_16x16x32_bf16 v[72:75], v[152:155], v[208:211], v[72:75]
	s_setprio 0
	s_setprio 1
	v_mfma_f32_16x16x32_bf16 v[116:119], v[156:159], v[180:183], v[116:119]
	v_mfma_f32_16x16x32_bf16 v[112:115], v[172:175], v[180:183], v[112:115]
	v_mfma_f32_16x16x32_bf16 v[100:103], v[156:159], v[188:191], v[100:103]
	v_mfma_f32_16x16x32_bf16 v[96:99], v[172:175], v[188:191], v[96:99]
	v_mfma_f32_16x16x32_bf16 v[84:87], v[156:159], v[196:199], v[84:87]
	v_mfma_f32_16x16x32_bf16 v[80:83], v[172:175], v[196:199], v[80:83]
	v_mfma_f32_16x16x32_bf16 v[68:71], v[156:159], v[204:207], v[68:71]
	v_mfma_f32_16x16x32_bf16 v[64:67], v[172:175], v[204:207], v[64:67]
	v_mfma_f32_16x16x32_bf16 v[116:119], v[168:171], v[184:187], v[116:119]
	v_mfma_f32_16x16x32_bf16 v[112:115], v[176:179], v[184:187], v[112:115]
	v_mfma_f32_16x16x32_bf16 v[100:103], v[168:171], v[192:195], v[100:103]
	v_mfma_f32_16x16x32_bf16 v[96:99], v[176:179], v[192:195], v[96:99]
	v_mfma_f32_16x16x32_bf16 v[84:87], v[168:171], v[200:203], v[84:87]
	v_mfma_f32_16x16x32_bf16 v[80:83], v[176:179], v[200:203], v[80:83]
	v_mfma_f32_16x16x32_bf16 v[68:71], v[168:171], v[208:211], v[68:71]
	v_mfma_f32_16x16x32_bf16 v[64:67], v[176:179], v[208:211], v[64:67]
	s_setprio 0
	s_barrier
	s_add_u32 s42, s42, s44
	s_addc_u32 s43, s43, s45
	s_add_i32 s44, s72, s33
	s_mov_b32 m0, s44
	ds_read_b128 v[180:183], v166 offset:49152
	ds_read_b128 v[184:187], v166 offset:50176
	ds_read_b128 v[188:191], v166 offset:51200
	ds_read_b128 v[192:195], v166 offset:52224
	ds_read_b128 v[196:199], v166 offset:53248
	ds_read_b128 v[200:203], v166 offset:54272
	ds_read_b128 v[204:207], v166 offset:55296
	ds_read_b128 v[208:211], v166 offset:56320
	global_load_lds_dwordx4 v142, s[42:43]
	s_add_i32 m0, s44, 0x2000
	s_nop 0
	global_load_lds_dwordx4 v146, s[42:43]
	s_add_u32 s42, s42, 0x160000
	s_addc_u32 s43, s43, 0
	s_add_i32 s44, s73, s33
	s_mov_b32 m0, s44
	s_nop 0
	global_load_lds_dwordx4 v142, s[42:43]
	s_add_i32 m0, s44, 0x2000
	s_nop 0
	global_load_lds_dwordx4 v146, s[42:43]
	s_mov_b32 m0, s55
	s_nop 0
	global_load_lds_dwordx4 v140, s[48:49]
	s_mov_b32 m0, s56
	s_nop 0
	global_load_lds_dwordx4 v144, s[48:49]
	s_waitcnt vmcnt(8)
	s_waitcnt lgkmcnt(0)
	s_barrier
	s_setprio 1
	s_waitcnt lgkmcnt(0)
	v_mfma_f32_16x16x32_bf16 v[60:63], v[128:131], v[180:183], v[60:63]
	v_mfma_f32_16x16x32_bf16 v[56:59], v[136:139], v[180:183], v[56:59]
	v_mfma_f32_16x16x32_bf16 v[44:47], v[128:131], v[188:191], v[44:47]
	v_mfma_f32_16x16x32_bf16 v[40:43], v[136:139], v[188:191], v[40:43]
	v_mfma_f32_16x16x32_bf16 v[28:31], v[128:131], v[196:199], v[28:31]
	v_mfma_f32_16x16x32_bf16 v[24:27], v[136:139], v[196:199], v[24:27]
	v_mfma_f32_16x16x32_bf16 v[12:15], v[128:131], v[204:207], v[12:15]
	v_mfma_f32_16x16x32_bf16 v[8:11], v[136:139], v[204:207], v[8:11]
	v_mfma_f32_16x16x32_bf16 v[60:63], v[132:135], v[184:187], v[60:63]
	v_mfma_f32_16x16x32_bf16 v[56:59], v[152:155], v[184:187], v[56:59]
	v_mfma_f32_16x16x32_bf16 v[44:47], v[132:135], v[192:195], v[44:47]
	v_mfma_f32_16x16x32_bf16 v[40:43], v[152:155], v[192:195], v[40:43]
	v_mfma_f32_16x16x32_bf16 v[28:31], v[132:135], v[200:203], v[28:31]
	v_mfma_f32_16x16x32_bf16 v[24:27], v[152:155], v[200:203], v[24:27]
	v_mfma_f32_16x16x32_bf16 v[12:15], v[132:135], v[208:211], v[12:15]
	v_mfma_f32_16x16x32_bf16 v[8:11], v[152:155], v[208:211], v[8:11]
	s_setprio 0
	s_setprio 1
	v_mfma_f32_16x16x32_bf16 v[52:55], v[156:159], v[180:183], v[52:55]
	v_mfma_f32_16x16x32_bf16 v[48:51], v[172:175], v[180:183], v[48:51]
	v_mfma_f32_16x16x32_bf16 v[36:39], v[156:159], v[188:191], v[36:39]
	v_mfma_f32_16x16x32_bf16 v[32:35], v[172:175], v[188:191], v[32:35]
	v_mfma_f32_16x16x32_bf16 v[20:23], v[156:159], v[196:199], v[20:23]
	v_mfma_f32_16x16x32_bf16 v[16:19], v[172:175], v[196:199], v[16:19]
	v_mfma_f32_16x16x32_bf16 v[4:7], v[156:159], v[204:207], v[4:7]
	v_mfma_f32_16x16x32_bf16 v[0:3], v[172:175], v[204:207], v[0:3]
	v_mfma_f32_16x16x32_bf16 v[52:55], v[168:171], v[184:187], v[52:55]
	v_mfma_f32_16x16x32_bf16 v[48:51], v[176:179], v[184:187], v[48:51]
	v_mfma_f32_16x16x32_bf16 v[36:39], v[168:171], v[192:195], v[36:39]
	v_mfma_f32_16x16x32_bf16 v[32:35], v[176:179], v[192:195], v[32:35]
	v_mfma_f32_16x16x32_bf16 v[20:23], v[168:171], v[200:203], v[20:23]
	v_mfma_f32_16x16x32_bf16 v[16:19], v[176:179], v[200:203], v[16:19]
	v_mfma_f32_16x16x32_bf16 v[4:7], v[168:171], v[208:211], v[4:7]
	v_mfma_f32_16x16x32_bf16 v[0:3], v[176:179], v[208:211], v[0:3]
	s_setprio 0
	s_barrier
	s_cmpk_gt_u32 s70, 0x55
	s_mov_b32 s70, s71
	s_cbranch_scc1 .LBB0_211

; #define PG8_STAGE(bufoff, gbase, voff) do { _Pragma("unroll") for (int _i = 0; _i < 2; ++_i) \
;         __builtin_amdgcn_global_load_lds((const unsigned*)((const char*)(gbase) + (voff)[_i]), (LAS unsigned*)(lds + (bufoff) + ldsw + _i * 8192), 16, 0, 0); } while (0)
; #define PG8_WAIT_V(n) asm volatile("s_waitcnt vmcnt(" #n ")" ::: "memory")
; #define PG8_BAR __builtin_amdgcn_s_barrier()
; template <class Epi>
; __device__ __forceinline__ void gemm_phase(LAS unsigned char* lds, const Gemm g, const StaticOrder S, const Epi E) {
;     ...
;     const int aoff = lds_byte(wr * 64 + fr, fq * 8), boff = lds_byte(wc * 32 + fr, fq * 8);
;     ...
;     PG8_STAGE(PG8_SB(0, 0), cB, voffB); PG8_STAGE(PG8_SB(0, 1), cB + hstepB, voffB); PG8_STAGE(PG8_SA(0, 0), cA, voffA); PG8_STAGE(PG8_SA(0, 1), cA + hstepA, voffA);
;     if (wr == 1) PG8_BAR;
;     PG8_WAIT_V(2); PG8_BAR;
;     PG8_STAGE(PG8_SB(1, 0), cB + ksc, voffB); PG8_STAGE(PG8_SA(1, 0), cA + ksc, voffA); PG8_STAGE(PG8_SB(1, 1), cB + hstepB + ksc, voffB);
;     PG8_WAIT_V(6); PG8_BAR;
.LBB0_296:
	s_add_u32 s8, s82, 0x2a990000
	s_addc_u32 s9, s83, 0
	s_lshl_b32 s3, s3, 5
	s_mov_b64 s[44:45], 0x80
	s_and_b32 s3, s3, 0x60
	s_add_i32 m0, s31, 0x18000
	v_lshl_add_u64 v[6:7], v[6:7], 0, s[44:45]
	s_lshl_b32 s12, s1, 13
	s_lshl_b32 s13, s3, 7
	s_waitcnt vmcnt(2)
	s_barrier
	global_load_lds_dwordx4 v[6:7], off
	v_lshl_add_u64 v[4:5], v[4:5], 0, s[44:45]
	s_add_i32 m0, s31, 0x1a000
	s_add_i32 s58, s31, 0x8000
	s_add_i32 s59, s31, 0xa000
	global_load_lds_dwordx4 v[4:5], off
	v_lshl_add_u64 v[0:1], v[0:1], 0, s[44:45]
	s_mov_b32 m0, s58
	s_add_u32 s10, s34, 0x80080
	global_load_lds_dwordx4 v[0:1], off
	v_lshl_add_u64 v[0:1], v[2:3], 0, s[44:45]
	s_mov_b32 m0, s59
	s_addc_u32 s11, s35, 0
	global_load_lds_dwordx4 v[0:1], off
	s_add_i32 m0, s31, 0x1c000
	s_nop 0
	global_load_lds_dwordx4 v130, s[10:11]
	s_add_i32 m0, s31, 0x1e000
	v_lshlrev_b32_e32 v2, 2, v224
	global_load_lds_dwordx4 v134, s[10:11]
	v_and_b32_e32 v0, 15, v224
	v_lshlrev_b32_e32 v1, 1, v8
	s_sext_i32_i8 s69, s0
	v_lshl_or_b32 v142, s1, 6, v0
	v_lshl_or_b32 v0, v0, 6, v1
	v_and_b32_e32 v2, 32, v2
	v_lshlrev_b32_e32 v3, 6, v224
	s_movk_i32 s0, 0x3c0
	s_waitcnt vmcnt(6)
	s_ashr_i32 s60, s78, 31
	v_bitop3_b32 v0, v0, s12, v2 bitop3:0xde
	v_and_or_b32 v1, v3, s0, v1
	s_cmpk_lt_u32 s2, 0x100
	v_bitop3_b32 v143, s13, v1, v2 bitop3:0xf6
	v_add_u32_e32 v254, 0x10000, v143
	s_cselect_b64 s[10:11], -1, 0
	v_or_b32_e32 v144, s3, v8
	v_mov_b64_e32 v[136:137], 0x400
	v_mov_b64_e32 v[138:139], 0x3ff
	s_movk_i32 s61, 0x80
	s_add_i32 s62, 0, 0x10000
	s_add_i32 s63, 0, 0x14000
	v_add_u32_e32 v145, 0, v0
	v_mov_b32_e32 v146, 0x358637bd
	s_mov_b64 s[12:13], 0x100000
	s_mov_b32 s64, 0x100000
	s_mov_b64 s[14:15], 0x120000
	s_mov_b32 s65, 0x120000
	s_mov_b64 s[16:17], 0x140000
	s_mov_b32 s66, 0x140000
	s_mov_b64 s[18:19], 0x160000
	s_mov_b32 s67, 0x160000
	s_barrier
	s_branch .LBB0_299

; #define PG8_STAGE(bufoff, gbase, voff) do { _Pragma("unroll") for (int _i = 0; _i < 2; ++_i) \
;         __builtin_amdgcn_global_load_lds((const unsigned*)((const char*)(gbase) + (voff)[_i]), (LAS unsigned*)(lds + (bufoff) + ldsw + _i * 8192), 16, 0, 0); } while (0)
; #define PG8_LDA(dst, b, h) do { _Pragma("unroll") for (int m = 0; m < 4; ++m) _Pragma("unroll") for (int k = 0; k < 2; ++k) dst[m][k] = *(const LAS bf16x8*)(lds + PG8_SA(b, h) + aoff + m * 2048 + k * 1024); } while (0)
; #define PG8_LDB(dst, b, h) do { _Pragma("unroll") for (int n = 0; n < 2; ++n) _Pragma("unroll") for (int k = 0; k < 2; ++k) dst[n][k] = *(const LAS bf16x8*)(lds + PG8_SB(b, h) + boff + n * 2048 + k * 1024); } while (0)
; #define PG8_MMA(ai, bj, At, Bt) do { __builtin_amdgcn_s_setprio(1); _Pragma("unroll") for (int m = 0; m < 4; ++m) _Pragma("unroll") for (int n = 0; n < 2; ++n) _Pragma("unroll") for (int k = 0; k < 2; ++k) \
;         acc[ai][bj][m][n] = __builtin_amdgcn_mfma_f32_16x16x32_bf16(Bt[n][k], At[m][k], acc[ai][bj][m][n], 0, 0, 0); __builtin_amdgcn_s_setprio(0); } while (0)
; #define PG8_WAIT_V(n) asm volatile("s_waitcnt vmcnt(" #n ")" ::: "memory")
; #define PG8_WAIT_L(n) asm volatile("s_waitcnt lgkmcnt(" #n ")" ::: "memory")
; #define PG8_BAR __builtin_amdgcn_s_barrier()
; #define PG8_SCHED __builtin_amdgcn_sched_barrier(0)
; template <class Epi>
; __device__ __forceinline__ void gemm_phase(LAS unsigned char* lds, const Gemm g, const StaticOrder S, const Epi E) {
;     ...
;             const char* a1 = cA + (long)(t + 1) * ksc;
;             const char* a2 = last ? nA : cA + (long)(t + 2) * ksc; const char* b2 = last ? nB : cB + (long)(t + 2) * ksc;
;             const long ks3 = last ? ksn : ksc;
;             const char* a3 = a2 + ks3; const char* b3 = b2 + ks3;
;             PG8_LDB(B0, 0, 0); PG8_LDB(B1, 0, 1); PG8_SCHED; PG8_LDA(At, 0, 0); PG8_STAGE(PG8_SA(1, 1), a1 + hstepA, voffA);
;             PG8_WAIT_V(8); PG8_WAIT_L(0); PG8_BAR; PG8_MMA(0, 0, At, B0); PG8_MMA(0, 1, At, B1); PG8_BAR; PG8_SCHED;
;             PG8_LDA(At, 0, 1); PG8_STAGE(PG8_SB(0, 0), b2, voffB); PG8_STAGE(PG8_SB(0, 1), b2 + hstepB, voffB); PG8_STAGE(PG8_SA(0, 0), a2, voffA);
;             PG8_WAIT_V(8); PG8_WAIT_L(0); PG8_BAR; PG8_MMA(1, 0, At, B0); PG8_MMA(1, 1, At, B1); PG8_BAR; PG8_SCHED;
.LBB0_310:
	ds_read_b128 v[148:151], v254
	ds_read_b128 v[152:155], v254 offset:1024
	ds_read_b128 v[156:159], v254 offset:2048
	ds_read_b128 v[160:163], v254 offset:3072
	ds_read_b128 v[164:167], v254 offset:16384
	ds_read_b128 v[168:171], v254 offset:17408
	ds_read_b128 v[172:175], v254 offset:18432
	ds_read_b128 v[176:179], v254 offset:19456
	s_or_b32 s52, s70, 1
	s_mul_i32 s53, s45, s52
	s_mul_hi_u32 s72, s44, s52
	s_add_i32 s73, s72, s53
	s_mul_i32 s72, s44, s52
	s_add_u32 s52, s50, s48
	s_addc_u32 s53, s51, s49
	s_add_u32 s72, s21, s72
	s_addc_u32 s73, s23, s73
	s_add_i32 m0, s31, 0xc000
	ds_read_b128 v[180:183], v145
	ds_read_b128 v[184:187], v145 offset:1024
	ds_read_b128 v[188:191], v145 offset:2048
	ds_read_b128 v[192:195], v145 offset:3072
	ds_read_b128 v[196:199], v145 offset:4096
	ds_read_b128 v[200:203], v145 offset:5120
	ds_read_b128 v[204:207], v145 offset:6144
	ds_read_b128 v[208:211], v145 offset:7168
	global_load_lds_dwordx4 v128, s[72:73]
	s_add_i32 m0, s31, 0xe000
	s_nop 0
	global_load_lds_dwordx4 v132, s[72:73]
	s_waitcnt vmcnt(8)
	s_waitcnt lgkmcnt(0)
	s_barrier
	s_setprio 1
	s_waitcnt lgkmcnt(0)
	v_mfma_f32_16x16x32_bf16 v[124:127], v[148:151], v[180:183], v[124:127]
	v_mfma_f32_16x16x32_bf16 v[120:123], v[156:159], v[180:183], v[120:123]
	v_mfma_f32_16x16x32_bf16 v[116:119], v[148:151], v[188:191], v[116:119]
	v_mfma_f32_16x16x32_bf16 v[112:115], v[156:159], v[188:191], v[112:115]
	v_mfma_f32_16x16x32_bf16 v[108:111], v[148:151], v[196:199], v[108:111]
	v_mfma_f32_16x16x32_bf16 v[100:103], v[156:159], v[196:199], v[100:103]
	v_mfma_f32_16x16x32_bf16 v[76:79], v[148:151], v[204:207], v[76:79]
	v_mfma_f32_16x16x32_bf16 v[72:75], v[156:159], v[204:207], v[72:75]
	v_mfma_f32_16x16x32_bf16 v[124:127], v[152:155], v[184:187], v[124:127]
	v_mfma_f32_16x16x32_bf16 v[120:123], v[160:163], v[184:187], v[120:123]
	v_mfma_f32_16x16x32_bf16 v[116:119], v[152:155], v[192:195], v[116:119]
	v_mfma_f32_16x16x32_bf16 v[112:115], v[160:163], v[192:195], v[112:115]
	v_mfma_f32_16x16x32_bf16 v[108:111], v[152:155], v[200:203], v[108:111]
	v_mfma_f32_16x16x32_bf16 v[100:103], v[160:163], v[200:203], v[100:103]
	v_mfma_f32_16x16x32_bf16 v[76:79], v[152:155], v[208:211], v[76:79]
	v_mfma_f32_16x16x32_bf16 v[72:75], v[160:163], v[208:211], v[72:75]
	s_setprio 0
	s_setprio 1
	v_mfma_f32_16x16x32_bf16 v[104:107], v[164:167], v[180:183], v[104:107]
	v_mfma_f32_16x16x32_bf16 v[96:99], v[172:175], v[180:183], v[96:99]
	v_mfma_f32_16x16x32_bf16 v[92:95], v[164:167], v[188:191], v[92:95]
	v_mfma_f32_16x16x32_bf16 v[88:91], v[172:175], v[188:191], v[88:91]
	v_mfma_f32_16x16x32_bf16 v[84:87], v[164:167], v[196:199], v[84:87]
	v_mfma_f32_16x16x32_bf16 v[80:83], v[172:175], v[196:199], v[80:83]
	v_mfma_f32_16x16x32_bf16 v[68:71], v[164:167], v[204:207], v[68:71]
	v_mfma_f32_16x16x32_bf16 v[64:67], v[172:175], v[204:207], v[64:67]
	v_mfma_f32_16x16x32_bf16 v[104:107], v[168:171], v[184:187], v[104:107]
	v_mfma_f32_16x16x32_bf16 v[96:99], v[176:179], v[184:187], v[96:99]
	v_mfma_f32_16x16x32_bf16 v[92:95], v[168:171], v[192:195], v[92:95]
	v_mfma_f32_16x16x32_bf16 v[88:91], v[176:179], v[192:195], v[88:91]
	v_mfma_f32_16x16x32_bf16 v[84:87], v[168:171], v[200:203], v[84:87]
	v_mfma_f32_16x16x32_bf16 v[80:83], v[176:179], v[200:203], v[80:83]
	v_mfma_f32_16x16x32_bf16 v[68:71], v[168:171], v[208:211], v[68:71]
	v_mfma_f32_16x16x32_bf16 v[64:67], v[176:179], v[208:211], v[64:67]
	s_setprio 0
	s_barrier
	s_add_i32 s72, s62, s54
	s_mov_b32 m0, s72
	ds_read_b128 v[180:183], v145 offset:16384
	ds_read_b128 v[184:187], v145 offset:17408
	ds_read_b128 v[188:191], v145 offset:18432
	ds_read_b128 v[192:195], v145 offset:19456
	ds_read_b128 v[196:199], v145 offset:20480
	ds_read_b128 v[200:203], v145 offset:21504
	ds_read_b128 v[204:207], v145 offset:22528
	ds_read_b128 v[208:211], v145 offset:23552
	global_load_lds_dwordx4 v130, s[46:47]
	s_add_i32 m0, s72, 0x2000
	s_add_u32 s72, s46, 0x80000
	s_addc_u32 s73, s47, 0
	s_add_i32 s74, s63, s54
	global_load_lds_dwordx4 v134, s[46:47]
	s_mov_b32 m0, s74
	s_nop 0
	global_load_lds_dwordx4 v130, s[72:73]
	s_add_i32 m0, s74, 0x2000
	s_nop 0
	global_load_lds_dwordx4 v134, s[72:73]
	s_mov_b32 m0, s31
	s_nop 0
	global_load_lds_dwordx4 v128, s[50:51]
	s_mov_b32 m0, s55
	s_nop 0
	global_load_lds_dwordx4 v132, s[50:51]
	s_waitcnt vmcnt(8)
	s_waitcnt lgkmcnt(0)
	s_barrier
	s_setprio 1
	s_waitcnt lgkmcnt(0)
	v_mfma_f32_16x16x32_bf16 v[60:63], v[148:151], v[180:183], v[60:63]
	v_mfma_f32_16x16x32_bf16 v[56:59], v[156:159], v[180:183], v[56:59]
	v_mfma_f32_16x16x32_bf16 v[48:51], v[148:151], v[188:191], v[48:51]
	v_mfma_f32_16x16x32_bf16 v[40:43], v[156:159], v[188:191], v[40:43]
	v_mfma_f32_16x16x32_bf16 v[32:35], v[148:151], v[196:199], v[32:35]
	v_mfma_f32_16x16x32_bf16 v[24:27], v[156:159], v[196:199], v[24:27]
	v_mfma_f32_16x16x32_bf16 v[16:19], v[148:151], v[204:207], v[16:19]
	v_mfma_f32_16x16x32_bf16 v[8:11], v[156:159], v[204:207], v[8:11]
	v_mfma_f32_16x16x32_bf16 v[60:63], v[152:155], v[184:187], v[60:63]
	v_mfma_f32_16x16x32_bf16 v[56:59], v[160:163], v[184:187], v[56:59]
	v_mfma_f32_16x16x32_bf16 v[48:51], v[152:155], v[192:195], v[48:51]
	v_mfma_f32_16x16x32_bf16 v[40:43], v[160:163], v[192:195], v[40:43]
	v_mfma_f32_16x16x32_bf16 v[32:35], v[152:155], v[200:203], v[32:35]
	v_mfma_f32_16x16x32_bf16 v[24:27], v[160:163], v[200:203], v[24:27]
	v_mfma_f32_16x16x32_bf16 v[16:19], v[152:155], v[208:211], v[16:19]
	v_mfma_f32_16x16x32_bf16 v[8:11], v[160:163], v[208:211], v[8:11]
	s_setprio 0
	s_setprio 1
	v_mfma_f32_16x16x32_bf16 v[52:55], v[164:167], v[180:183], v[52:55]
	v_mfma_f32_16x16x32_bf16 v[44:47], v[172:175], v[180:183], v[44:47]
	v_mfma_f32_16x16x32_bf16 v[36:39], v[164:167], v[188:191], v[36:39]
	v_mfma_f32_16x16x32_bf16 v[28:31], v[172:175], v[188:191], v[28:31]
	v_mfma_f32_16x16x32_bf16 v[20:23], v[164:167], v[196:199], v[20:23]
	v_mfma_f32_16x16x32_bf16 v[12:15], v[172:175], v[196:199], v[12:15]
	v_mfma_f32_16x16x32_bf16 v[4:7], v[164:167], v[204:207], v[4:7]
	v_mfma_f32_16x16x32_bf16 v[0:3], v[172:175], v[204:207], v[0:3]
	v_mfma_f32_16x16x32_bf16 v[52:55], v[168:171], v[184:187], v[52:55]
	v_mfma_f32_16x16x32_bf16 v[44:47], v[176:179], v[184:187], v[44:47]
	v_mfma_f32_16x16x32_bf16 v[36:39], v[168:171], v[192:195], v[36:39]
	v_mfma_f32_16x16x32_bf16 v[28:31], v[176:179], v[192:195], v[28:31]
	v_mfma_f32_16x16x32_bf16 v[20:23], v[168:171], v[200:203], v[20:23]
	v_mfma_f32_16x16x32_bf16 v[12:15], v[176:179], v[200:203], v[12:15]
	v_mfma_f32_16x16x32_bf16 v[4:7], v[168:171], v[208:211], v[4:7]
	v_mfma_f32_16x16x32_bf16 v[0:3], v[176:179], v[208:211], v[0:3]
	s_setprio 0
	s_barrier
; #define PG8_STAGE(bufoff, gbase, voff) do { _Pragma("unroll") for (int _i = 0; _i < 2; ++_i) \
;         __builtin_amdgcn_global_load_lds((const unsigned*)((const char*)(gbase) + (voff)[_i]), (LAS unsigned*)(lds + (bufoff) + ldsw + _i * 8192), 16, 0, 0); } while (0)
; #define PG8_LDA(dst, b, h) do { _Pragma("unroll") for (int m = 0; m < 4; ++m) _Pragma("unroll") for (int k = 0; k < 2; ++k) dst[m][k] = *(const LAS bf16x8*)(lds + PG8_SA(b, h) + aoff + m * 2048 + k * 1024); } while (0)
; #define PG8_LDB(dst, b, h) do { _Pragma("unroll") for (int n = 0; n < 2; ++n) _Pragma("unroll") for (int k = 0; k < 2; ++k) dst[n][k] = *(const LAS bf16x8*)(lds + PG8_SB(b, h) + boff + n * 2048 + k * 1024); } while (0)
; #define PG8_MMA(ai, bj, At, Bt) do { __builtin_amdgcn_s_setprio(1); _Pragma("unroll") for (int m = 0; m < 4; ++m) _Pragma("unroll") for (int n = 0; n < 2; ++n) _Pragma("unroll") for (int k = 0; k < 2; ++k) \
;         acc[ai][bj][m][n] = __builtin_amdgcn_mfma_f32_16x16x32_bf16(Bt[n][k], At[m][k], acc[ai][bj][m][n], 0, 0, 0); __builtin_amdgcn_s_setprio(0); } while (0)
; #define PG8_WAIT_V(n) asm volatile("s_waitcnt vmcnt(" #n ")" ::: "memory")
; #define PG8_WAIT_L(n) asm volatile("s_waitcnt lgkmcnt(" #n ")" ::: "memory")
; #define PG8_BAR __builtin_amdgcn_s_barrier()
; #define PG8_SCHED __builtin_amdgcn_sched_barrier(0)
; template <class Epi>
; __device__ __forceinline__ void gemm_phase(LAS unsigned char* lds, const Gemm g, const StaticOrder S, const Epi E) {
;     ...
;             PG8_LDB(B0, 1, 0); PG8_LDB(B1, 1, 1); PG8_SCHED; PG8_LDA(At, 1, 0); PG8_STAGE(PG8_SA(0, 1), a2 + hstepA, voffA);
;             PG8_WAIT_V(8); PG8_WAIT_L(0); PG8_BAR; PG8_MMA(0, 0, At, B0); PG8_MMA(0, 1, At, B1); PG8_BAR; PG8_SCHED;
;             PG8_LDA(At, 1, 1); PG8_STAGE(PG8_SB(1, 0), b3, voffB); PG8_STAGE(PG8_SB(1, 1), b3 + hstepB, voffB); PG8_STAGE(PG8_SA(1, 0), a3, voffA);
;             PG8_WAIT_V(8); PG8_WAIT_L(0); PG8_BAR; PG8_MMA(1, 0, At, B0); PG8_MMA(1, 1, At, B1); PG8_BAR; PG8_SCHED;
	s_add_i32 s72, 0, 0x18000
	s_add_i32 s73, 0, 0x1c000
	ds_read_b128 v[148:151], v254 offset:32768
	ds_read_b128 v[152:155], v254 offset:33792
	ds_read_b128 v[156:159], v254 offset:34816
	ds_read_b128 v[160:163], v254 offset:35840
	ds_read_b128 v[164:167], v254 offset:49152
	ds_read_b128 v[168:171], v254 offset:50176
	ds_read_b128 v[172:175], v254 offset:51200
	ds_read_b128 v[176:179], v254 offset:52224
	s_add_u32 s50, s50, 0x80000
	s_addc_u32 s51, s51, 0
	s_mov_b32 m0, s56
	ds_read_b128 v[180:183], v145 offset:32768
	ds_read_b128 v[184:187], v145 offset:33792
	ds_read_b128 v[188:191], v145 offset:34816
	ds_read_b128 v[192:195], v145 offset:35840
	ds_read_b128 v[196:199], v145 offset:36864
	ds_read_b128 v[200:203], v145 offset:37888
	ds_read_b128 v[204:207], v145 offset:38912
	ds_read_b128 v[208:211], v145 offset:39936
	global_load_lds_dwordx4 v128, s[50:51]
	s_mov_b32 m0, s57
	s_nop 0
	global_load_lds_dwordx4 v132, s[50:51]
	s_waitcnt vmcnt(8)
	s_waitcnt lgkmcnt(0)
	s_barrier
	s_setprio 1
	s_waitcnt lgkmcnt(0)
	v_mfma_f32_16x16x32_bf16 v[124:127], v[148:151], v[180:183], v[124:127]
	v_mfma_f32_16x16x32_bf16 v[120:123], v[156:159], v[180:183], v[120:123]
	v_mfma_f32_16x16x32_bf16 v[116:119], v[148:151], v[188:191], v[116:119]
	v_mfma_f32_16x16x32_bf16 v[112:115], v[156:159], v[188:191], v[112:115]
	v_mfma_f32_16x16x32_bf16 v[108:111], v[148:151], v[196:199], v[108:111]
	v_mfma_f32_16x16x32_bf16 v[100:103], v[156:159], v[196:199], v[100:103]
	v_mfma_f32_16x16x32_bf16 v[76:79], v[148:151], v[204:207], v[76:79]
	v_mfma_f32_16x16x32_bf16 v[72:75], v[156:159], v[204:207], v[72:75]
	v_mfma_f32_16x16x32_bf16 v[124:127], v[152:155], v[184:187], v[124:127]
	v_mfma_f32_16x16x32_bf16 v[120:123], v[160:163], v[184:187], v[120:123]
	v_mfma_f32_16x16x32_bf16 v[116:119], v[152:155], v[192:195], v[116:119]
	v_mfma_f32_16x16x32_bf16 v[112:115], v[160:163], v[192:195], v[112:115]
	v_mfma_f32_16x16x32_bf16 v[108:111], v[152:155], v[200:203], v[108:111]
	v_mfma_f32_16x16x32_bf16 v[100:103], v[160:163], v[200:203], v[100:103]
	v_mfma_f32_16x16x32_bf16 v[76:79], v[152:155], v[208:211], v[76:79]
	v_mfma_f32_16x16x32_bf16 v[72:75], v[160:163], v[208:211], v[72:75]
	s_setprio 0
	s_setprio 1
	v_mfma_f32_16x16x32_bf16 v[104:107], v[164:167], v[180:183], v[104:107]
	v_mfma_f32_16x16x32_bf16 v[96:99], v[172:175], v[180:183], v[96:99]
	v_mfma_f32_16x16x32_bf16 v[92:95], v[164:167], v[188:191], v[92:95]
	v_mfma_f32_16x16x32_bf16 v[88:91], v[172:175], v[188:191], v[88:91]
	v_mfma_f32_16x16x32_bf16 v[84:87], v[164:167], v[196:199], v[84:87]
	v_mfma_f32_16x16x32_bf16 v[80:83], v[172:175], v[196:199], v[80:83]
	v_mfma_f32_16x16x32_bf16 v[68:71], v[164:167], v[204:207], v[68:71]
	v_mfma_f32_16x16x32_bf16 v[64:67], v[172:175], v[204:207], v[64:67]
	v_mfma_f32_16x16x32_bf16 v[104:107], v[168:171], v[184:187], v[104:107]
	v_mfma_f32_16x16x32_bf16 v[96:99], v[176:179], v[184:187], v[96:99]
	v_mfma_f32_16x16x32_bf16 v[92:95], v[168:171], v[192:195], v[92:95]
	v_mfma_f32_16x16x32_bf16 v[88:91], v[176:179], v[192:195], v[88:91]
	v_mfma_f32_16x16x32_bf16 v[84:87], v[168:171], v[200:203], v[84:87]
	v_mfma_f32_16x16x32_bf16 v[80:83], v[176:179], v[200:203], v[80:83]
	v_mfma_f32_16x16x32_bf16 v[68:71], v[168:171], v[208:211], v[68:71]
	v_mfma_f32_16x16x32_bf16 v[64:67], v[176:179], v[208:211], v[64:67]
	s_setprio 0
	s_barrier
	s_add_u32 s46, s46, s48
	s_addc_u32 s47, s47, s49
	s_add_i32 s48, s72, s54
	s_mov_b32 m0, s48
	ds_read_b128 v[180:183], v145 offset:49152
	ds_read_b128 v[184:187], v145 offset:50176
	ds_read_b128 v[188:191], v145 offset:51200
	ds_read_b128 v[192:195], v145 offset:52224
	ds_read_b128 v[196:199], v145 offset:53248
	ds_read_b128 v[200:203], v145 offset:54272
	ds_read_b128 v[204:207], v145 offset:55296
	ds_read_b128 v[208:211], v145 offset:56320
	global_load_lds_dwordx4 v130, s[46:47]
	s_add_i32 m0, s48, 0x2000
	s_nop 0
	global_load_lds_dwordx4 v134, s[46:47]
	s_add_u32 s46, s46, 0x80000
	s_addc_u32 s47, s47, 0
	s_add_i32 s48, s73, s54
	s_mov_b32 m0, s48
	s_nop 0
	global_load_lds_dwordx4 v130, s[46:47]
	s_add_i32 m0, s48, 0x2000
	s_nop 0
	global_load_lds_dwordx4 v134, s[46:47]
	s_mov_b32 m0, s58
	s_nop 0
	global_load_lds_dwordx4 v128, s[52:53]
	s_mov_b32 m0, s59
	s_nop 0
	global_load_lds_dwordx4 v132, s[52:53]
	s_waitcnt vmcnt(8)
	s_waitcnt lgkmcnt(0)
	s_barrier
	s_setprio 1
	s_waitcnt lgkmcnt(0)
	v_mfma_f32_16x16x32_bf16 v[60:63], v[148:151], v[180:183], v[60:63]
	v_mfma_f32_16x16x32_bf16 v[56:59], v[156:159], v[180:183], v[56:59]
	v_mfma_f32_16x16x32_bf16 v[48:51], v[148:151], v[188:191], v[48:51]
	v_mfma_f32_16x16x32_bf16 v[40:43], v[156:159], v[188:191], v[40:43]
	v_mfma_f32_16x16x32_bf16 v[32:35], v[148:151], v[196:199], v[32:35]
	v_mfma_f32_16x16x32_bf16 v[24:27], v[156:159], v[196:199], v[24:27]
	v_mfma_f32_16x16x32_bf16 v[16:19], v[148:151], v[204:207], v[16:19]
	v_mfma_f32_16x16x32_bf16 v[8:11], v[156:159], v[204:207], v[8:11]
	v_mfma_f32_16x16x32_bf16 v[60:63], v[152:155], v[184:187], v[60:63]
	v_mfma_f32_16x16x32_bf16 v[56:59], v[160:163], v[184:187], v[56:59]
	v_mfma_f32_16x16x32_bf16 v[48:51], v[152:155], v[192:195], v[48:51]
	v_mfma_f32_16x16x32_bf16 v[40:43], v[160:163], v[192:195], v[40:43]
	v_mfma_f32_16x16x32_bf16 v[32:35], v[152:155], v[200:203], v[32:35]
	v_mfma_f32_16x16x32_bf16 v[24:27], v[160:163], v[200:203], v[24:27]
	v_mfma_f32_16x16x32_bf16 v[16:19], v[152:155], v[208:211], v[16:19]
	v_mfma_f32_16x16x32_bf16 v[8:11], v[160:163], v[208:211], v[8:11]
	s_setprio 0
	s_setprio 1
	v_mfma_f32_16x16x32_bf16 v[52:55], v[164:167], v[180:183], v[52:55]
	v_mfma_f32_16x16x32_bf16 v[44:47], v[172:175], v[180:183], v[44:47]
	v_mfma_f32_16x16x32_bf16 v[36:39], v[164:167], v[188:191], v[36:39]
	v_mfma_f32_16x16x32_bf16 v[28:31], v[172:175], v[188:191], v[28:31]
	v_mfma_f32_16x16x32_bf16 v[20:23], v[164:167], v[196:199], v[20:23]
	v_mfma_f32_16x16x32_bf16 v[12:15], v[172:175], v[196:199], v[12:15]
	v_mfma_f32_16x16x32_bf16 v[4:7], v[164:167], v[204:207], v[4:7]
	v_mfma_f32_16x16x32_bf16 v[0:3], v[172:175], v[204:207], v[0:3]
	v_mfma_f32_16x16x32_bf16 v[52:55], v[168:171], v[184:187], v[52:55]
	v_mfma_f32_16x16x32_bf16 v[44:47], v[176:179], v[184:187], v[44:47]
	v_mfma_f32_16x16x32_bf16 v[36:39], v[168:171], v[192:195], v[36:39]
	v_mfma_f32_16x16x32_bf16 v[28:31], v[176:179], v[192:195], v[28:31]
	v_mfma_f32_16x16x32_bf16 v[20:23], v[168:171], v[200:203], v[20:23]
	v_mfma_f32_16x16x32_bf16 v[12:15], v[176:179], v[200:203], v[12:15]
	v_mfma_f32_16x16x32_bf16 v[4:7], v[168:171], v[208:211], v[4:7]
	v_mfma_f32_16x16x32_bf16 v[0:3], v[176:179], v[208:211], v[0:3]
	s_setprio 0
	s_barrier
	s_cmp_gt_u32 s70, 29
	s_mov_b32 s70, s71
	s_cbranch_scc1 .LBB0_315

; #define PG8_STAGE(bufoff, gbase, voff) do { _Pragma("unroll") for (int _i = 0; _i < 2; ++_i) \
;         __builtin_amdgcn_global_load_lds((const unsigned*)((const char*)(gbase) + (voff)[_i]), (LAS unsigned*)(lds + (bufoff) + ldsw + _i * 8192), 16, 0, 0); } while (0)
; #define PG8_WAIT_V(n) asm volatile("s_waitcnt vmcnt(" #n ")" ::: "memory")
; #define PG8_BAR __builtin_amdgcn_s_barrier()
; template <class Epi>
; __device__ __forceinline__ void gemm_phase(LAS unsigned char* lds, const Gemm g, const StaticOrder S, const Epi E) {
;     ...
;     const int aoff = lds_byte(wr * 64 + fr, fq * 8), boff = lds_byte(wc * 32 + fr, fq * 8);
;     ...
;     PG8_STAGE(PG8_SB(0, 0), cB, voffB); PG8_STAGE(PG8_SB(0, 1), cB + hstepB, voffB); PG8_STAGE(PG8_SA(0, 0), cA, voffA); PG8_STAGE(PG8_SA(0, 1), cA + hstepA, voffA);
;     if (wr == 1) PG8_BAR;
;     PG8_WAIT_V(2); PG8_BAR;
;     PG8_STAGE(PG8_SB(1, 0), cB + ksc, voffB); PG8_STAGE(PG8_SA(1, 0), cA + ksc, voffA); PG8_STAGE(PG8_SB(1, 1), cB + hstepB + ksc, voffB);
;     PG8_WAIT_V(6); PG8_BAR;
.LBB0_467:
	s_add_u32 s10, s82, 0xa680800
	s_addc_u32 s11, s83, 0
	s_lshl_b32 s1, s1, 5
	s_mov_b64 s[48:49], 0x80
	s_and_b32 s1, s1, 0x60
	s_add_i32 m0, s45, 0x18000
	v_lshl_add_u64 v[6:7], v[6:7], 0, s[48:49]
	s_lshl_b32 s13, s0, 13
	s_lshl_b32 s14, s1, 7
	s_ashr_i32 s17, s79, 31
	s_waitcnt vmcnt(2)
	s_barrier
	global_load_lds_dwordx4 v[6:7], off
	v_lshl_add_u64 v[4:5], v[4:5], 0, s[48:49]
	s_add_i32 m0, s45, 0x1a000
	s_add_i32 s63, s45, 0x8000
	s_add_i32 s64, s45, 0xa000
	global_load_lds_dwordx4 v[4:5], off
	v_lshl_add_u64 v[0:1], v[0:1], 0, s[48:49]
	s_mov_b32 m0, s63
	s_add_u32 s2, s50, 0x10080
	global_load_lds_dwordx4 v[0:1], off
	v_lshl_add_u64 v[0:1], v[2:3], 0, s[48:49]
	s_mov_b32 m0, s64
	s_addc_u32 s3, s51, 0
	global_load_lds_dwordx4 v[0:1], off
	s_add_i32 m0, s45, 0x1c000
	s_nop 0
	global_load_lds_dwordx4 v146, s[2:3]
	s_add_i32 m0, s45, 0x1e000
	v_lshlrev_b32_e32 v2, 2, v224
	global_load_lds_dwordx4 v150, s[2:3]
	v_and_b32_e32 v0, 15, v224
	v_lshlrev_b32_e32 v1, 1, v8
	s_ashr_i32 s65, s78, 31
	v_lshl_or_b32 v160, s0, 6, v0
	v_lshl_or_b32 v0, v0, 6, v1
	v_and_b32_e32 v2, 32, v2
	v_lshlrev_b32_e32 v3, 6, v224
	s_movk_i32 s0, 0x3c0
	s_cmpk_lt_u32 s12, 0x100
	v_bitop3_b32 v0, v0, s13, v2 bitop3:0xde
	v_and_or_b32 v1, v3, s0, v1
	s_cselect_b64 s[12:13], -1, 0
	s_cmp_lg_u64 s[6:7], 0
	v_bitop3_b32 v161, s14, v1, v2 bitop3:0xf6
	v_add_u32_e32 v254, 0x10000, v161
	s_waitcnt vmcnt(6)
	s_cselect_b64 s[14:15], -1, 0
	s_add_u32 s16, s79, s78
	s_addc_u32 s17, s17, s65
	s_add_i32 s66, 0, 0x10000
	s_add_i32 s67, 0, 0x14000
	v_or_b32_e32 v162, s1, v8
	v_mov_b64_e32 v[152:153], 0x100
	v_mov_b64_e32 v[154:155], 0xff
	v_add_u32_e32 v163, s66, v161
	v_add_u32_e32 v164, s67, v161
	v_add_u32_e32 v165, 0, v0
	s_mov_b64 s[18:19], 0x90000
	s_mov_b32 s68, 0x90000
	s_mov_b64 s[20:21], 0xa0000
	s_mov_b32 s69, 0xa0000
	s_mov_b64 s[22:23], 0xb0000
	s_mov_b32 s70, 0xb0000
	s_barrier
	s_branch .LBB0_470

; #define PG8_STAGE(bufoff, gbase, voff) do { _Pragma("unroll") for (int _i = 0; _i < 2; ++_i) \
;         __builtin_amdgcn_global_load_lds((const unsigned*)((const char*)(gbase) + (voff)[_i]), (LAS unsigned*)(lds + (bufoff) + ldsw + _i * 8192), 16, 0, 0); } while (0)
; #define PG8_LDA(dst, b, h) do { _Pragma("unroll") for (int m = 0; m < 4; ++m) _Pragma("unroll") for (int k = 0; k < 2; ++k) dst[m][k] = *(const LAS bf16x8*)(lds + PG8_SA(b, h) + aoff + m * 2048 + k * 1024); } while (0)
; #define PG8_LDB(dst, b, h) do { _Pragma("unroll") for (int n = 0; n < 2; ++n) _Pragma("unroll") for (int k = 0; k < 2; ++k) dst[n][k] = *(const LAS bf16x8*)(lds + PG8_SB(b, h) + boff + n * 2048 + k * 1024); } while (0)
; #define PG8_MMA(ai, bj, At, Bt) do { __builtin_amdgcn_s_setprio(1); _Pragma("unroll") for (int m = 0; m < 4; ++m) _Pragma("unroll") for (int n = 0; n < 2; ++n) _Pragma("unroll") for (int k = 0; k < 2; ++k) \
;         acc[ai][bj][m][n] = __builtin_amdgcn_mfma_f32_16x16x32_bf16(Bt[n][k], At[m][k], acc[ai][bj][m][n], 0, 0, 0); __builtin_amdgcn_s_setprio(0); } while (0)
; #define PG8_WAIT_V(n) asm volatile("s_waitcnt vmcnt(" #n ")" ::: "memory")
; #define PG8_WAIT_L(n) asm volatile("s_waitcnt lgkmcnt(" #n ")" ::: "memory")
; #define PG8_BAR __builtin_amdgcn_s_barrier()
; #define PG8_SCHED __builtin_amdgcn_sched_barrier(0)
; template <class Epi>
; __device__ __forceinline__ void gemm_phase(LAS unsigned char* lds, const Gemm g, const StaticOrder S, const Epi E) {
;     ...
;             const char* a1 = cA + (long)(t + 1) * ksc;
;             const char* a2 = last ? nA : cA + (long)(t + 2) * ksc; const char* b2 = last ? nB : cB + (long)(t + 2) * ksc;
;             const long ks3 = last ? ksn : ksc;
;             const char* a3 = a2 + ks3; const char* b3 = b2 + ks3;
;             PG8_LDB(B0, 0, 0); PG8_LDB(B1, 0, 1); PG8_SCHED; PG8_LDA(At, 0, 0); PG8_STAGE(PG8_SA(1, 1), a1 + hstepA, voffA);
;             PG8_WAIT_V(8); PG8_WAIT_L(0); PG8_BAR; PG8_MMA(0, 0, At, B0); PG8_MMA(0, 1, At, B1); PG8_BAR; PG8_SCHED;
;             PG8_LDA(At, 0, 1); PG8_STAGE(PG8_SB(0, 0), b2, voffB); PG8_STAGE(PG8_SB(0, 1), b2 + hstepB, voffB); PG8_STAGE(PG8_SA(0, 0), a2, voffA);
;             PG8_WAIT_V(8); PG8_WAIT_L(0); PG8_BAR; PG8_MMA(1, 0, At, B0); PG8_MMA(1, 1, At, B1); PG8_BAR; PG8_SCHED;
.LBB0_566:
	v_add_u32_e32 v152, s67, v164
	v_add_u32_e32 v176, s68, v164
	ds_read_b128 v[128:131], v152
	ds_read_b128 v[132:135], v152 offset:1024
	ds_read_b128 v[136:139], v152 offset:2048
	ds_read_b128 v[152:155], v152 offset:3072
	ds_read_b128 v[156:159], v176
	ds_read_b128 v[168:171], v176 offset:1024
	ds_read_b128 v[172:175], v176 offset:2048
	ds_read_b128 v[176:179], v176 offset:3072
	s_or_b32 s21, s29, 1
	s_mul_i32 s58, s45, s21
	s_mul_hi_u32 s59, s44, s21
	s_add_i32 s59, s59, s58
	s_mul_i32 s21, s44, s21
	s_add_u32 s21, s42, s21
	s_addc_u32 s75, s43, s59
	s_add_u32 s58, s56, s54
	s_addc_u32 s59, s57, s55
	s_add_u32 s74, s21, 0x80000
	s_addc_u32 s75, s75, 0
	s_add_i32 m0, s31, 0xc000
	ds_read_b128 v[180:183], v166
	ds_read_b128 v[184:187], v166 offset:1024
	ds_read_b128 v[188:191], v166 offset:2048
	ds_read_b128 v[192:195], v166 offset:3072
	ds_read_b128 v[196:199], v166 offset:4096
	ds_read_b128 v[200:203], v166 offset:5120
	ds_read_b128 v[204:207], v166 offset:6144
	ds_read_b128 v[208:211], v166 offset:7168
	global_load_lds_dwordx4 v140, s[74:75]
	s_add_i32 m0, s31, 0xe000
	s_nop 0
	global_load_lds_dwordx4 v144, s[74:75]
	s_waitcnt vmcnt(8)
	s_waitcnt lgkmcnt(0)
	s_barrier
	s_setprio 1
	s_waitcnt lgkmcnt(0)
	v_mfma_f32_16x16x32_bf16 v[124:127], v[128:131], v[180:183], v[124:127]
	v_mfma_f32_16x16x32_bf16 v[120:123], v[136:139], v[180:183], v[120:123]
	v_mfma_f32_16x16x32_bf16 v[108:111], v[128:131], v[188:191], v[108:111]
	v_mfma_f32_16x16x32_bf16 v[104:107], v[136:139], v[188:191], v[104:107]
	v_mfma_f32_16x16x32_bf16 v[92:95], v[128:131], v[196:199], v[92:95]
	v_mfma_f32_16x16x32_bf16 v[88:91], v[136:139], v[196:199], v[88:91]
	v_mfma_f32_16x16x32_bf16 v[76:79], v[128:131], v[204:207], v[76:79]
	v_mfma_f32_16x16x32_bf16 v[72:75], v[136:139], v[204:207], v[72:75]
	v_mfma_f32_16x16x32_bf16 v[124:127], v[132:135], v[184:187], v[124:127]
	v_mfma_f32_16x16x32_bf16 v[120:123], v[152:155], v[184:187], v[120:123]
	v_mfma_f32_16x16x32_bf16 v[108:111], v[132:135], v[192:195], v[108:111]
	v_mfma_f32_16x16x32_bf16 v[104:107], v[152:155], v[192:195], v[104:107]
	v_mfma_f32_16x16x32_bf16 v[92:95], v[132:135], v[200:203], v[92:95]
	v_mfma_f32_16x16x32_bf16 v[88:91], v[152:155], v[200:203], v[88:91]
	v_mfma_f32_16x16x32_bf16 v[76:79], v[132:135], v[208:211], v[76:79]
	v_mfma_f32_16x16x32_bf16 v[72:75], v[152:155], v[208:211], v[72:75]
	s_setprio 0
	s_setprio 1
	v_mfma_f32_16x16x32_bf16 v[116:119], v[156:159], v[180:183], v[116:119]
	v_mfma_f32_16x16x32_bf16 v[112:115], v[172:175], v[180:183], v[112:115]
	v_mfma_f32_16x16x32_bf16 v[100:103], v[156:159], v[188:191], v[100:103]
	v_mfma_f32_16x16x32_bf16 v[96:99], v[172:175], v[188:191], v[96:99]
	v_mfma_f32_16x16x32_bf16 v[84:87], v[156:159], v[196:199], v[84:87]
	v_mfma_f32_16x16x32_bf16 v[80:83], v[172:175], v[196:199], v[80:83]
	v_mfma_f32_16x16x32_bf16 v[68:71], v[156:159], v[204:207], v[68:71]
	v_mfma_f32_16x16x32_bf16 v[64:67], v[172:175], v[204:207], v[64:67]
	v_mfma_f32_16x16x32_bf16 v[116:119], v[168:171], v[184:187], v[116:119]
	v_mfma_f32_16x16x32_bf16 v[112:115], v[176:179], v[184:187], v[112:115]
	v_mfma_f32_16x16x32_bf16 v[100:103], v[168:171], v[192:195], v[100:103]
	v_mfma_f32_16x16x32_bf16 v[96:99], v[176:179], v[192:195], v[96:99]
	v_mfma_f32_16x16x32_bf16 v[84:87], v[168:171], v[200:203], v[84:87]
	v_mfma_f32_16x16x32_bf16 v[80:83], v[176:179], v[200:203], v[80:83]
	v_mfma_f32_16x16x32_bf16 v[68:71], v[168:171], v[208:211], v[68:71]
	v_mfma_f32_16x16x32_bf16 v[64:67], v[176:179], v[208:211], v[64:67]
	s_setprio 0
	s_barrier
	s_add_i32 s21, s67, s33
	s_mov_b32 m0, s21
	ds_read_b128 v[180:183], v166 offset:16384
	ds_read_b128 v[184:187], v166 offset:17408
	ds_read_b128 v[188:191], v166 offset:18432
	ds_read_b128 v[192:195], v166 offset:19456
	ds_read_b128 v[196:199], v166 offset:20480
	ds_read_b128 v[200:203], v166 offset:21504
	ds_read_b128 v[204:207], v166 offset:22528
	ds_read_b128 v[208:211], v166 offset:23552
	global_load_lds_dwordx4 v142, s[52:53]
	s_add_i32 m0, s21, 0x2000
	s_add_u32 s74, s52, 0x80000
	s_addc_u32 s75, s53, 0
	s_add_i32 s21, s68, s33
	global_load_lds_dwordx4 v146, s[52:53]
	s_mov_b32 m0, s21
	s_nop 0
	global_load_lds_dwordx4 v142, s[74:75]
	s_add_i32 m0, s21, 0x2000
	s_nop 0
	global_load_lds_dwordx4 v146, s[74:75]
	s_mov_b32 m0, s31
	s_nop 0
	global_load_lds_dwordx4 v140, s[56:57]
	s_mov_b32 m0, s60
	s_nop 0
	global_load_lds_dwordx4 v144, s[56:57]
	s_waitcnt vmcnt(8)
	s_waitcnt lgkmcnt(0)
	s_barrier
	s_setprio 1
	s_waitcnt lgkmcnt(0)
	v_mfma_f32_16x16x32_bf16 v[60:63], v[128:131], v[180:183], v[60:63]
	v_mfma_f32_16x16x32_bf16 v[56:59], v[136:139], v[180:183], v[56:59]
	v_mfma_f32_16x16x32_bf16 v[44:47], v[128:131], v[188:191], v[44:47]
	v_mfma_f32_16x16x32_bf16 v[40:43], v[136:139], v[188:191], v[40:43]
	v_mfma_f32_16x16x32_bf16 v[28:31], v[128:131], v[196:199], v[28:31]
	v_mfma_f32_16x16x32_bf16 v[24:27], v[136:139], v[196:199], v[24:27]
	v_mfma_f32_16x16x32_bf16 v[12:15], v[128:131], v[204:207], v[12:15]
	v_mfma_f32_16x16x32_bf16 v[8:11], v[136:139], v[204:207], v[8:11]
	v_mfma_f32_16x16x32_bf16 v[60:63], v[132:135], v[184:187], v[60:63]
	v_mfma_f32_16x16x32_bf16 v[56:59], v[152:155], v[184:187], v[56:59]
	v_mfma_f32_16x16x32_bf16 v[44:47], v[132:135], v[192:195], v[44:47]
	v_mfma_f32_16x16x32_bf16 v[40:43], v[152:155], v[192:195], v[40:43]
	v_mfma_f32_16x16x32_bf16 v[28:31], v[132:135], v[200:203], v[28:31]
	v_mfma_f32_16x16x32_bf16 v[24:27], v[152:155], v[200:203], v[24:27]
	v_mfma_f32_16x16x32_bf16 v[12:15], v[132:135], v[208:211], v[12:15]
	v_mfma_f32_16x16x32_bf16 v[8:11], v[152:155], v[208:211], v[8:11]
	s_setprio 0
	s_setprio 1
	v_mfma_f32_16x16x32_bf16 v[52:55], v[156:159], v[180:183], v[52:55]
	v_mfma_f32_16x16x32_bf16 v[48:51], v[172:175], v[180:183], v[48:51]
	v_mfma_f32_16x16x32_bf16 v[36:39], v[156:159], v[188:191], v[36:39]
	v_mfma_f32_16x16x32_bf16 v[32:35], v[172:175], v[188:191], v[32:35]
	v_mfma_f32_16x16x32_bf16 v[20:23], v[156:159], v[196:199], v[20:23]
	v_mfma_f32_16x16x32_bf16 v[16:19], v[172:175], v[196:199], v[16:19]
	v_mfma_f32_16x16x32_bf16 v[4:7], v[156:159], v[204:207], v[4:7]
	v_mfma_f32_16x16x32_bf16 v[0:3], v[172:175], v[204:207], v[0:3]
	v_mfma_f32_16x16x32_bf16 v[52:55], v[168:171], v[184:187], v[52:55]
	v_mfma_f32_16x16x32_bf16 v[48:51], v[176:179], v[184:187], v[48:51]
	v_mfma_f32_16x16x32_bf16 v[36:39], v[168:171], v[192:195], v[36:39]
	v_mfma_f32_16x16x32_bf16 v[32:35], v[176:179], v[192:195], v[32:35]
	v_mfma_f32_16x16x32_bf16 v[20:23], v[168:171], v[200:203], v[20:23]
	v_mfma_f32_16x16x32_bf16 v[16:19], v[176:179], v[200:203], v[16:19]
	v_mfma_f32_16x16x32_bf16 v[4:7], v[168:171], v[208:211], v[4:7]
	v_mfma_f32_16x16x32_bf16 v[0:3], v[176:179], v[208:211], v[0:3]
	s_setprio 0
	s_barrier
; #define PG8_STAGE(bufoff, gbase, voff) do { _Pragma("unroll") for (int _i = 0; _i < 2; ++_i) \
;         __builtin_amdgcn_global_load_lds((const unsigned*)((const char*)(gbase) + (voff)[_i]), (LAS unsigned*)(lds + (bufoff) + ldsw + _i * 8192), 16, 0, 0); } while (0)
; #define PG8_LDA(dst, b, h) do { _Pragma("unroll") for (int m = 0; m < 4; ++m) _Pragma("unroll") for (int k = 0; k < 2; ++k) dst[m][k] = *(const LAS bf16x8*)(lds + PG8_SA(b, h) + aoff + m * 2048 + k * 1024); } while (0)
; #define PG8_LDB(dst, b, h) do { _Pragma("unroll") for (int n = 0; n < 2; ++n) _Pragma("unroll") for (int k = 0; k < 2; ++k) dst[n][k] = *(const LAS bf16x8*)(lds + PG8_SB(b, h) + boff + n * 2048 + k * 1024); } while (0)
; #define PG8_MMA(ai, bj, At, Bt) do { __builtin_amdgcn_s_setprio(1); _Pragma("unroll") for (int m = 0; m < 4; ++m) _Pragma("unroll") for (int n = 0; n < 2; ++n) _Pragma("unroll") for (int k = 0; k < 2; ++k) \
;         acc[ai][bj][m][n] = __builtin_amdgcn_mfma_f32_16x16x32_bf16(Bt[n][k], At[m][k], acc[ai][bj][m][n], 0, 0, 0); __builtin_amdgcn_s_setprio(0); } while (0)
; #define PG8_WAIT_V(n) asm volatile("s_waitcnt vmcnt(" #n ")" ::: "memory")
; #define PG8_WAIT_L(n) asm volatile("s_waitcnt lgkmcnt(" #n ")" ::: "memory")
; #define PG8_BAR __builtin_amdgcn_s_barrier()
; #define PG8_SCHED __builtin_amdgcn_sched_barrier(0)
; template <class Epi>
; __device__ __forceinline__ void gemm_phase(LAS unsigned char* lds, const Gemm g, const StaticOrder S, const Epi E) {
;     ...
;             PG8_LDB(B0, 1, 0); PG8_LDB(B1, 1, 1); PG8_SCHED; PG8_LDA(At, 1, 0); PG8_STAGE(PG8_SA(0, 1), a2 + hstepA, voffA);
;             PG8_WAIT_V(8); PG8_WAIT_L(0); PG8_BAR; PG8_MMA(0, 0, At, B0); PG8_MMA(0, 1, At, B1); PG8_BAR; PG8_SCHED;
;             PG8_LDA(At, 1, 1); PG8_STAGE(PG8_SB(1, 0), b3, voffB); PG8_STAGE(PG8_SB(1, 1), b3 + hstepB, voffB); PG8_STAGE(PG8_SA(1, 0), a3, voffA);
;             PG8_WAIT_V(8); PG8_WAIT_L(0); PG8_BAR; PG8_MMA(1, 0, At, B0); PG8_MMA(1, 1, At, B1); PG8_BAR; PG8_SCHED;
	s_add_i32 s21, 0, 0x18000
	s_add_i32 s74, 0, 0x1c000
	v_add_u32_e32 v152, s21, v164
	v_add_u32_e32 v176, s74, v164
	ds_read_b128 v[128:131], v152
	ds_read_b128 v[132:135], v152 offset:1024
	ds_read_b128 v[136:139], v152 offset:2048
	ds_read_b128 v[152:155], v152 offset:3072
	ds_read_b128 v[156:159], v176
	ds_read_b128 v[168:171], v176 offset:1024
	ds_read_b128 v[172:175], v176 offset:2048
	ds_read_b128 v[176:179], v176 offset:3072
	s_add_u32 s56, s56, 0x80000
	s_addc_u32 s57, s57, 0
	s_mov_b32 m0, s61
	ds_read_b128 v[180:183], v166 offset:32768
	ds_read_b128 v[184:187], v166 offset:33792
	ds_read_b128 v[188:191], v166 offset:34816
	ds_read_b128 v[192:195], v166 offset:35840
	ds_read_b128 v[196:199], v166 offset:36864
	ds_read_b128 v[200:203], v166 offset:37888
	ds_read_b128 v[204:207], v166 offset:38912
	ds_read_b128 v[208:211], v166 offset:39936
	global_load_lds_dwordx4 v140, s[56:57]
	s_mov_b32 m0, s62
	s_nop 0
	global_load_lds_dwordx4 v144, s[56:57]
	s_waitcnt vmcnt(8)
	s_waitcnt lgkmcnt(0)
	s_barrier
	s_setprio 1
	s_waitcnt lgkmcnt(0)
	v_mfma_f32_16x16x32_bf16 v[124:127], v[128:131], v[180:183], v[124:127]
	v_mfma_f32_16x16x32_bf16 v[120:123], v[136:139], v[180:183], v[120:123]
	v_mfma_f32_16x16x32_bf16 v[108:111], v[128:131], v[188:191], v[108:111]
	v_mfma_f32_16x16x32_bf16 v[104:107], v[136:139], v[188:191], v[104:107]
	v_mfma_f32_16x16x32_bf16 v[92:95], v[128:131], v[196:199], v[92:95]
	v_mfma_f32_16x16x32_bf16 v[88:91], v[136:139], v[196:199], v[88:91]
	v_mfma_f32_16x16x32_bf16 v[76:79], v[128:131], v[204:207], v[76:79]
	v_mfma_f32_16x16x32_bf16 v[72:75], v[136:139], v[204:207], v[72:75]
	v_mfma_f32_16x16x32_bf16 v[124:127], v[132:135], v[184:187], v[124:127]
	v_mfma_f32_16x16x32_bf16 v[120:123], v[152:155], v[184:187], v[120:123]
	v_mfma_f32_16x16x32_bf16 v[108:111], v[132:135], v[192:195], v[108:111]
	v_mfma_f32_16x16x32_bf16 v[104:107], v[152:155], v[192:195], v[104:107]
	v_mfma_f32_16x16x32_bf16 v[92:95], v[132:135], v[200:203], v[92:95]
	v_mfma_f32_16x16x32_bf16 v[88:91], v[152:155], v[200:203], v[88:91]
	v_mfma_f32_16x16x32_bf16 v[76:79], v[132:135], v[208:211], v[76:79]
	v_mfma_f32_16x16x32_bf16 v[72:75], v[152:155], v[208:211], v[72:75]
	s_setprio 0
	s_setprio 1
	v_mfma_f32_16x16x32_bf16 v[116:119], v[156:159], v[180:183], v[116:119]
	v_mfma_f32_16x16x32_bf16 v[112:115], v[172:175], v[180:183], v[112:115]
	v_mfma_f32_16x16x32_bf16 v[100:103], v[156:159], v[188:191], v[100:103]
	v_mfma_f32_16x16x32_bf16 v[96:99], v[172:175], v[188:191], v[96:99]
	v_mfma_f32_16x16x32_bf16 v[84:87], v[156:159], v[196:199], v[84:87]
	v_mfma_f32_16x16x32_bf16 v[80:83], v[172:175], v[196:199], v[80:83]
	v_mfma_f32_16x16x32_bf16 v[68:71], v[156:159], v[204:207], v[68:71]
	v_mfma_f32_16x16x32_bf16 v[64:67], v[172:175], v[204:207], v[64:67]
	v_mfma_f32_16x16x32_bf16 v[116:119], v[168:171], v[184:187], v[116:119]
	v_mfma_f32_16x16x32_bf16 v[112:115], v[176:179], v[184:187], v[112:115]
	v_mfma_f32_16x16x32_bf16 v[100:103], v[168:171], v[192:195], v[100:103]
	v_mfma_f32_16x16x32_bf16 v[96:99], v[176:179], v[192:195], v[96:99]
	v_mfma_f32_16x16x32_bf16 v[84:87], v[168:171], v[200:203], v[84:87]
	v_mfma_f32_16x16x32_bf16 v[80:83], v[176:179], v[200:203], v[80:83]
	v_mfma_f32_16x16x32_bf16 v[68:71], v[168:171], v[208:211], v[68:71]
	v_mfma_f32_16x16x32_bf16 v[64:67], v[176:179], v[208:211], v[64:67]
	s_setprio 0
	s_barrier
	s_add_u32 s52, s52, s54
	s_addc_u32 s53, s53, s55
	s_add_i32 s21, s21, s33
	s_mov_b32 m0, s21
	ds_read_b128 v[180:183], v166 offset:49152
	ds_read_b128 v[184:187], v166 offset:50176
	ds_read_b128 v[188:191], v166 offset:51200
	ds_read_b128 v[192:195], v166 offset:52224
	ds_read_b128 v[196:199], v166 offset:53248
	ds_read_b128 v[200:203], v166 offset:54272
	ds_read_b128 v[204:207], v166 offset:55296
	ds_read_b128 v[208:211], v166 offset:56320
	global_load_lds_dwordx4 v142, s[52:53]
	s_add_i32 m0, s21, 0x2000
	s_nop 0
	global_load_lds_dwordx4 v146, s[52:53]
	s_add_u32 s52, s52, 0x80000
	s_addc_u32 s53, s53, 0
	s_add_i32 s21, s74, s33
	s_mov_b32 m0, s21
	s_nop 0
	global_load_lds_dwordx4 v142, s[52:53]
	s_add_i32 m0, s21, 0x2000
	s_nop 0
	global_load_lds_dwordx4 v146, s[52:53]
	s_mov_b32 m0, s64
	s_nop 0
	global_load_lds_dwordx4 v140, s[58:59]
	s_mov_b32 m0, s65
	s_nop 0
	global_load_lds_dwordx4 v144, s[58:59]
	s_waitcnt vmcnt(8)
	s_waitcnt lgkmcnt(0)
	s_barrier
	s_setprio 1
	s_waitcnt lgkmcnt(0)
	v_mfma_f32_16x16x32_bf16 v[60:63], v[128:131], v[180:183], v[60:63]
	v_mfma_f32_16x16x32_bf16 v[56:59], v[136:139], v[180:183], v[56:59]
	v_mfma_f32_16x16x32_bf16 v[44:47], v[128:131], v[188:191], v[44:47]
	v_mfma_f32_16x16x32_bf16 v[40:43], v[136:139], v[188:191], v[40:43]
	v_mfma_f32_16x16x32_bf16 v[28:31], v[128:131], v[196:199], v[28:31]
	v_mfma_f32_16x16x32_bf16 v[24:27], v[136:139], v[196:199], v[24:27]
	v_mfma_f32_16x16x32_bf16 v[12:15], v[128:131], v[204:207], v[12:15]
	v_mfma_f32_16x16x32_bf16 v[8:11], v[136:139], v[204:207], v[8:11]
	v_mfma_f32_16x16x32_bf16 v[60:63], v[132:135], v[184:187], v[60:63]
	v_mfma_f32_16x16x32_bf16 v[56:59], v[152:155], v[184:187], v[56:59]
	v_mfma_f32_16x16x32_bf16 v[44:47], v[132:135], v[192:195], v[44:47]
	v_mfma_f32_16x16x32_bf16 v[40:43], v[152:155], v[192:195], v[40:43]
	v_mfma_f32_16x16x32_bf16 v[28:31], v[132:135], v[200:203], v[28:31]
	v_mfma_f32_16x16x32_bf16 v[24:27], v[152:155], v[200:203], v[24:27]
	v_mfma_f32_16x16x32_bf16 v[12:15], v[132:135], v[208:211], v[12:15]
	v_mfma_f32_16x16x32_bf16 v[8:11], v[152:155], v[208:211], v[8:11]
	s_setprio 0
	s_setprio 1
	v_mfma_f32_16x16x32_bf16 v[52:55], v[156:159], v[180:183], v[52:55]
	v_mfma_f32_16x16x32_bf16 v[48:51], v[172:175], v[180:183], v[48:51]
	v_mfma_f32_16x16x32_bf16 v[36:39], v[156:159], v[188:191], v[36:39]
	v_mfma_f32_16x16x32_bf16 v[32:35], v[172:175], v[188:191], v[32:35]
	v_mfma_f32_16x16x32_bf16 v[20:23], v[156:159], v[196:199], v[20:23]
	v_mfma_f32_16x16x32_bf16 v[16:19], v[172:175], v[196:199], v[16:19]
	v_mfma_f32_16x16x32_bf16 v[4:7], v[156:159], v[204:207], v[4:7]
	v_mfma_f32_16x16x32_bf16 v[0:3], v[172:175], v[204:207], v[0:3]
	v_mfma_f32_16x16x32_bf16 v[52:55], v[168:171], v[184:187], v[52:55]
	v_mfma_f32_16x16x32_bf16 v[48:51], v[176:179], v[184:187], v[48:51]
	v_mfma_f32_16x16x32_bf16 v[36:39], v[168:171], v[192:195], v[36:39]
	v_mfma_f32_16x16x32_bf16 v[32:35], v[176:179], v[192:195], v[32:35]
	v_mfma_f32_16x16x32_bf16 v[20:23], v[168:171], v[200:203], v[20:23]
	v_mfma_f32_16x16x32_bf16 v[16:19], v[176:179], v[200:203], v[16:19]
	v_mfma_f32_16x16x32_bf16 v[4:7], v[168:171], v[208:211], v[4:7]
	v_mfma_f32_16x16x32_bf16 v[0:3], v[176:179], v[208:211], v[0:3]
	s_setprio 0
	s_barrier
	s_cmp_gt_u32 s29, 29
	s_mov_b32 s29, s19
	s_cbranch_scc1 .LBB0_571

; #define PG8_STAGE(bufoff, gbase, voff) do { _Pragma("unroll") for (int _i = 0; _i < 2; ++_i) \
;         __builtin_amdgcn_global_load_lds((const unsigned*)((const char*)(gbase) + (voff)[_i]), (LAS unsigned*)(lds + (bufoff) + ldsw + _i * 8192), 16, 0, 0); } while (0)
; #define PG8_WAIT_V(n) asm volatile("s_waitcnt vmcnt(" #n ")" ::: "memory")
; #define PG8_BAR __builtin_amdgcn_s_barrier()
; template <class Epi>
; __device__ __forceinline__ void gemm_phase(LAS unsigned char* lds, const Gemm g, const StaticOrder S, const Epi E) {
;     ...
;     const int aoff = lds_byte(wr * 64 + fr, fq * 8), boff = lds_byte(wc * 32 + fr, fq * 8);
;     ...
;     PG8_STAGE(PG8_SB(0, 0), cB, voffB); PG8_STAGE(PG8_SB(0, 1), cB + hstepB, voffB); PG8_STAGE(PG8_SA(0, 0), cA, voffA); PG8_STAGE(PG8_SA(0, 1), cA + hstepA, voffA);
;     if (wr == 1) PG8_BAR;
;     PG8_WAIT_V(2); PG8_BAR;
;     PG8_STAGE(PG8_SB(1, 0), cB + ksc, voffB); PG8_STAGE(PG8_SA(1, 0), cA + ksc, voffA); PG8_STAGE(PG8_SB(1, 1), cB + hstepB + ksc, voffB);
;     PG8_WAIT_V(6); PG8_BAR;
.LBB0_660:
	s_add_u32 s6, s82, 0x2a9a0000
	s_addc_u32 s7, s83, 0
	s_lshl_b32 s9, s9, 5
	s_mov_b64 s[26:27], 0x80
	s_and_b32 s14, s9, 0x60
	s_add_i32 m0, s21, 0x18000
	v_lshl_add_u64 v[6:7], v[6:7], 0, s[26:27]
	s_lshl_b32 s10, s8, 13
	s_lshl_b32 s9, s14, 7
	s_waitcnt vmcnt(2)
	s_barrier
	global_load_lds_dwordx4 v[6:7], off
	v_lshl_add_u64 v[4:5], v[4:5], 0, s[26:27]
	s_add_i32 m0, s21, 0x1a000
	s_add_i32 s57, s21, 0x8000
	s_add_i32 s58, s21, 0xa000
	global_load_lds_dwordx4 v[4:5], off
	v_lshl_add_u64 v[0:1], v[0:1], 0, s[26:27]
	s_mov_b32 m0, s57
	s_add_u32 s12, s22, 0x80080
	global_load_lds_dwordx4 v[0:1], off
	v_lshl_add_u64 v[0:1], v[2:3], 0, s[26:27]
	s_mov_b32 m0, s58
	s_addc_u32 s13, s23, 0
	global_load_lds_dwordx4 v[0:1], off
	s_add_i32 m0, s21, 0x1c000
	s_nop 0
	global_load_lds_dwordx4 v132, s[12:13]
	s_add_i32 m0, s21, 0x1e000
	v_lshlrev_b32_e32 v2, 2, v224
	global_load_lds_dwordx4 v128, s[12:13]
	v_and_b32_e32 v0, 15, v224
	v_lshlrev_b32_e32 v1, 1, v8
	s_sext_i32_i16 s65, s0
	v_lshl_or_b32 v142, s8, 6, v0
	v_lshl_or_b32 v0, v0, 6, v1
	v_and_b32_e32 v2, 32, v2
	v_lshlrev_b32_e32 v3, 6, v224
	s_movk_i32 s0, 0x3c0
	s_waitcnt vmcnt(6)
	s_ashr_i32 s59, s78, 31
	v_bitop3_b32 v0, v0, s10, v2 bitop3:0xde
	v_and_or_b32 v1, v3, s0, v1
	s_cmpk_lt_u32 s1, 0x100
	v_bitop3_b32 v143, s9, v1, v2 bitop3:0xf6
	v_add_u32_e32 v254, 0x10000, v143
	s_cselect_b64 s[8:9], -1, 0
	v_or_b32_e32 v144, s14, v8
	v_mov_b64_e32 v[136:137], 0xb00
	v_mov_b64_e32 v[138:139], 0xaff
	s_movk_i32 s60, 0xff80
	s_add_i32 s61, 0, 0x10000
	s_add_i32 s62, 0, 0x14000
	v_add_u32_e32 v145, 0, v0
	s_movk_i32 s63, 0x2c00
	v_mov_b32_e32 v146, 0x358637bd
	s_barrier
	s_branch .LBB0_663

; #define PG8_STAGE(bufoff, gbase, voff) do { _Pragma("unroll") for (int _i = 0; _i < 2; ++_i) \
;         __builtin_amdgcn_global_load_lds((const unsigned*)((const char*)(gbase) + (voff)[_i]), (LAS unsigned*)(lds + (bufoff) + ldsw + _i * 8192), 16, 0, 0); } while (0)
; #define PG8_LDA(dst, b, h) do { _Pragma("unroll") for (int m = 0; m < 4; ++m) _Pragma("unroll") for (int k = 0; k < 2; ++k) dst[m][k] = *(const LAS bf16x8*)(lds + PG8_SA(b, h) + aoff + m * 2048 + k * 1024); } while (0)
; #define PG8_LDB(dst, b, h) do { _Pragma("unroll") for (int n = 0; n < 2; ++n) _Pragma("unroll") for (int k = 0; k < 2; ++k) dst[n][k] = *(const LAS bf16x8*)(lds + PG8_SB(b, h) + boff + n * 2048 + k * 1024); } while (0)
; #define PG8_MMA(ai, bj, At, Bt) do { __builtin_amdgcn_s_setprio(1); _Pragma("unroll") for (int m = 0; m < 4; ++m) _Pragma("unroll") for (int n = 0; n < 2; ++n) _Pragma("unroll") for (int k = 0; k < 2; ++k) \
;         acc[ai][bj][m][n] = __builtin_amdgcn_mfma_f32_16x16x32_bf16(Bt[n][k], At[m][k], acc[ai][bj][m][n], 0, 0, 0); __builtin_amdgcn_s_setprio(0); } while (0)
; #define PG8_WAIT_V(n) asm volatile("s_waitcnt vmcnt(" #n ")" ::: "memory")
; #define PG8_WAIT_L(n) asm volatile("s_waitcnt lgkmcnt(" #n ")" ::: "memory")
; #define PG8_BAR __builtin_amdgcn_s_barrier()
; #define PG8_SCHED __builtin_amdgcn_sched_barrier(0)
; template <class Epi>
; __device__ __forceinline__ void gemm_phase(LAS unsigned char* lds, const Gemm g, const StaticOrder S, const Epi E) {
;     ...
;             const char* a1 = cA + (long)(t + 1) * ksc;
;             const char* a2 = last ? nA : cA + (long)(t + 2) * ksc; const char* b2 = last ? nB : cB + (long)(t + 2) * ksc;
;             const long ks3 = last ? ksn : ksc;
;             const char* a3 = a2 + ks3; const char* b3 = b2 + ks3;
;             PG8_LDB(B0, 0, 0); PG8_LDB(B1, 0, 1); PG8_SCHED; PG8_LDA(At, 0, 0); PG8_STAGE(PG8_SA(1, 1), a1 + hstepA, voffA);
;             PG8_WAIT_V(8); PG8_WAIT_L(0); PG8_BAR; PG8_MMA(0, 0, At, B0); PG8_MMA(0, 1, At, B1); PG8_BAR; PG8_SCHED;
;             PG8_LDA(At, 0, 1); PG8_STAGE(PG8_SB(0, 0), b2, voffB); PG8_STAGE(PG8_SB(0, 1), b2 + hstepB, voffB); PG8_STAGE(PG8_SA(0, 0), a2, voffA);
;             PG8_WAIT_V(8); PG8_WAIT_L(0); PG8_BAR; PG8_MMA(1, 0, At, B0); PG8_MMA(1, 1, At, B1); PG8_BAR; PG8_SCHED;
.LBB0_666:
	ds_read_b128 v[148:151], v254
	ds_read_b128 v[152:155], v254 offset:1024
	ds_read_b128 v[156:159], v254 offset:2048
	ds_read_b128 v[160:163], v254 offset:3072
	ds_read_b128 v[164:167], v254 offset:16384
	ds_read_b128 v[168:171], v254 offset:17408
	ds_read_b128 v[172:175], v254 offset:18432
	ds_read_b128 v[176:179], v254 offset:19456
	s_or_b32 s13, s66, 1
	s_mul_i32 s48, s27, s13
	s_mul_hi_u32 s49, s26, s13
	s_add_i32 s49, s49, s48
	s_mul_i32 s13, s26, s13
	s_add_u32 s13, s24, s13
	s_addc_u32 s67, s25, s49
	s_add_u32 s48, s46, s44
	s_addc_u32 s49, s47, s45
	s_add_u32 s68, s13, 0x80000
	s_addc_u32 s69, s67, 0
	s_add_i32 m0, s21, 0xc000
	ds_read_b128 v[180:183], v145
	ds_read_b128 v[184:187], v145 offset:1024
	ds_read_b128 v[188:191], v145 offset:2048
	ds_read_b128 v[192:195], v145 offset:3072
	ds_read_b128 v[196:199], v145 offset:4096
	ds_read_b128 v[200:203], v145 offset:5120
	ds_read_b128 v[204:207], v145 offset:6144
	ds_read_b128 v[208:211], v145 offset:7168
	global_load_lds_dwordx4 v134, s[68:69]
	s_add_i32 m0, s21, 0xe000
	s_nop 0
	global_load_lds_dwordx4 v130, s[68:69]
	s_waitcnt vmcnt(8)
	s_waitcnt lgkmcnt(0)
	s_barrier
	s_setprio 1
	s_waitcnt lgkmcnt(0)
	v_mfma_f32_16x16x32_bf16 v[116:119], v[148:151], v[180:183], v[116:119]
	v_mfma_f32_16x16x32_bf16 v[112:115], v[156:159], v[180:183], v[112:115]
	v_mfma_f32_16x16x32_bf16 v[108:111], v[148:151], v[188:191], v[108:111]
	v_mfma_f32_16x16x32_bf16 v[104:107], v[156:159], v[188:191], v[104:107]
	v_mfma_f32_16x16x32_bf16 v[92:95], v[148:151], v[196:199], v[92:95]
	v_mfma_f32_16x16x32_bf16 v[88:91], v[156:159], v[196:199], v[88:91]
	v_mfma_f32_16x16x32_bf16 v[76:79], v[148:151], v[204:207], v[76:79]
	v_mfma_f32_16x16x32_bf16 v[72:75], v[156:159], v[204:207], v[72:75]
	v_mfma_f32_16x16x32_bf16 v[116:119], v[152:155], v[184:187], v[116:119]
	v_mfma_f32_16x16x32_bf16 v[112:115], v[160:163], v[184:187], v[112:115]
	v_mfma_f32_16x16x32_bf16 v[108:111], v[152:155], v[192:195], v[108:111]
	v_mfma_f32_16x16x32_bf16 v[104:107], v[160:163], v[192:195], v[104:107]
	v_mfma_f32_16x16x32_bf16 v[92:95], v[152:155], v[200:203], v[92:95]
	v_mfma_f32_16x16x32_bf16 v[88:91], v[160:163], v[200:203], v[88:91]
	v_mfma_f32_16x16x32_bf16 v[76:79], v[152:155], v[208:211], v[76:79]
	v_mfma_f32_16x16x32_bf16 v[72:75], v[160:163], v[208:211], v[72:75]
	s_setprio 0
	s_setprio 1
	v_mfma_f32_16x16x32_bf16 v[124:127], v[164:167], v[180:183], v[124:127]
	v_mfma_f32_16x16x32_bf16 v[120:123], v[172:175], v[180:183], v[120:123]
	v_mfma_f32_16x16x32_bf16 v[100:103], v[164:167], v[188:191], v[100:103]
	v_mfma_f32_16x16x32_bf16 v[96:99], v[172:175], v[188:191], v[96:99]
	v_mfma_f32_16x16x32_bf16 v[84:87], v[164:167], v[196:199], v[84:87]
	v_mfma_f32_16x16x32_bf16 v[80:83], v[172:175], v[196:199], v[80:83]
	v_mfma_f32_16x16x32_bf16 v[68:71], v[164:167], v[204:207], v[68:71]
	v_mfma_f32_16x16x32_bf16 v[64:67], v[172:175], v[204:207], v[64:67]
	v_mfma_f32_16x16x32_bf16 v[124:127], v[168:171], v[184:187], v[124:127]
	v_mfma_f32_16x16x32_bf16 v[120:123], v[176:179], v[184:187], v[120:123]
	v_mfma_f32_16x16x32_bf16 v[100:103], v[168:171], v[192:195], v[100:103]
	v_mfma_f32_16x16x32_bf16 v[96:99], v[176:179], v[192:195], v[96:99]
	v_mfma_f32_16x16x32_bf16 v[84:87], v[168:171], v[200:203], v[84:87]
	v_mfma_f32_16x16x32_bf16 v[80:83], v[176:179], v[200:203], v[80:83]
	v_mfma_f32_16x16x32_bf16 v[68:71], v[168:171], v[208:211], v[68:71]
	v_mfma_f32_16x16x32_bf16 v[64:67], v[176:179], v[208:211], v[64:67]
	s_setprio 0
	s_barrier
	s_add_i32 s13, s61, s51
	s_mov_b32 m0, s13
	ds_read_b128 v[180:183], v145 offset:16384
	ds_read_b128 v[184:187], v145 offset:17408
	ds_read_b128 v[188:191], v145 offset:18432
	ds_read_b128 v[192:195], v145 offset:19456
	ds_read_b128 v[196:199], v145 offset:20480
	ds_read_b128 v[200:203], v145 offset:21504
	ds_read_b128 v[204:207], v145 offset:22528
	ds_read_b128 v[208:211], v145 offset:23552
	global_load_lds_dwordx4 v132, s[42:43]
	s_add_i32 m0, s13, 0x2000
	s_add_u32 s68, s42, 0x80000
	s_addc_u32 s69, s43, 0
	s_add_i32 s13, s62, s51
	global_load_lds_dwordx4 v128, s[42:43]
	s_mov_b32 m0, s13
	s_nop 0
	global_load_lds_dwordx4 v132, s[68:69]
	s_add_i32 m0, s13, 0x2000
	s_nop 0
	global_load_lds_dwordx4 v128, s[68:69]
	s_mov_b32 m0, s21
	s_nop 0
	global_load_lds_dwordx4 v134, s[46:47]
	s_mov_b32 m0, s54
	s_nop 0
	global_load_lds_dwordx4 v130, s[46:47]
	s_waitcnt vmcnt(8)
	s_waitcnt lgkmcnt(0)
	s_barrier
	s_setprio 1
	s_waitcnt lgkmcnt(0)
	v_mfma_f32_16x16x32_bf16 v[60:63], v[148:151], v[180:183], v[60:63]
	v_mfma_f32_16x16x32_bf16 v[56:59], v[156:159], v[180:183], v[56:59]
	v_mfma_f32_16x16x32_bf16 v[44:47], v[148:151], v[188:191], v[44:47]
	v_mfma_f32_16x16x32_bf16 v[40:43], v[156:159], v[188:191], v[40:43]
	v_mfma_f32_16x16x32_bf16 v[28:31], v[148:151], v[196:199], v[28:31]
	v_mfma_f32_16x16x32_bf16 v[24:27], v[156:159], v[196:199], v[24:27]
	v_mfma_f32_16x16x32_bf16 v[12:15], v[148:151], v[204:207], v[12:15]
	v_mfma_f32_16x16x32_bf16 v[8:11], v[156:159], v[204:207], v[8:11]
	v_mfma_f32_16x16x32_bf16 v[60:63], v[152:155], v[184:187], v[60:63]
	v_mfma_f32_16x16x32_bf16 v[56:59], v[160:163], v[184:187], v[56:59]
	v_mfma_f32_16x16x32_bf16 v[44:47], v[152:155], v[192:195], v[44:47]
	v_mfma_f32_16x16x32_bf16 v[40:43], v[160:163], v[192:195], v[40:43]
	v_mfma_f32_16x16x32_bf16 v[28:31], v[152:155], v[200:203], v[28:31]
	v_mfma_f32_16x16x32_bf16 v[24:27], v[160:163], v[200:203], v[24:27]
	v_mfma_f32_16x16x32_bf16 v[12:15], v[152:155], v[208:211], v[12:15]
	v_mfma_f32_16x16x32_bf16 v[8:11], v[160:163], v[208:211], v[8:11]
	s_setprio 0
	s_setprio 1
	v_mfma_f32_16x16x32_bf16 v[52:55], v[164:167], v[180:183], v[52:55]
	v_mfma_f32_16x16x32_bf16 v[48:51], v[172:175], v[180:183], v[48:51]
	v_mfma_f32_16x16x32_bf16 v[36:39], v[164:167], v[188:191], v[36:39]
	v_mfma_f32_16x16x32_bf16 v[32:35], v[172:175], v[188:191], v[32:35]
	v_mfma_f32_16x16x32_bf16 v[20:23], v[164:167], v[196:199], v[20:23]
	v_mfma_f32_16x16x32_bf16 v[16:19], v[172:175], v[196:199], v[16:19]
	v_mfma_f32_16x16x32_bf16 v[4:7], v[164:167], v[204:207], v[4:7]
	v_mfma_f32_16x16x32_bf16 v[0:3], v[172:175], v[204:207], v[0:3]
	v_mfma_f32_16x16x32_bf16 v[52:55], v[168:171], v[184:187], v[52:55]
	v_mfma_f32_16x16x32_bf16 v[48:51], v[176:179], v[184:187], v[48:51]
	v_mfma_f32_16x16x32_bf16 v[36:39], v[168:171], v[192:195], v[36:39]
	v_mfma_f32_16x16x32_bf16 v[32:35], v[176:179], v[192:195], v[32:35]
	v_mfma_f32_16x16x32_bf16 v[20:23], v[168:171], v[200:203], v[20:23]
	v_mfma_f32_16x16x32_bf16 v[16:19], v[176:179], v[200:203], v[16:19]
	v_mfma_f32_16x16x32_bf16 v[4:7], v[168:171], v[208:211], v[4:7]
	v_mfma_f32_16x16x32_bf16 v[0:3], v[176:179], v[208:211], v[0:3]
	s_setprio 0
	s_barrier
; #define PG8_STAGE(bufoff, gbase, voff) do { _Pragma("unroll") for (int _i = 0; _i < 2; ++_i) \
;         __builtin_amdgcn_global_load_lds((const unsigned*)((const char*)(gbase) + (voff)[_i]), (LAS unsigned*)(lds + (bufoff) + ldsw + _i * 8192), 16, 0, 0); } while (0)
; #define PG8_LDA(dst, b, h) do { _Pragma("unroll") for (int m = 0; m < 4; ++m) _Pragma("unroll") for (int k = 0; k < 2; ++k) dst[m][k] = *(const LAS bf16x8*)(lds + PG8_SA(b, h) + aoff + m * 2048 + k * 1024); } while (0)
; #define PG8_LDB(dst, b, h) do { _Pragma("unroll") for (int n = 0; n < 2; ++n) _Pragma("unroll") for (int k = 0; k < 2; ++k) dst[n][k] = *(const LAS bf16x8*)(lds + PG8_SB(b, h) + boff + n * 2048 + k * 1024); } while (0)
; #define PG8_MMA(ai, bj, At, Bt) do { __builtin_amdgcn_s_setprio(1); _Pragma("unroll") for (int m = 0; m < 4; ++m) _Pragma("unroll") for (int n = 0; n < 2; ++n) _Pragma("unroll") for (int k = 0; k < 2; ++k) \
;         acc[ai][bj][m][n] = __builtin_amdgcn_mfma_f32_16x16x32_bf16(Bt[n][k], At[m][k], acc[ai][bj][m][n], 0, 0, 0); __builtin_amdgcn_s_setprio(0); } while (0)
; #define PG8_WAIT_V(n) asm volatile("s_waitcnt vmcnt(" #n ")" ::: "memory")
; #define PG8_WAIT_L(n) asm volatile("s_waitcnt lgkmcnt(" #n ")" ::: "memory")
; #define PG8_BAR __builtin_amdgcn_s_barrier()
; #define PG8_SCHED __builtin_amdgcn_sched_barrier(0)
; template <class Epi>
; __device__ __forceinline__ void gemm_phase(LAS unsigned char* lds, const Gemm g, const StaticOrder S, const Epi E) {
;     ...
;             PG8_LDB(B0, 1, 0); PG8_LDB(B1, 1, 1); PG8_SCHED; PG8_LDA(At, 1, 0); PG8_STAGE(PG8_SA(0, 1), a2 + hstepA, voffA);
;             PG8_WAIT_V(8); PG8_WAIT_L(0); PG8_BAR; PG8_MMA(0, 0, At, B0); PG8_MMA(0, 1, At, B1); PG8_BAR; PG8_SCHED;
;             PG8_LDA(At, 1, 1); PG8_STAGE(PG8_SB(1, 0), b3, voffB); PG8_STAGE(PG8_SB(1, 1), b3 + hstepB, voffB); PG8_STAGE(PG8_SA(1, 0), a3, voffA);
;             PG8_WAIT_V(8); PG8_WAIT_L(0); PG8_BAR; PG8_MMA(1, 0, At, B0); PG8_MMA(1, 1, At, B1); PG8_BAR; PG8_SCHED;
;         }
	s_add_i32 s13, 0, 0x18000
	s_add_i32 s67, 0, 0x1c000
	ds_read_b128 v[148:151], v254 offset:32768
	ds_read_b128 v[152:155], v254 offset:33792
	ds_read_b128 v[156:159], v254 offset:34816
	ds_read_b128 v[160:163], v254 offset:35840
	ds_read_b128 v[164:167], v254 offset:49152
	ds_read_b128 v[168:171], v254 offset:50176
	ds_read_b128 v[172:175], v254 offset:51200
	ds_read_b128 v[176:179], v254 offset:52224
	s_add_u32 s46, s46, 0x80000
	s_addc_u32 s47, s47, 0
	s_mov_b32 m0, s55
	ds_read_b128 v[180:183], v145 offset:32768
	ds_read_b128 v[184:187], v145 offset:33792
	ds_read_b128 v[188:191], v145 offset:34816
	ds_read_b128 v[192:195], v145 offset:35840
	ds_read_b128 v[196:199], v145 offset:36864
	ds_read_b128 v[200:203], v145 offset:37888
	ds_read_b128 v[204:207], v145 offset:38912
	ds_read_b128 v[208:211], v145 offset:39936
	global_load_lds_dwordx4 v134, s[46:47]
	s_mov_b32 m0, s56
	s_nop 0
	global_load_lds_dwordx4 v130, s[46:47]
	s_waitcnt vmcnt(8)
	s_waitcnt lgkmcnt(0)
	s_barrier
	s_setprio 1
	s_waitcnt lgkmcnt(0)
	v_mfma_f32_16x16x32_bf16 v[116:119], v[148:151], v[180:183], v[116:119]
	v_mfma_f32_16x16x32_bf16 v[112:115], v[156:159], v[180:183], v[112:115]
	v_mfma_f32_16x16x32_bf16 v[108:111], v[148:151], v[188:191], v[108:111]
	v_mfma_f32_16x16x32_bf16 v[104:107], v[156:159], v[188:191], v[104:107]
	v_mfma_f32_16x16x32_bf16 v[92:95], v[148:151], v[196:199], v[92:95]
	v_mfma_f32_16x16x32_bf16 v[88:91], v[156:159], v[196:199], v[88:91]
	v_mfma_f32_16x16x32_bf16 v[76:79], v[148:151], v[204:207], v[76:79]
	v_mfma_f32_16x16x32_bf16 v[72:75], v[156:159], v[204:207], v[72:75]
	v_mfma_f32_16x16x32_bf16 v[116:119], v[152:155], v[184:187], v[116:119]
	v_mfma_f32_16x16x32_bf16 v[112:115], v[160:163], v[184:187], v[112:115]
	v_mfma_f32_16x16x32_bf16 v[108:111], v[152:155], v[192:195], v[108:111]
	v_mfma_f32_16x16x32_bf16 v[104:107], v[160:163], v[192:195], v[104:107]
	v_mfma_f32_16x16x32_bf16 v[92:95], v[152:155], v[200:203], v[92:95]
	v_mfma_f32_16x16x32_bf16 v[88:91], v[160:163], v[200:203], v[88:91]
	v_mfma_f32_16x16x32_bf16 v[76:79], v[152:155], v[208:211], v[76:79]
	v_mfma_f32_16x16x32_bf16 v[72:75], v[160:163], v[208:211], v[72:75]
	s_setprio 0
	s_setprio 1
	v_mfma_f32_16x16x32_bf16 v[124:127], v[164:167], v[180:183], v[124:127]
	v_mfma_f32_16x16x32_bf16 v[120:123], v[172:175], v[180:183], v[120:123]
	v_mfma_f32_16x16x32_bf16 v[100:103], v[164:167], v[188:191], v[100:103]
	v_mfma_f32_16x16x32_bf16 v[96:99], v[172:175], v[188:191], v[96:99]
	v_mfma_f32_16x16x32_bf16 v[84:87], v[164:167], v[196:199], v[84:87]
	v_mfma_f32_16x16x32_bf16 v[80:83], v[172:175], v[196:199], v[80:83]
	v_mfma_f32_16x16x32_bf16 v[68:71], v[164:167], v[204:207], v[68:71]
	v_mfma_f32_16x16x32_bf16 v[64:67], v[172:175], v[204:207], v[64:67]
	v_mfma_f32_16x16x32_bf16 v[124:127], v[168:171], v[184:187], v[124:127]
	v_mfma_f32_16x16x32_bf16 v[120:123], v[176:179], v[184:187], v[120:123]
	v_mfma_f32_16x16x32_bf16 v[100:103], v[168:171], v[192:195], v[100:103]
	v_mfma_f32_16x16x32_bf16 v[96:99], v[176:179], v[192:195], v[96:99]
	v_mfma_f32_16x16x32_bf16 v[84:87], v[168:171], v[200:203], v[84:87]
	v_mfma_f32_16x16x32_bf16 v[80:83], v[176:179], v[200:203], v[80:83]
	v_mfma_f32_16x16x32_bf16 v[68:71], v[168:171], v[208:211], v[68:71]
	v_mfma_f32_16x16x32_bf16 v[64:67], v[176:179], v[208:211], v[64:67]
	s_setprio 0
	s_barrier
	s_add_u32 s42, s42, s44
	s_addc_u32 s43, s43, s45
	s_add_i32 s13, s13, s51
	s_mov_b32 m0, s13
	ds_read_b128 v[180:183], v145 offset:49152
	ds_read_b128 v[184:187], v145 offset:50176
	ds_read_b128 v[188:191], v145 offset:51200
	ds_read_b128 v[192:195], v145 offset:52224
	ds_read_b128 v[196:199], v145 offset:53248
	ds_read_b128 v[200:203], v145 offset:54272
	ds_read_b128 v[204:207], v145 offset:55296
	ds_read_b128 v[208:211], v145 offset:56320
	global_load_lds_dwordx4 v132, s[42:43]
	s_add_i32 m0, s13, 0x2000
	s_nop 0
	global_load_lds_dwordx4 v128, s[42:43]
	s_add_u32 s42, s42, 0x80000
	s_addc_u32 s43, s43, 0
	s_add_i32 s13, s67, s51
	s_mov_b32 m0, s13
	s_nop 0
	global_load_lds_dwordx4 v132, s[42:43]
	s_add_i32 m0, s13, 0x2000
	s_nop 0
	global_load_lds_dwordx4 v128, s[42:43]
	s_mov_b32 m0, s57
	s_nop 0
	global_load_lds_dwordx4 v134, s[48:49]
	s_mov_b32 m0, s58
	s_nop 0
	global_load_lds_dwordx4 v130, s[48:49]
	s_waitcnt vmcnt(8)
	s_waitcnt lgkmcnt(0)
	s_barrier
	s_setprio 1
	s_waitcnt lgkmcnt(0)
	v_mfma_f32_16x16x32_bf16 v[60:63], v[148:151], v[180:183], v[60:63]
	v_mfma_f32_16x16x32_bf16 v[56:59], v[156:159], v[180:183], v[56:59]
	v_mfma_f32_16x16x32_bf16 v[44:47], v[148:151], v[188:191], v[44:47]
	v_mfma_f32_16x16x32_bf16 v[40:43], v[156:159], v[188:191], v[40:43]
	v_mfma_f32_16x16x32_bf16 v[28:31], v[148:151], v[196:199], v[28:31]
	v_mfma_f32_16x16x32_bf16 v[24:27], v[156:159], v[196:199], v[24:27]
	v_mfma_f32_16x16x32_bf16 v[12:15], v[148:151], v[204:207], v[12:15]
	v_mfma_f32_16x16x32_bf16 v[8:11], v[156:159], v[204:207], v[8:11]
	v_mfma_f32_16x16x32_bf16 v[60:63], v[152:155], v[184:187], v[60:63]
	v_mfma_f32_16x16x32_bf16 v[56:59], v[160:163], v[184:187], v[56:59]
	v_mfma_f32_16x16x32_bf16 v[44:47], v[152:155], v[192:195], v[44:47]
	v_mfma_f32_16x16x32_bf16 v[40:43], v[160:163], v[192:195], v[40:43]
	v_mfma_f32_16x16x32_bf16 v[28:31], v[152:155], v[200:203], v[28:31]
	v_mfma_f32_16x16x32_bf16 v[24:27], v[160:163], v[200:203], v[24:27]
	v_mfma_f32_16x16x32_bf16 v[12:15], v[152:155], v[208:211], v[12:15]
	v_mfma_f32_16x16x32_bf16 v[8:11], v[160:163], v[208:211], v[8:11]
	s_setprio 0
	s_setprio 1
	v_mfma_f32_16x16x32_bf16 v[52:55], v[164:167], v[180:183], v[52:55]
	v_mfma_f32_16x16x32_bf16 v[48:51], v[172:175], v[180:183], v[48:51]
	v_mfma_f32_16x16x32_bf16 v[36:39], v[164:167], v[188:191], v[36:39]
	v_mfma_f32_16x16x32_bf16 v[32:35], v[172:175], v[188:191], v[32:35]
	v_mfma_f32_16x16x32_bf16 v[20:23], v[164:167], v[196:199], v[20:23]
	v_mfma_f32_16x16x32_bf16 v[16:19], v[172:175], v[196:199], v[16:19]
	v_mfma_f32_16x16x32_bf16 v[4:7], v[164:167], v[204:207], v[4:7]
	v_mfma_f32_16x16x32_bf16 v[0:3], v[172:175], v[204:207], v[0:3]
	v_mfma_f32_16x16x32_bf16 v[52:55], v[168:171], v[184:187], v[52:55]
	v_mfma_f32_16x16x32_bf16 v[48:51], v[176:179], v[184:187], v[48:51]
	v_mfma_f32_16x16x32_bf16 v[36:39], v[168:171], v[192:195], v[36:39]
	v_mfma_f32_16x16x32_bf16 v[32:35], v[176:179], v[192:195], v[32:35]
	v_mfma_f32_16x16x32_bf16 v[20:23], v[168:171], v[200:203], v[20:23]
	v_mfma_f32_16x16x32_bf16 v[16:19], v[176:179], v[200:203], v[16:19]
	v_mfma_f32_16x16x32_bf16 v[4:7], v[168:171], v[208:211], v[4:7]
	v_mfma_f32_16x16x32_bf16 v[0:3], v[176:179], v[208:211], v[0:3]
	s_setprio 0
	s_barrier
	s_cmp_gt_u32 s66, 29
	s_mov_b32 s66, s11
	s_cbranch_scc1 .LBB0_671

; #define PG8_STAGE(bufoff, gbase, voff) do { _Pragma("unroll") for (int _i = 0; _i < 2; ++_i) \
;         __builtin_amdgcn_global_load_lds((const unsigned*)((const char*)(gbase) + (voff)[_i]), (LAS unsigned*)(lds + (bufoff) + ldsw + _i * 8192), 16, 0, 0); } while (0)
; #define PG8_LDA(dst, b, h) do { _Pragma("unroll") for (int m = 0; m < 4; ++m) _Pragma("unroll") for (int k = 0; k < 2; ++k) dst[m][k] = *(const LAS bf16x8*)(lds + PG8_SA(b, h) + aoff + m * 2048 + k * 1024); } while (0)
; #define PG8_LDB(dst, b, h) do { _Pragma("unroll") for (int n = 0; n < 2; ++n) _Pragma("unroll") for (int k = 0; k < 2; ++k) dst[n][k] = *(const LAS bf16x8*)(lds + PG8_SB(b, h) + boff + n * 2048 + k * 1024); } while (0)
; #define PG8_MMA(ai, bj, At, Bt) do { __builtin_amdgcn_s_setprio(1); _Pragma("unroll") for (int m = 0; m < 4; ++m) _Pragma("unroll") for (int n = 0; n < 2; ++n) _Pragma("unroll") for (int k = 0; k < 2; ++k) \
;         acc[ai][bj][m][n] = __builtin_amdgcn_mfma_f32_16x16x32_bf16(Bt[n][k], At[m][k], acc[ai][bj][m][n], 0, 0, 0); __builtin_amdgcn_s_setprio(0); } while (0)
; #define PG8_WAIT_V(n) asm volatile("s_waitcnt vmcnt(" #n ")" ::: "memory")
; #define PG8_WAIT_L(n) asm volatile("s_waitcnt lgkmcnt(" #n ")" ::: "memory")
; #define PG8_BAR __builtin_amdgcn_s_barrier()
; #define PG8_SCHED __builtin_amdgcn_sched_barrier(0)
; template <class Epi>
; __device__ __forceinline__ void gemm_phase(LAS unsigned char* lds, const Gemm g, const StaticOrder S, const Epi E) {
;     ...
;             const char* a1 = cA + (long)(t + 1) * ksc;
;             const char* a2 = last ? nA : cA + (long)(t + 2) * ksc; const char* b2 = last ? nB : cB + (long)(t + 2) * ksc;
;             const long ks3 = last ? ksn : ksc;
;             const char* a3 = a2 + ks3; const char* b3 = b2 + ks3;
;             PG8_LDB(B0, 0, 0); PG8_LDB(B1, 0, 1); PG8_SCHED; PG8_LDA(At, 0, 0); PG8_STAGE(PG8_SA(1, 1), a1 + hstepA, voffA);
;             PG8_WAIT_V(8); PG8_WAIT_L(0); PG8_BAR; PG8_MMA(0, 0, At, B0); PG8_MMA(0, 1, At, B1); PG8_BAR; PG8_SCHED;
;             PG8_LDA(At, 0, 1); PG8_STAGE(PG8_SB(0, 0), b2, voffB); PG8_STAGE(PG8_SB(0, 1), b2 + hstepB, voffB); PG8_STAGE(PG8_SA(0, 0), a2, voffA);
;             PG8_WAIT_V(8); PG8_WAIT_L(0); PG8_BAR; PG8_MMA(1, 0, At, B0); PG8_MMA(1, 1, At, B1); PG8_BAR; PG8_SCHED;
.LBB0_753:
	v_add_u32_e32 v152, s60, v164
	v_add_u32_e32 v176, s61, v164
	ds_read_b128 v[128:131], v152
	ds_read_b128 v[132:135], v152 offset:1024
	ds_read_b128 v[136:139], v152 offset:2048
	ds_read_b128 v[152:155], v152 offset:3072
	ds_read_b128 v[156:159], v176
	ds_read_b128 v[168:171], v176 offset:1024
	ds_read_b128 v[172:175], v176 offset:2048
	ds_read_b128 v[176:179], v176 offset:3072
	s_or_b32 s48, s71, 1
	s_mul_i32 s49, s35, s48
	s_mul_hi_u32 s73, s34, s48
	s_add_i32 s73, s73, s49
	s_mul_i32 s48, s34, s48
	s_add_u32 s74, s30, s48
	s_addc_u32 s73, s31, s73
	s_add_u32 s48, s46, s44
	s_addc_u32 s49, s47, s45
	s_add_u32 s74, s74, 0x160000
	s_addc_u32 s75, s73, 0
	s_add_i32 m0, s52, 0xc000
	ds_read_b128 v[180:183], v166
	ds_read_b128 v[184:187], v166 offset:1024
	ds_read_b128 v[188:191], v166 offset:2048
	ds_read_b128 v[192:195], v166 offset:3072
	ds_read_b128 v[196:199], v166 offset:4096
	ds_read_b128 v[200:203], v166 offset:5120
	ds_read_b128 v[204:207], v166 offset:6144
	ds_read_b128 v[208:211], v166 offset:7168
	global_load_lds_dwordx4 v140, s[74:75]
	s_add_i32 m0, s52, 0xe000
	s_nop 0
	global_load_lds_dwordx4 v144, s[74:75]
	s_waitcnt vmcnt(8)
	s_waitcnt lgkmcnt(0)
	s_barrier
	s_setprio 1
	s_waitcnt lgkmcnt(0)
	v_mfma_f32_16x16x32_bf16 v[124:127], v[128:131], v[180:183], v[124:127]
	v_mfma_f32_16x16x32_bf16 v[120:123], v[136:139], v[180:183], v[120:123]
	v_mfma_f32_16x16x32_bf16 v[108:111], v[128:131], v[188:191], v[108:111]
	v_mfma_f32_16x16x32_bf16 v[104:107], v[136:139], v[188:191], v[104:107]
	v_mfma_f32_16x16x32_bf16 v[92:95], v[128:131], v[196:199], v[92:95]
	v_mfma_f32_16x16x32_bf16 v[88:91], v[136:139], v[196:199], v[88:91]
	v_mfma_f32_16x16x32_bf16 v[76:79], v[128:131], v[204:207], v[76:79]
	v_mfma_f32_16x16x32_bf16 v[72:75], v[136:139], v[204:207], v[72:75]
	v_mfma_f32_16x16x32_bf16 v[124:127], v[132:135], v[184:187], v[124:127]
	v_mfma_f32_16x16x32_bf16 v[120:123], v[152:155], v[184:187], v[120:123]
	v_mfma_f32_16x16x32_bf16 v[108:111], v[132:135], v[192:195], v[108:111]
	v_mfma_f32_16x16x32_bf16 v[104:107], v[152:155], v[192:195], v[104:107]
	v_mfma_f32_16x16x32_bf16 v[92:95], v[132:135], v[200:203], v[92:95]
	v_mfma_f32_16x16x32_bf16 v[88:91], v[152:155], v[200:203], v[88:91]
	v_mfma_f32_16x16x32_bf16 v[76:79], v[132:135], v[208:211], v[76:79]
	v_mfma_f32_16x16x32_bf16 v[72:75], v[152:155], v[208:211], v[72:75]
	s_setprio 0
	s_setprio 1
	v_mfma_f32_16x16x32_bf16 v[116:119], v[156:159], v[180:183], v[116:119]
	v_mfma_f32_16x16x32_bf16 v[112:115], v[172:175], v[180:183], v[112:115]
	v_mfma_f32_16x16x32_bf16 v[100:103], v[156:159], v[188:191], v[100:103]
	v_mfma_f32_16x16x32_bf16 v[96:99], v[172:175], v[188:191], v[96:99]
	v_mfma_f32_16x16x32_bf16 v[84:87], v[156:159], v[196:199], v[84:87]
	v_mfma_f32_16x16x32_bf16 v[80:83], v[172:175], v[196:199], v[80:83]
	v_mfma_f32_16x16x32_bf16 v[68:71], v[156:159], v[204:207], v[68:71]
	v_mfma_f32_16x16x32_bf16 v[64:67], v[172:175], v[204:207], v[64:67]
	v_mfma_f32_16x16x32_bf16 v[116:119], v[168:171], v[184:187], v[116:119]
	v_mfma_f32_16x16x32_bf16 v[112:115], v[176:179], v[184:187], v[112:115]
	v_mfma_f32_16x16x32_bf16 v[100:103], v[168:171], v[192:195], v[100:103]
	v_mfma_f32_16x16x32_bf16 v[96:99], v[176:179], v[192:195], v[96:99]
	v_mfma_f32_16x16x32_bf16 v[84:87], v[168:171], v[200:203], v[84:87]
	v_mfma_f32_16x16x32_bf16 v[80:83], v[176:179], v[200:203], v[80:83]
	v_mfma_f32_16x16x32_bf16 v[68:71], v[168:171], v[208:211], v[68:71]
	v_mfma_f32_16x16x32_bf16 v[64:67], v[176:179], v[208:211], v[64:67]
	s_setprio 0
	s_barrier
	s_add_i32 s73, s60, s51
	s_mov_b32 m0, s73
	ds_read_b128 v[180:183], v166 offset:16384
	ds_read_b128 v[184:187], v166 offset:17408
	ds_read_b128 v[188:191], v166 offset:18432
	ds_read_b128 v[192:195], v166 offset:19456
	ds_read_b128 v[196:199], v166 offset:20480
	ds_read_b128 v[200:203], v166 offset:21504
	ds_read_b128 v[204:207], v166 offset:22528
	ds_read_b128 v[208:211], v166 offset:23552
	global_load_lds_dwordx4 v142, s[42:43]
	s_add_i32 m0, s73, 0x2000
	s_add_u32 s74, s42, 0x160000
	s_addc_u32 s75, s43, 0
	s_add_i32 s73, s61, s51
	global_load_lds_dwordx4 v146, s[42:43]
	s_mov_b32 m0, s73
	s_nop 0
	global_load_lds_dwordx4 v142, s[74:75]
	s_add_i32 m0, s73, 0x2000
	s_nop 0
	global_load_lds_dwordx4 v146, s[74:75]
	s_mov_b32 m0, s52
	s_nop 0
	global_load_lds_dwordx4 v140, s[46:47]
	s_mov_b32 m0, s53
	s_nop 0
	global_load_lds_dwordx4 v144, s[46:47]
	s_waitcnt vmcnt(8)
	s_waitcnt lgkmcnt(0)
	s_barrier
	s_setprio 1
	s_waitcnt lgkmcnt(0)
	v_mfma_f32_16x16x32_bf16 v[60:63], v[128:131], v[180:183], v[60:63]
	v_mfma_f32_16x16x32_bf16 v[56:59], v[136:139], v[180:183], v[56:59]
	v_mfma_f32_16x16x32_bf16 v[44:47], v[128:131], v[188:191], v[44:47]
	v_mfma_f32_16x16x32_bf16 v[40:43], v[136:139], v[188:191], v[40:43]
	v_mfma_f32_16x16x32_bf16 v[28:31], v[128:131], v[196:199], v[28:31]
	v_mfma_f32_16x16x32_bf16 v[24:27], v[136:139], v[196:199], v[24:27]
	v_mfma_f32_16x16x32_bf16 v[12:15], v[128:131], v[204:207], v[12:15]
	v_mfma_f32_16x16x32_bf16 v[8:11], v[136:139], v[204:207], v[8:11]
	v_mfma_f32_16x16x32_bf16 v[60:63], v[132:135], v[184:187], v[60:63]
	v_mfma_f32_16x16x32_bf16 v[56:59], v[152:155], v[184:187], v[56:59]
	v_mfma_f32_16x16x32_bf16 v[44:47], v[132:135], v[192:195], v[44:47]
	v_mfma_f32_16x16x32_bf16 v[40:43], v[152:155], v[192:195], v[40:43]
	v_mfma_f32_16x16x32_bf16 v[28:31], v[132:135], v[200:203], v[28:31]
	v_mfma_f32_16x16x32_bf16 v[24:27], v[152:155], v[200:203], v[24:27]
	v_mfma_f32_16x16x32_bf16 v[12:15], v[132:135], v[208:211], v[12:15]
	v_mfma_f32_16x16x32_bf16 v[8:11], v[152:155], v[208:211], v[8:11]
	s_setprio 0
	s_setprio 1
	v_mfma_f32_16x16x32_bf16 v[52:55], v[156:159], v[180:183], v[52:55]
	v_mfma_f32_16x16x32_bf16 v[48:51], v[172:175], v[180:183], v[48:51]
	v_mfma_f32_16x16x32_bf16 v[36:39], v[156:159], v[188:191], v[36:39]
	v_mfma_f32_16x16x32_bf16 v[32:35], v[172:175], v[188:191], v[32:35]
	v_mfma_f32_16x16x32_bf16 v[20:23], v[156:159], v[196:199], v[20:23]
	v_mfma_f32_16x16x32_bf16 v[16:19], v[172:175], v[196:199], v[16:19]
	v_mfma_f32_16x16x32_bf16 v[4:7], v[156:159], v[204:207], v[4:7]
	v_mfma_f32_16x16x32_bf16 v[0:3], v[172:175], v[204:207], v[0:3]
	v_mfma_f32_16x16x32_bf16 v[52:55], v[168:171], v[184:187], v[52:55]
	v_mfma_f32_16x16x32_bf16 v[48:51], v[176:179], v[184:187], v[48:51]
	v_mfma_f32_16x16x32_bf16 v[36:39], v[168:171], v[192:195], v[36:39]
	v_mfma_f32_16x16x32_bf16 v[32:35], v[176:179], v[192:195], v[32:35]
	v_mfma_f32_16x16x32_bf16 v[20:23], v[168:171], v[200:203], v[20:23]
	v_mfma_f32_16x16x32_bf16 v[16:19], v[176:179], v[200:203], v[16:19]
	v_mfma_f32_16x16x32_bf16 v[4:7], v[168:171], v[208:211], v[4:7]
	v_mfma_f32_16x16x32_bf16 v[0:3], v[176:179], v[208:211], v[0:3]
	s_setprio 0
	s_barrier
; #define PG8_STAGE(bufoff, gbase, voff) do { _Pragma("unroll") for (int _i = 0; _i < 2; ++_i) \
;         __builtin_amdgcn_global_load_lds((const unsigned*)((const char*)(gbase) + (voff)[_i]), (LAS unsigned*)(lds + (bufoff) + ldsw + _i * 8192), 16, 0, 0); } while (0)
; #define PG8_LDA(dst, b, h) do { _Pragma("unroll") for (int m = 0; m < 4; ++m) _Pragma("unroll") for (int k = 0; k < 2; ++k) dst[m][k] = *(const LAS bf16x8*)(lds + PG8_SA(b, h) + aoff + m * 2048 + k * 1024); } while (0)
; #define PG8_LDB(dst, b, h) do { _Pragma("unroll") for (int n = 0; n < 2; ++n) _Pragma("unroll") for (int k = 0; k < 2; ++k) dst[n][k] = *(const LAS bf16x8*)(lds + PG8_SB(b, h) + boff + n * 2048 + k * 1024); } while (0)
; #define PG8_MMA(ai, bj, At, Bt) do { __builtin_amdgcn_s_setprio(1); _Pragma("unroll") for (int m = 0; m < 4; ++m) _Pragma("unroll") for (int n = 0; n < 2; ++n) _Pragma("unroll") for (int k = 0; k < 2; ++k) \
;         acc[ai][bj][m][n] = __builtin_amdgcn_mfma_f32_16x16x32_bf16(Bt[n][k], At[m][k], acc[ai][bj][m][n], 0, 0, 0); __builtin_amdgcn_s_setprio(0); } while (0)
; #define PG8_WAIT_V(n) asm volatile("s_waitcnt vmcnt(" #n ")" ::: "memory")
; #define PG8_WAIT_L(n) asm volatile("s_waitcnt lgkmcnt(" #n ")" ::: "memory")
; #define PG8_BAR __builtin_amdgcn_s_barrier()
; #define PG8_SCHED __builtin_amdgcn_sched_barrier(0)
; template <class Epi>
; __device__ __forceinline__ void gemm_phase(LAS unsigned char* lds, const Gemm g, const StaticOrder S, const Epi E) {
;     ...
;             PG8_LDB(B0, 1, 0); PG8_LDB(B1, 1, 1); PG8_SCHED; PG8_LDA(At, 1, 0); PG8_STAGE(PG8_SA(0, 1), a2 + hstepA, voffA);
;             PG8_WAIT_V(8); PG8_WAIT_L(0); PG8_BAR; PG8_MMA(0, 0, At, B0); PG8_MMA(0, 1, At, B1); PG8_BAR; PG8_SCHED;
;             PG8_LDA(At, 1, 1); PG8_STAGE(PG8_SB(1, 0), b3, voffB); PG8_STAGE(PG8_SB(1, 1), b3 + hstepB, voffB); PG8_STAGE(PG8_SA(1, 0), a3, voffA);
;             PG8_WAIT_V(8); PG8_WAIT_L(0); PG8_BAR; PG8_MMA(1, 0, At, B0); PG8_MMA(1, 1, At, B1); PG8_BAR; PG8_SCHED;
;         }
	s_add_i32 s73, 0, 0x18000
	s_add_i32 s74, 0, 0x1c000
	v_add_u32_e32 v152, s73, v164
	v_add_u32_e32 v176, s74, v164
	ds_read_b128 v[128:131], v152
	ds_read_b128 v[132:135], v152 offset:1024
	ds_read_b128 v[136:139], v152 offset:2048
	ds_read_b128 v[152:155], v152 offset:3072
	ds_read_b128 v[156:159], v176
	ds_read_b128 v[168:171], v176 offset:1024
	ds_read_b128 v[172:175], v176 offset:2048
	ds_read_b128 v[176:179], v176 offset:3072
	s_add_u32 s46, s46, 0x160000
	s_addc_u32 s47, s47, 0
	s_mov_b32 m0, s54
	ds_read_b128 v[180:183], v166 offset:32768
	ds_read_b128 v[184:187], v166 offset:33792
	ds_read_b128 v[188:191], v166 offset:34816
	ds_read_b128 v[192:195], v166 offset:35840
	ds_read_b128 v[196:199], v166 offset:36864
	ds_read_b128 v[200:203], v166 offset:37888
	ds_read_b128 v[204:207], v166 offset:38912
	ds_read_b128 v[208:211], v166 offset:39936
	global_load_lds_dwordx4 v140, s[46:47]
	s_mov_b32 m0, s55
	s_nop 0
	global_load_lds_dwordx4 v144, s[46:47]
	s_waitcnt vmcnt(8)
	s_waitcnt lgkmcnt(0)
	s_barrier
	s_setprio 1
	s_waitcnt lgkmcnt(0)
	v_mfma_f32_16x16x32_bf16 v[124:127], v[128:131], v[180:183], v[124:127]
	v_mfma_f32_16x16x32_bf16 v[120:123], v[136:139], v[180:183], v[120:123]
	v_mfma_f32_16x16x32_bf16 v[108:111], v[128:131], v[188:191], v[108:111]
	v_mfma_f32_16x16x32_bf16 v[104:107], v[136:139], v[188:191], v[104:107]
	v_mfma_f32_16x16x32_bf16 v[92:95], v[128:131], v[196:199], v[92:95]
	v_mfma_f32_16x16x32_bf16 v[88:91], v[136:139], v[196:199], v[88:91]
	v_mfma_f32_16x16x32_bf16 v[76:79], v[128:131], v[204:207], v[76:79]
	v_mfma_f32_16x16x32_bf16 v[72:75], v[136:139], v[204:207], v[72:75]
	v_mfma_f32_16x16x32_bf16 v[124:127], v[132:135], v[184:187], v[124:127]
	v_mfma_f32_16x16x32_bf16 v[120:123], v[152:155], v[184:187], v[120:123]
	v_mfma_f32_16x16x32_bf16 v[108:111], v[132:135], v[192:195], v[108:111]
	v_mfma_f32_16x16x32_bf16 v[104:107], v[152:155], v[192:195], v[104:107]
	v_mfma_f32_16x16x32_bf16 v[92:95], v[132:135], v[200:203], v[92:95]
	v_mfma_f32_16x16x32_bf16 v[88:91], v[152:155], v[200:203], v[88:91]
	v_mfma_f32_16x16x32_bf16 v[76:79], v[132:135], v[208:211], v[76:79]
	v_mfma_f32_16x16x32_bf16 v[72:75], v[152:155], v[208:211], v[72:75]
	s_setprio 0
	s_setprio 1
	v_mfma_f32_16x16x32_bf16 v[116:119], v[156:159], v[180:183], v[116:119]
	v_mfma_f32_16x16x32_bf16 v[112:115], v[172:175], v[180:183], v[112:115]
	v_mfma_f32_16x16x32_bf16 v[100:103], v[156:159], v[188:191], v[100:103]
	v_mfma_f32_16x16x32_bf16 v[96:99], v[172:175], v[188:191], v[96:99]
	v_mfma_f32_16x16x32_bf16 v[84:87], v[156:159], v[196:199], v[84:87]
	v_mfma_f32_16x16x32_bf16 v[80:83], v[172:175], v[196:199], v[80:83]
	v_mfma_f32_16x16x32_bf16 v[68:71], v[156:159], v[204:207], v[68:71]
	v_mfma_f32_16x16x32_bf16 v[64:67], v[172:175], v[204:207], v[64:67]
	v_mfma_f32_16x16x32_bf16 v[116:119], v[168:171], v[184:187], v[116:119]
	v_mfma_f32_16x16x32_bf16 v[112:115], v[176:179], v[184:187], v[112:115]
	v_mfma_f32_16x16x32_bf16 v[100:103], v[168:171], v[192:195], v[100:103]
	v_mfma_f32_16x16x32_bf16 v[96:99], v[176:179], v[192:195], v[96:99]
	v_mfma_f32_16x16x32_bf16 v[84:87], v[168:171], v[200:203], v[84:87]
	v_mfma_f32_16x16x32_bf16 v[80:83], v[176:179], v[200:203], v[80:83]
	v_mfma_f32_16x16x32_bf16 v[68:71], v[168:171], v[208:211], v[68:71]
	v_mfma_f32_16x16x32_bf16 v[64:67], v[176:179], v[208:211], v[64:67]
	s_setprio 0
	s_barrier
	s_add_u32 s42, s42, s44
	s_addc_u32 s43, s43, s45
	s_add_i32 s44, s73, s51
	s_mov_b32 m0, s44
	ds_read_b128 v[180:183], v166 offset:49152
	ds_read_b128 v[184:187], v166 offset:50176
	ds_read_b128 v[188:191], v166 offset:51200
	ds_read_b128 v[192:195], v166 offset:52224
	ds_read_b128 v[196:199], v166 offset:53248
	ds_read_b128 v[200:203], v166 offset:54272
	ds_read_b128 v[204:207], v166 offset:55296
	ds_read_b128 v[208:211], v166 offset:56320
	global_load_lds_dwordx4 v142, s[42:43]
	s_add_i32 m0, s44, 0x2000
	s_nop 0
	global_load_lds_dwordx4 v146, s[42:43]
	s_add_u32 s42, s42, 0x160000
	s_addc_u32 s43, s43, 0
	s_add_i32 s44, s74, s51
	s_mov_b32 m0, s44
	s_nop 0
	global_load_lds_dwordx4 v142, s[42:43]
	s_add_i32 m0, s44, 0x2000
	s_nop 0
	global_load_lds_dwordx4 v146, s[42:43]
	s_mov_b32 m0, s57
	s_nop 0
	global_load_lds_dwordx4 v140, s[48:49]
	s_mov_b32 m0, s58
	s_nop 0
	global_load_lds_dwordx4 v144, s[48:49]
	s_waitcnt vmcnt(8)
	s_waitcnt lgkmcnt(0)
	s_barrier
	s_setprio 1
	s_waitcnt lgkmcnt(0)
	v_mfma_f32_16x16x32_bf16 v[60:63], v[128:131], v[180:183], v[60:63]
	v_mfma_f32_16x16x32_bf16 v[56:59], v[136:139], v[180:183], v[56:59]
	v_mfma_f32_16x16x32_bf16 v[44:47], v[128:131], v[188:191], v[44:47]
	v_mfma_f32_16x16x32_bf16 v[40:43], v[136:139], v[188:191], v[40:43]
	v_mfma_f32_16x16x32_bf16 v[28:31], v[128:131], v[196:199], v[28:31]
	v_mfma_f32_16x16x32_bf16 v[24:27], v[136:139], v[196:199], v[24:27]
	v_mfma_f32_16x16x32_bf16 v[12:15], v[128:131], v[204:207], v[12:15]
	v_mfma_f32_16x16x32_bf16 v[8:11], v[136:139], v[204:207], v[8:11]
	v_mfma_f32_16x16x32_bf16 v[60:63], v[132:135], v[184:187], v[60:63]
	v_mfma_f32_16x16x32_bf16 v[56:59], v[152:155], v[184:187], v[56:59]
	v_mfma_f32_16x16x32_bf16 v[44:47], v[132:135], v[192:195], v[44:47]
	v_mfma_f32_16x16x32_bf16 v[40:43], v[152:155], v[192:195], v[40:43]
	v_mfma_f32_16x16x32_bf16 v[28:31], v[132:135], v[200:203], v[28:31]
	v_mfma_f32_16x16x32_bf16 v[24:27], v[152:155], v[200:203], v[24:27]
	v_mfma_f32_16x16x32_bf16 v[12:15], v[132:135], v[208:211], v[12:15]
	v_mfma_f32_16x16x32_bf16 v[8:11], v[152:155], v[208:211], v[8:11]
	s_setprio 0
	s_setprio 1
	v_mfma_f32_16x16x32_bf16 v[52:55], v[156:159], v[180:183], v[52:55]
	v_mfma_f32_16x16x32_bf16 v[48:51], v[172:175], v[180:183], v[48:51]
	v_mfma_f32_16x16x32_bf16 v[36:39], v[156:159], v[188:191], v[36:39]
	v_mfma_f32_16x16x32_bf16 v[32:35], v[172:175], v[188:191], v[32:35]
	v_mfma_f32_16x16x32_bf16 v[20:23], v[156:159], v[196:199], v[20:23]
	v_mfma_f32_16x16x32_bf16 v[16:19], v[172:175], v[196:199], v[16:19]
	v_mfma_f32_16x16x32_bf16 v[4:7], v[156:159], v[204:207], v[4:7]
	v_mfma_f32_16x16x32_bf16 v[0:3], v[172:175], v[204:207], v[0:3]
	v_mfma_f32_16x16x32_bf16 v[52:55], v[168:171], v[184:187], v[52:55]
	v_mfma_f32_16x16x32_bf16 v[48:51], v[176:179], v[184:187], v[48:51]
	v_mfma_f32_16x16x32_bf16 v[36:39], v[168:171], v[192:195], v[36:39]
	v_mfma_f32_16x16x32_bf16 v[32:35], v[176:179], v[192:195], v[32:35]
	v_mfma_f32_16x16x32_bf16 v[20:23], v[168:171], v[200:203], v[20:23]
	v_mfma_f32_16x16x32_bf16 v[16:19], v[176:179], v[200:203], v[16:19]
	v_mfma_f32_16x16x32_bf16 v[4:7], v[168:171], v[208:211], v[4:7]
	v_mfma_f32_16x16x32_bf16 v[0:3], v[176:179], v[208:211], v[0:3]
	s_setprio 0
	s_barrier
	s_cmpk_gt_u32 s71, 0x55
	s_mov_b32 s71, s72
	s_cbranch_scc1 .LBB0_758

; #define PG8_STAGE(bufoff, gbase, voff) do { _Pragma("unroll") for (int _i = 0; _i < 2; ++_i) \
;         __builtin_amdgcn_global_load_lds((const unsigned*)((const char*)(gbase) + (voff)[_i]), (LAS unsigned*)(lds + (bufoff) + ldsw + _i * 8192), 16, 0, 0); } while (0)
; #define PG8_WAIT_V(n) asm volatile("s_waitcnt vmcnt(" #n ")" ::: "memory")
; #define PG8_BAR __builtin_amdgcn_s_barrier()
; template <class Epi>
; __device__ __forceinline__ void gemm_phase(LAS unsigned char* lds, const Gemm g, const StaticOrder S, const Epi E) {
;     ...
;     for (int i = 0; i < 2; ++i) { int R, C; stage_rc(tid * 16 + i * 8192, R, C); const int Rb = Epi::PERM ? ((R & ~31) + perm32(R & 31)) : R;
;         voffA[i] = (unsigned)(R * g.lda + C) * 2u; voffB[i] = (unsigned)(Rb * g.ldb + C) * 2u; }
;     const size_t kstep = (size_t)(BK * 2);
;     const size_t hstepA = (size_t)HALF * g.lda * 2, hstepB = (size_t)HALF * g.ldb * 2;
;     const size_t tstepA = 2 * hstepA, tstepB = 2 * hstepB;
;     const unsigned ldsw = (unsigned)wid * 1024u;
;     const int aoff = lds_byte(wr * 64 + fr, fq * 8), boff = lds_byte(wc * 32 + fr, fq * 8);
;     ...
;     PG8_STAGE(PG8_SB(1, 0), cB + ksc, voffB); PG8_STAGE(PG8_SA(1, 0), cA + ksc, voffA); PG8_STAGE(PG8_SB(1, 1), cB + hstepB + ksc, voffB);
;     PG8_WAIT_V(6); PG8_BAR;
.LBB0_847:
	s_add_u32 s6, s82, 0x2a9b0000
	s_addc_u32 s7, s83, 0
	s_lshl_b32 s9, s9, 5
	s_mov_b64 s[26:27], 0x80
	s_and_b32 s14, s9, 0x60
	s_add_i32 m0, s21, 0x18000
	v_lshl_add_u64 v[6:7], v[6:7], 0, s[26:27]
	s_lshl_b32 s10, s8, 13
	s_lshl_b32 s9, s14, 7
	s_waitcnt vmcnt(2)
	s_barrier
	global_load_lds_dwordx4 v[6:7], off
	v_lshl_add_u64 v[4:5], v[4:5], 0, s[26:27]
	s_add_i32 m0, s21, 0x1a000
	s_add_i32 s55, s21, 0x8000
	s_add_i32 s56, s21, 0xa000
	global_load_lds_dwordx4 v[4:5], off
	v_lshl_add_u64 v[0:1], v[0:1], 0, s[26:27]
	s_mov_b32 m0, s55
	s_add_u32 s12, s22, 0x80080
	global_load_lds_dwordx4 v[0:1], off
	v_lshl_add_u64 v[0:1], v[2:3], 0, s[26:27]
	s_mov_b32 m0, s56
	s_addc_u32 s13, s23, 0
	global_load_lds_dwordx4 v[0:1], off
	s_add_i32 m0, s21, 0x1c000
	s_nop 0
	global_load_lds_dwordx4 v132, s[12:13]
	s_add_i32 m0, s21, 0x1e000
	v_lshlrev_b32_e32 v2, 2, v224
	global_load_lds_dwordx4 v128, s[12:13]
	v_and_b32_e32 v0, 15, v224
	v_lshlrev_b32_e32 v1, 1, v8
	s_sext_i32_i16 s63, s0
	v_lshl_or_b32 v142, s8, 6, v0
	v_lshl_or_b32 v0, v0, 6, v1
	v_and_b32_e32 v2, 32, v2
	v_lshlrev_b32_e32 v3, 6, v224
	s_movk_i32 s0, 0x3c0
	s_waitcnt vmcnt(6)
	s_ashr_i32 s57, s78, 31
	v_bitop3_b32 v0, v0, s10, v2 bitop3:0xde
	v_and_or_b32 v1, v3, s0, v1
	s_cmpk_lt_u32 s1, 0x100
	v_bitop3_b32 v143, s9, v1, v2 bitop3:0xf6
	v_add_u32_e32 v254, 0x10000, v143
	s_cselect_b64 s[8:9], -1, 0
	v_or_b32_e32 v144, s14, v8
	v_mov_b64_e32 v[136:137], 0xb00
	v_mov_b64_e32 v[138:139], 0xaff
	s_movk_i32 s58, 0xff80
	s_add_i32 s59, 0, 0x10000
	s_add_i32 s60, 0, 0x14000
	v_add_u32_e32 v145, 0, v0
	s_movk_i32 s61, 0x2c00
	v_mov_b32_e32 v146, 0x358637bd
	s_barrier
	s_branch .LBB0_850

; #define PG8_STAGE(bufoff, gbase, voff) do { _Pragma("unroll") for (int _i = 0; _i < 2; ++_i) \
;         __builtin_amdgcn_global_load_lds((const unsigned*)((const char*)(gbase) + (voff)[_i]), (LAS unsigned*)(lds + (bufoff) + ldsw + _i * 8192), 16, 0, 0); } while (0)
; #define PG8_LDA(dst, b, h) do { _Pragma("unroll") for (int m = 0; m < 4; ++m) _Pragma("unroll") for (int k = 0; k < 2; ++k) dst[m][k] = *(const LAS bf16x8*)(lds + PG8_SA(b, h) + aoff + m * 2048 + k * 1024); } while (0)
; #define PG8_LDB(dst, b, h) do { _Pragma("unroll") for (int n = 0; n < 2; ++n) _Pragma("unroll") for (int k = 0; k < 2; ++k) dst[n][k] = *(const LAS bf16x8*)(lds + PG8_SB(b, h) + boff + n * 2048 + k * 1024); } while (0)
; #define PG8_MMA(ai, bj, At, Bt) do { __builtin_amdgcn_s_setprio(1); _Pragma("unroll") for (int m = 0; m < 4; ++m) _Pragma("unroll") for (int n = 0; n < 2; ++n) _Pragma("unroll") for (int k = 0; k < 2; ++k) \
;         acc[ai][bj][m][n] = __builtin_amdgcn_mfma_f32_16x16x32_bf16(Bt[n][k], At[m][k], acc[ai][bj][m][n], 0, 0, 0); __builtin_amdgcn_s_setprio(0); } while (0)
; #define PG8_WAIT_V(n) asm volatile("s_waitcnt vmcnt(" #n ")" ::: "memory")
; #define PG8_WAIT_L(n) asm volatile("s_waitcnt lgkmcnt(" #n ")" ::: "memory")
; #define PG8_BAR __builtin_amdgcn_s_barrier()
; #define PG8_SCHED __builtin_amdgcn_sched_barrier(0)
; template <class Epi>
; __device__ __forceinline__ void gemm_phase(LAS unsigned char* lds, const Gemm g, const StaticOrder S, const Epi E) {
;     ...
;             const char* a1 = cA + (long)(t + 1) * ksc;
;             const char* a2 = last ? nA : cA + (long)(t + 2) * ksc; const char* b2 = last ? nB : cB + (long)(t + 2) * ksc;
;             const long ks3 = last ? ksn : ksc;
;             const char* a3 = a2 + ks3; const char* b3 = b2 + ks3;
;             PG8_LDB(B0, 0, 0); PG8_LDB(B1, 0, 1); PG8_SCHED; PG8_LDA(At, 0, 0); PG8_STAGE(PG8_SA(1, 1), a1 + hstepA, voffA);
;             PG8_WAIT_V(8); PG8_WAIT_L(0); PG8_BAR; PG8_MMA(0, 0, At, B0); PG8_MMA(0, 1, At, B1); PG8_BAR; PG8_SCHED;
;             PG8_LDA(At, 0, 1); PG8_STAGE(PG8_SB(0, 0), b2, voffB); PG8_STAGE(PG8_SB(0, 1), b2 + hstepB, voffB); PG8_STAGE(PG8_SA(0, 0), a2, voffA);
;             PG8_WAIT_V(8); PG8_WAIT_L(0); PG8_BAR; PG8_MMA(1, 0, At, B0); PG8_MMA(1, 1, At, B1); PG8_BAR; PG8_SCHED;
.LBB0_853:
	ds_read_b128 v[148:151], v254
	ds_read_b128 v[152:155], v254 offset:1024
	ds_read_b128 v[156:159], v254 offset:2048
	ds_read_b128 v[160:163], v254 offset:3072
	ds_read_b128 v[164:167], v254 offset:16384
	ds_read_b128 v[168:171], v254 offset:17408
	ds_read_b128 v[172:175], v254 offset:18432
	ds_read_b128 v[176:179], v254 offset:19456
	s_or_b32 s13, s64, 1
	s_mul_i32 s48, s27, s13
	s_mul_hi_u32 s49, s26, s13
	s_add_i32 s49, s49, s48
	s_mul_i32 s13, s26, s13
	s_add_u32 s13, s24, s13
	s_addc_u32 s65, s25, s49
	s_add_u32 s48, s46, s44
	s_addc_u32 s49, s47, s45
	s_add_u32 s66, s13, 0x80000
	s_addc_u32 s67, s65, 0
	s_add_i32 m0, s21, 0xc000
	ds_read_b128 v[180:183], v145
	ds_read_b128 v[184:187], v145 offset:1024
	ds_read_b128 v[188:191], v145 offset:2048
	ds_read_b128 v[192:195], v145 offset:3072
	ds_read_b128 v[196:199], v145 offset:4096
	ds_read_b128 v[200:203], v145 offset:5120
	ds_read_b128 v[204:207], v145 offset:6144
	ds_read_b128 v[208:211], v145 offset:7168
	global_load_lds_dwordx4 v134, s[66:67]
	s_add_i32 m0, s21, 0xe000
	s_nop 0
	global_load_lds_dwordx4 v130, s[66:67]
	s_waitcnt vmcnt(8)
	s_waitcnt lgkmcnt(0)
	s_barrier
	s_setprio 1
	s_waitcnt lgkmcnt(0)
	v_mfma_f32_16x16x32_bf16 v[116:119], v[148:151], v[180:183], v[116:119]
	v_mfma_f32_16x16x32_bf16 v[112:115], v[156:159], v[180:183], v[112:115]
	v_mfma_f32_16x16x32_bf16 v[108:111], v[148:151], v[188:191], v[108:111]
	v_mfma_f32_16x16x32_bf16 v[104:107], v[156:159], v[188:191], v[104:107]
	v_mfma_f32_16x16x32_bf16 v[92:95], v[148:151], v[196:199], v[92:95]
	v_mfma_f32_16x16x32_bf16 v[88:91], v[156:159], v[196:199], v[88:91]
	v_mfma_f32_16x16x32_bf16 v[76:79], v[148:151], v[204:207], v[76:79]
	v_mfma_f32_16x16x32_bf16 v[72:75], v[156:159], v[204:207], v[72:75]
	v_mfma_f32_16x16x32_bf16 v[116:119], v[152:155], v[184:187], v[116:119]
	v_mfma_f32_16x16x32_bf16 v[112:115], v[160:163], v[184:187], v[112:115]
	v_mfma_f32_16x16x32_bf16 v[108:111], v[152:155], v[192:195], v[108:111]
	v_mfma_f32_16x16x32_bf16 v[104:107], v[160:163], v[192:195], v[104:107]
	v_mfma_f32_16x16x32_bf16 v[92:95], v[152:155], v[200:203], v[92:95]
	v_mfma_f32_16x16x32_bf16 v[88:91], v[160:163], v[200:203], v[88:91]
	v_mfma_f32_16x16x32_bf16 v[76:79], v[152:155], v[208:211], v[76:79]
	v_mfma_f32_16x16x32_bf16 v[72:75], v[160:163], v[208:211], v[72:75]
	s_setprio 0
	s_setprio 1
	v_mfma_f32_16x16x32_bf16 v[124:127], v[164:167], v[180:183], v[124:127]
	v_mfma_f32_16x16x32_bf16 v[120:123], v[172:175], v[180:183], v[120:123]
	v_mfma_f32_16x16x32_bf16 v[100:103], v[164:167], v[188:191], v[100:103]
	v_mfma_f32_16x16x32_bf16 v[96:99], v[172:175], v[188:191], v[96:99]
	v_mfma_f32_16x16x32_bf16 v[84:87], v[164:167], v[196:199], v[84:87]
	v_mfma_f32_16x16x32_bf16 v[80:83], v[172:175], v[196:199], v[80:83]
	v_mfma_f32_16x16x32_bf16 v[68:71], v[164:167], v[204:207], v[68:71]
	v_mfma_f32_16x16x32_bf16 v[64:67], v[172:175], v[204:207], v[64:67]
	v_mfma_f32_16x16x32_bf16 v[124:127], v[168:171], v[184:187], v[124:127]
	v_mfma_f32_16x16x32_bf16 v[120:123], v[176:179], v[184:187], v[120:123]
	v_mfma_f32_16x16x32_bf16 v[100:103], v[168:171], v[192:195], v[100:103]
	v_mfma_f32_16x16x32_bf16 v[96:99], v[176:179], v[192:195], v[96:99]
	v_mfma_f32_16x16x32_bf16 v[84:87], v[168:171], v[200:203], v[84:87]
	v_mfma_f32_16x16x32_bf16 v[80:83], v[176:179], v[200:203], v[80:83]
	v_mfma_f32_16x16x32_bf16 v[68:71], v[168:171], v[208:211], v[68:71]
	v_mfma_f32_16x16x32_bf16 v[64:67], v[176:179], v[208:211], v[64:67]
	s_setprio 0
	s_barrier
	s_add_i32 s13, s59, s33
	s_mov_b32 m0, s13
	ds_read_b128 v[180:183], v145 offset:16384
	ds_read_b128 v[184:187], v145 offset:17408
	ds_read_b128 v[188:191], v145 offset:18432
	ds_read_b128 v[192:195], v145 offset:19456
	ds_read_b128 v[196:199], v145 offset:20480
	ds_read_b128 v[200:203], v145 offset:21504
	ds_read_b128 v[204:207], v145 offset:22528
	ds_read_b128 v[208:211], v145 offset:23552
	global_load_lds_dwordx4 v132, s[42:43]
	s_add_i32 m0, s13, 0x2000
	s_add_u32 s66, s42, 0x80000
	s_addc_u32 s67, s43, 0
	s_add_i32 s13, s60, s33
	global_load_lds_dwordx4 v128, s[42:43]
	s_mov_b32 m0, s13
	s_nop 0
	global_load_lds_dwordx4 v132, s[66:67]
	s_add_i32 m0, s13, 0x2000
	s_nop 0
	global_load_lds_dwordx4 v128, s[66:67]
	s_mov_b32 m0, s21
	s_nop 0
	global_load_lds_dwordx4 v134, s[46:47]
	s_mov_b32 m0, s52
	s_nop 0
	global_load_lds_dwordx4 v130, s[46:47]
	s_waitcnt vmcnt(8)
	s_waitcnt lgkmcnt(0)
	s_barrier
	s_setprio 1
	s_waitcnt lgkmcnt(0)
	v_mfma_f32_16x16x32_bf16 v[60:63], v[148:151], v[180:183], v[60:63]
	v_mfma_f32_16x16x32_bf16 v[56:59], v[156:159], v[180:183], v[56:59]
	v_mfma_f32_16x16x32_bf16 v[44:47], v[148:151], v[188:191], v[44:47]
	v_mfma_f32_16x16x32_bf16 v[40:43], v[156:159], v[188:191], v[40:43]
	v_mfma_f32_16x16x32_bf16 v[28:31], v[148:151], v[196:199], v[28:31]
	v_mfma_f32_16x16x32_bf16 v[24:27], v[156:159], v[196:199], v[24:27]
	v_mfma_f32_16x16x32_bf16 v[12:15], v[148:151], v[204:207], v[12:15]
	v_mfma_f32_16x16x32_bf16 v[8:11], v[156:159], v[204:207], v[8:11]
	v_mfma_f32_16x16x32_bf16 v[60:63], v[152:155], v[184:187], v[60:63]
	v_mfma_f32_16x16x32_bf16 v[56:59], v[160:163], v[184:187], v[56:59]
	v_mfma_f32_16x16x32_bf16 v[44:47], v[152:155], v[192:195], v[44:47]
	v_mfma_f32_16x16x32_bf16 v[40:43], v[160:163], v[192:195], v[40:43]
	v_mfma_f32_16x16x32_bf16 v[28:31], v[152:155], v[200:203], v[28:31]
	v_mfma_f32_16x16x32_bf16 v[24:27], v[160:163], v[200:203], v[24:27]
	v_mfma_f32_16x16x32_bf16 v[12:15], v[152:155], v[208:211], v[12:15]
	v_mfma_f32_16x16x32_bf16 v[8:11], v[160:163], v[208:211], v[8:11]
	s_setprio 0
	s_setprio 1
	v_mfma_f32_16x16x32_bf16 v[52:55], v[164:167], v[180:183], v[52:55]
	v_mfma_f32_16x16x32_bf16 v[48:51], v[172:175], v[180:183], v[48:51]
	v_mfma_f32_16x16x32_bf16 v[36:39], v[164:167], v[188:191], v[36:39]
	v_mfma_f32_16x16x32_bf16 v[32:35], v[172:175], v[188:191], v[32:35]
	v_mfma_f32_16x16x32_bf16 v[20:23], v[164:167], v[196:199], v[20:23]
	v_mfma_f32_16x16x32_bf16 v[16:19], v[172:175], v[196:199], v[16:19]
	v_mfma_f32_16x16x32_bf16 v[4:7], v[164:167], v[204:207], v[4:7]
	v_mfma_f32_16x16x32_bf16 v[0:3], v[172:175], v[204:207], v[0:3]
	v_mfma_f32_16x16x32_bf16 v[52:55], v[168:171], v[184:187], v[52:55]
	v_mfma_f32_16x16x32_bf16 v[48:51], v[176:179], v[184:187], v[48:51]
	v_mfma_f32_16x16x32_bf16 v[36:39], v[168:171], v[192:195], v[36:39]
	v_mfma_f32_16x16x32_bf16 v[32:35], v[176:179], v[192:195], v[32:35]
	v_mfma_f32_16x16x32_bf16 v[20:23], v[168:171], v[200:203], v[20:23]
	v_mfma_f32_16x16x32_bf16 v[16:19], v[176:179], v[200:203], v[16:19]
	v_mfma_f32_16x16x32_bf16 v[4:7], v[168:171], v[208:211], v[4:7]
	v_mfma_f32_16x16x32_bf16 v[0:3], v[176:179], v[208:211], v[0:3]
	s_setprio 0
	s_barrier
; #define PG8_STAGE(bufoff, gbase, voff) do { _Pragma("unroll") for (int _i = 0; _i < 2; ++_i) \
;         __builtin_amdgcn_global_load_lds((const unsigned*)((const char*)(gbase) + (voff)[_i]), (LAS unsigned*)(lds + (bufoff) + ldsw + _i * 8192), 16, 0, 0); } while (0)
; #define PG8_LDA(dst, b, h) do { _Pragma("unroll") for (int m = 0; m < 4; ++m) _Pragma("unroll") for (int k = 0; k < 2; ++k) dst[m][k] = *(const LAS bf16x8*)(lds + PG8_SA(b, h) + aoff + m * 2048 + k * 1024); } while (0)
; #define PG8_LDB(dst, b, h) do { _Pragma("unroll") for (int n = 0; n < 2; ++n) _Pragma("unroll") for (int k = 0; k < 2; ++k) dst[n][k] = *(const LAS bf16x8*)(lds + PG8_SB(b, h) + boff + n * 2048 + k * 1024); } while (0)
; #define PG8_MMA(ai, bj, At, Bt) do { __builtin_amdgcn_s_setprio(1); _Pragma("unroll") for (int m = 0; m < 4; ++m) _Pragma("unroll") for (int n = 0; n < 2; ++n) _Pragma("unroll") for (int k = 0; k < 2; ++k) \
;         acc[ai][bj][m][n] = __builtin_amdgcn_mfma_f32_16x16x32_bf16(Bt[n][k], At[m][k], acc[ai][bj][m][n], 0, 0, 0); __builtin_amdgcn_s_setprio(0); } while (0)
; #define PG8_WAIT_V(n) asm volatile("s_waitcnt vmcnt(" #n ")" ::: "memory")
; #define PG8_WAIT_L(n) asm volatile("s_waitcnt lgkmcnt(" #n ")" ::: "memory")
; #define PG8_BAR __builtin_amdgcn_s_barrier()
; #define PG8_SCHED __builtin_amdgcn_sched_barrier(0)
; template <class Epi>
; __device__ __forceinline__ void gemm_phase(LAS unsigned char* lds, const Gemm g, const StaticOrder S, const Epi E) {
;     ...
;             PG8_LDB(B0, 1, 0); PG8_LDB(B1, 1, 1); PG8_SCHED; PG8_LDA(At, 1, 0); PG8_STAGE(PG8_SA(0, 1), a2 + hstepA, voffA);
;             PG8_WAIT_V(8); PG8_WAIT_L(0); PG8_BAR; PG8_MMA(0, 0, At, B0); PG8_MMA(0, 1, At, B1); PG8_BAR; PG8_SCHED;
;             PG8_LDA(At, 1, 1); PG8_STAGE(PG8_SB(1, 0), b3, voffB); PG8_STAGE(PG8_SB(1, 1), b3 + hstepB, voffB); PG8_STAGE(PG8_SA(1, 0), a3, voffA);
;             PG8_WAIT_V(8); PG8_WAIT_L(0); PG8_BAR; PG8_MMA(1, 0, At, B0); PG8_MMA(1, 1, At, B1); PG8_BAR; PG8_SCHED;
;         }
	s_add_i32 s13, 0, 0x18000
	s_add_i32 s65, 0, 0x1c000
	ds_read_b128 v[148:151], v254 offset:32768
	ds_read_b128 v[152:155], v254 offset:33792
	ds_read_b128 v[156:159], v254 offset:34816
	ds_read_b128 v[160:163], v254 offset:35840
	ds_read_b128 v[164:167], v254 offset:49152
	ds_read_b128 v[168:171], v254 offset:50176
	ds_read_b128 v[172:175], v254 offset:51200
	ds_read_b128 v[176:179], v254 offset:52224
	s_add_u32 s46, s46, 0x80000
	s_addc_u32 s47, s47, 0
	s_mov_b32 m0, s53
	ds_read_b128 v[180:183], v145 offset:32768
	ds_read_b128 v[184:187], v145 offset:33792
	ds_read_b128 v[188:191], v145 offset:34816
	ds_read_b128 v[192:195], v145 offset:35840
	ds_read_b128 v[196:199], v145 offset:36864
	ds_read_b128 v[200:203], v145 offset:37888
	ds_read_b128 v[204:207], v145 offset:38912
	ds_read_b128 v[208:211], v145 offset:39936
	global_load_lds_dwordx4 v134, s[46:47]
	s_mov_b32 m0, s54
	s_nop 0
	global_load_lds_dwordx4 v130, s[46:47]
	s_waitcnt vmcnt(8)
	s_waitcnt lgkmcnt(0)
	s_barrier
	s_setprio 1
	s_waitcnt lgkmcnt(0)
	v_mfma_f32_16x16x32_bf16 v[116:119], v[148:151], v[180:183], v[116:119]
	v_mfma_f32_16x16x32_bf16 v[112:115], v[156:159], v[180:183], v[112:115]
	v_mfma_f32_16x16x32_bf16 v[108:111], v[148:151], v[188:191], v[108:111]
	v_mfma_f32_16x16x32_bf16 v[104:107], v[156:159], v[188:191], v[104:107]
	v_mfma_f32_16x16x32_bf16 v[92:95], v[148:151], v[196:199], v[92:95]
	v_mfma_f32_16x16x32_bf16 v[88:91], v[156:159], v[196:199], v[88:91]
	v_mfma_f32_16x16x32_bf16 v[76:79], v[148:151], v[204:207], v[76:79]
	v_mfma_f32_16x16x32_bf16 v[72:75], v[156:159], v[204:207], v[72:75]
	v_mfma_f32_16x16x32_bf16 v[116:119], v[152:155], v[184:187], v[116:119]
	v_mfma_f32_16x16x32_bf16 v[112:115], v[160:163], v[184:187], v[112:115]
	v_mfma_f32_16x16x32_bf16 v[108:111], v[152:155], v[192:195], v[108:111]
	v_mfma_f32_16x16x32_bf16 v[104:107], v[160:163], v[192:195], v[104:107]
	v_mfma_f32_16x16x32_bf16 v[92:95], v[152:155], v[200:203], v[92:95]
	v_mfma_f32_16x16x32_bf16 v[88:91], v[160:163], v[200:203], v[88:91]
	v_mfma_f32_16x16x32_bf16 v[76:79], v[152:155], v[208:211], v[76:79]
	v_mfma_f32_16x16x32_bf16 v[72:75], v[160:163], v[208:211], v[72:75]
	s_setprio 0
	s_setprio 1
	v_mfma_f32_16x16x32_bf16 v[124:127], v[164:167], v[180:183], v[124:127]
	v_mfma_f32_16x16x32_bf16 v[120:123], v[172:175], v[180:183], v[120:123]
	v_mfma_f32_16x16x32_bf16 v[100:103], v[164:167], v[188:191], v[100:103]
	v_mfma_f32_16x16x32_bf16 v[96:99], v[172:175], v[188:191], v[96:99]
	v_mfma_f32_16x16x32_bf16 v[84:87], v[164:167], v[196:199], v[84:87]
	v_mfma_f32_16x16x32_bf16 v[80:83], v[172:175], v[196:199], v[80:83]
	v_mfma_f32_16x16x32_bf16 v[68:71], v[164:167], v[204:207], v[68:71]
	v_mfma_f32_16x16x32_bf16 v[64:67], v[172:175], v[204:207], v[64:67]
	v_mfma_f32_16x16x32_bf16 v[124:127], v[168:171], v[184:187], v[124:127]
	v_mfma_f32_16x16x32_bf16 v[120:123], v[176:179], v[184:187], v[120:123]
	v_mfma_f32_16x16x32_bf16 v[100:103], v[168:171], v[192:195], v[100:103]
	v_mfma_f32_16x16x32_bf16 v[96:99], v[176:179], v[192:195], v[96:99]
	v_mfma_f32_16x16x32_bf16 v[84:87], v[168:171], v[200:203], v[84:87]
	v_mfma_f32_16x16x32_bf16 v[80:83], v[176:179], v[200:203], v[80:83]
	v_mfma_f32_16x16x32_bf16 v[68:71], v[168:171], v[208:211], v[68:71]
	v_mfma_f32_16x16x32_bf16 v[64:67], v[176:179], v[208:211], v[64:67]
	s_setprio 0
	s_barrier
	s_add_u32 s42, s42, s44
	s_addc_u32 s43, s43, s45
	s_add_i32 s13, s13, s33
	s_mov_b32 m0, s13
	ds_read_b128 v[180:183], v145 offset:49152
	ds_read_b128 v[184:187], v145 offset:50176
	ds_read_b128 v[188:191], v145 offset:51200
	ds_read_b128 v[192:195], v145 offset:52224
	ds_read_b128 v[196:199], v145 offset:53248
	ds_read_b128 v[200:203], v145 offset:54272
	ds_read_b128 v[204:207], v145 offset:55296
	ds_read_b128 v[208:211], v145 offset:56320
	global_load_lds_dwordx4 v132, s[42:43]
	s_add_i32 m0, s13, 0x2000
	s_nop 0
	global_load_lds_dwordx4 v128, s[42:43]
	s_add_u32 s42, s42, 0x80000
	s_addc_u32 s43, s43, 0
	s_add_i32 s13, s65, s33
	s_mov_b32 m0, s13
	s_nop 0
	global_load_lds_dwordx4 v132, s[42:43]
	s_add_i32 m0, s13, 0x2000
	s_nop 0
	global_load_lds_dwordx4 v128, s[42:43]
	s_mov_b32 m0, s55
	s_nop 0
	global_load_lds_dwordx4 v134, s[48:49]
	s_mov_b32 m0, s56
	s_nop 0
	global_load_lds_dwordx4 v130, s[48:49]
	s_waitcnt vmcnt(8)
	s_waitcnt lgkmcnt(0)
	s_barrier
	s_setprio 1
	s_waitcnt lgkmcnt(0)
	v_mfma_f32_16x16x32_bf16 v[60:63], v[148:151], v[180:183], v[60:63]
	v_mfma_f32_16x16x32_bf16 v[56:59], v[156:159], v[180:183], v[56:59]
	v_mfma_f32_16x16x32_bf16 v[44:47], v[148:151], v[188:191], v[44:47]
	v_mfma_f32_16x16x32_bf16 v[40:43], v[156:159], v[188:191], v[40:43]
	v_mfma_f32_16x16x32_bf16 v[28:31], v[148:151], v[196:199], v[28:31]
	v_mfma_f32_16x16x32_bf16 v[24:27], v[156:159], v[196:199], v[24:27]
	v_mfma_f32_16x16x32_bf16 v[12:15], v[148:151], v[204:207], v[12:15]
	v_mfma_f32_16x16x32_bf16 v[8:11], v[156:159], v[204:207], v[8:11]
	v_mfma_f32_16x16x32_bf16 v[60:63], v[152:155], v[184:187], v[60:63]
	v_mfma_f32_16x16x32_bf16 v[56:59], v[160:163], v[184:187], v[56:59]
	v_mfma_f32_16x16x32_bf16 v[44:47], v[152:155], v[192:195], v[44:47]
	v_mfma_f32_16x16x32_bf16 v[40:43], v[160:163], v[192:195], v[40:43]
	v_mfma_f32_16x16x32_bf16 v[28:31], v[152:155], v[200:203], v[28:31]
	v_mfma_f32_16x16x32_bf16 v[24:27], v[160:163], v[200:203], v[24:27]
	v_mfma_f32_16x16x32_bf16 v[12:15], v[152:155], v[208:211], v[12:15]
	v_mfma_f32_16x16x32_bf16 v[8:11], v[160:163], v[208:211], v[8:11]
	s_setprio 0
	s_setprio 1
	v_mfma_f32_16x16x32_bf16 v[52:55], v[164:167], v[180:183], v[52:55]
	v_mfma_f32_16x16x32_bf16 v[48:51], v[172:175], v[180:183], v[48:51]
	v_mfma_f32_16x16x32_bf16 v[36:39], v[164:167], v[188:191], v[36:39]
	v_mfma_f32_16x16x32_bf16 v[32:35], v[172:175], v[188:191], v[32:35]
	v_mfma_f32_16x16x32_bf16 v[20:23], v[164:167], v[196:199], v[20:23]
	v_mfma_f32_16x16x32_bf16 v[16:19], v[172:175], v[196:199], v[16:19]
	v_mfma_f32_16x16x32_bf16 v[4:7], v[164:167], v[204:207], v[4:7]
	v_mfma_f32_16x16x32_bf16 v[0:3], v[172:175], v[204:207], v[0:3]
	v_mfma_f32_16x16x32_bf16 v[52:55], v[168:171], v[184:187], v[52:55]
	v_mfma_f32_16x16x32_bf16 v[48:51], v[176:179], v[184:187], v[48:51]
	v_mfma_f32_16x16x32_bf16 v[36:39], v[168:171], v[192:195], v[36:39]
	v_mfma_f32_16x16x32_bf16 v[32:35], v[176:179], v[192:195], v[32:35]
	v_mfma_f32_16x16x32_bf16 v[20:23], v[168:171], v[200:203], v[20:23]
	v_mfma_f32_16x16x32_bf16 v[16:19], v[176:179], v[200:203], v[16:19]
	v_mfma_f32_16x16x32_bf16 v[4:7], v[168:171], v[208:211], v[4:7]
	v_mfma_f32_16x16x32_bf16 v[0:3], v[176:179], v[208:211], v[0:3]
	s_setprio 0
	s_barrier
	s_cmp_gt_u32 s64, 29
	s_mov_b32 s64, s11
	s_cbranch_scc1 .LBB0_858

; #define PG8_STAGE(bufoff, gbase, voff) do { _Pragma("unroll") for (int _i = 0; _i < 2; ++_i) \
;         __builtin_amdgcn_global_load_lds((const unsigned*)((const char*)(gbase) + (voff)[_i]), (LAS unsigned*)(lds + (bufoff) + ldsw + _i * 8192), 16, 0, 0); } while (0)
; #define PG8_LDA(dst, b, h) do { _Pragma("unroll") for (int m = 0; m < 4; ++m) _Pragma("unroll") for (int k = 0; k < 2; ++k) dst[m][k] = *(const LAS bf16x8*)(lds + PG8_SA(b, h) + aoff + m * 2048 + k * 1024); } while (0)
; #define PG8_LDB(dst, b, h) do { _Pragma("unroll") for (int n = 0; n < 2; ++n) _Pragma("unroll") for (int k = 0; k < 2; ++k) dst[n][k] = *(const LAS bf16x8*)(lds + PG8_SB(b, h) + boff + n * 2048 + k * 1024); } while (0)
; #define PG8_MMA(ai, bj, At, Bt) do { __builtin_amdgcn_s_setprio(1); _Pragma("unroll") for (int m = 0; m < 4; ++m) _Pragma("unroll") for (int n = 0; n < 2; ++n) _Pragma("unroll") for (int k = 0; k < 2; ++k) \
;         acc[ai][bj][m][n] = __builtin_amdgcn_mfma_f32_16x16x32_bf16(Bt[n][k], At[m][k], acc[ai][bj][m][n], 0, 0, 0); __builtin_amdgcn_s_setprio(0); } while (0)
; #define PG8_WAIT_V(n) asm volatile("s_waitcnt vmcnt(" #n ")" ::: "memory")
; #define PG8_WAIT_L(n) asm volatile("s_waitcnt lgkmcnt(" #n ")" ::: "memory")
; #define PG8_BAR __builtin_amdgcn_s_barrier()
; #define PG8_SCHED __builtin_amdgcn_sched_barrier(0)
; template <class Epi>
; __device__ __forceinline__ void gemm_phase(LAS unsigned char* lds, const Gemm g, const StaticOrder S, const Epi E) {
;     ...
;             const char* a1 = cA + (long)(t + 1) * ksc;
;             const char* a2 = last ? nA : cA + (long)(t + 2) * ksc; const char* b2 = last ? nB : cB + (long)(t + 2) * ksc;
;             const long ks3 = last ? ksn : ksc;
;             const char* a3 = a2 + ks3; const char* b3 = b2 + ks3;
;             PG8_LDB(B0, 0, 0); PG8_LDB(B1, 0, 1); PG8_SCHED; PG8_LDA(At, 0, 0); PG8_STAGE(PG8_SA(1, 1), a1 + hstepA, voffA);
;             PG8_WAIT_V(8); PG8_WAIT_L(0); PG8_BAR; PG8_MMA(0, 0, At, B0); PG8_MMA(0, 1, At, B1); PG8_BAR; PG8_SCHED;
;             PG8_LDA(At, 0, 1); PG8_STAGE(PG8_SB(0, 0), b2, voffB); PG8_STAGE(PG8_SB(0, 1), b2 + hstepB, voffB); PG8_STAGE(PG8_SA(0, 0), a2, voffA);
;             PG8_WAIT_V(8); PG8_WAIT_L(0); PG8_BAR; PG8_MMA(1, 0, At, B0); PG8_MMA(1, 1, At, B1); PG8_BAR; PG8_SCHED;
.LBB0_938:
	v_add_u32_e32 v152, s59, v166
	v_add_u32_e32 v178, s60, v166
	ds_read_b128 v[128:131], v152
	ds_read_b128 v[132:135], v152 offset:1024
	ds_read_b128 v[136:139], v152 offset:2048
	ds_read_b128 v[152:155], v152 offset:3072
	ds_read_b128 v[156:159], v178
	ds_read_b128 v[170:173], v178 offset:1024
	ds_read_b128 v[174:177], v178 offset:2048
	ds_read_b128 v[178:181], v178 offset:3072
	s_or_b32 s48, s70, 1
	s_mul_i32 s49, s35, s48
	s_mul_hi_u32 s72, s34, s48
	s_add_i32 s72, s72, s49
	s_mul_i32 s48, s34, s48
	s_add_u32 s73, s30, s48
	s_addc_u32 s74, s31, s72
	s_add_u32 s48, s46, s44
	s_addc_u32 s49, s47, s45
	s_add_u32 s72, s73, 0x160000
	s_addc_u32 s73, s74, 0
	s_add_i32 m0, s50, 0xc000
	ds_read_b128 v[182:185], v168
	ds_read_b128 v[186:189], v168 offset:1024
	ds_read_b128 v[190:193], v168 offset:2048
	ds_read_b128 v[194:197], v168 offset:3072
	ds_read_b128 v[198:201], v168 offset:4096
	ds_read_b128 v[202:205], v168 offset:5120
	ds_read_b128 v[206:209], v168 offset:6144
	ds_read_b128 v[210:213], v168 offset:7168
	global_load_lds_dwordx4 v140, s[72:73]
	s_add_i32 m0, s50, 0xe000
	s_nop 0
	global_load_lds_dwordx4 v144, s[72:73]
	s_waitcnt vmcnt(8)
	s_waitcnt lgkmcnt(0)
	s_barrier
	s_setprio 1
	s_waitcnt lgkmcnt(0)
	v_mfma_f32_16x16x32_bf16 v[124:127], v[128:131], v[182:185], v[124:127]
	v_mfma_f32_16x16x32_bf16 v[120:123], v[136:139], v[182:185], v[120:123]
	v_mfma_f32_16x16x32_bf16 v[108:111], v[128:131], v[190:193], v[108:111]
	v_mfma_f32_16x16x32_bf16 v[104:107], v[136:139], v[190:193], v[104:107]
	v_mfma_f32_16x16x32_bf16 v[92:95], v[128:131], v[198:201], v[92:95]
	v_mfma_f32_16x16x32_bf16 v[88:91], v[136:139], v[198:201], v[88:91]
	v_mfma_f32_16x16x32_bf16 v[76:79], v[128:131], v[206:209], v[76:79]
	v_mfma_f32_16x16x32_bf16 v[72:75], v[136:139], v[206:209], v[72:75]
	v_mfma_f32_16x16x32_bf16 v[124:127], v[132:135], v[186:189], v[124:127]
	v_mfma_f32_16x16x32_bf16 v[120:123], v[152:155], v[186:189], v[120:123]
	v_mfma_f32_16x16x32_bf16 v[108:111], v[132:135], v[194:197], v[108:111]
	v_mfma_f32_16x16x32_bf16 v[104:107], v[152:155], v[194:197], v[104:107]
	v_mfma_f32_16x16x32_bf16 v[92:95], v[132:135], v[202:205], v[92:95]
	v_mfma_f32_16x16x32_bf16 v[88:91], v[152:155], v[202:205], v[88:91]
	v_mfma_f32_16x16x32_bf16 v[76:79], v[132:135], v[210:213], v[76:79]
	v_mfma_f32_16x16x32_bf16 v[72:75], v[152:155], v[210:213], v[72:75]
	s_setprio 0
	s_setprio 1
	v_mfma_f32_16x16x32_bf16 v[116:119], v[156:159], v[182:185], v[116:119]
	v_mfma_f32_16x16x32_bf16 v[112:115], v[174:177], v[182:185], v[112:115]
	v_mfma_f32_16x16x32_bf16 v[100:103], v[156:159], v[190:193], v[100:103]
	v_mfma_f32_16x16x32_bf16 v[96:99], v[174:177], v[190:193], v[96:99]
	v_mfma_f32_16x16x32_bf16 v[84:87], v[156:159], v[198:201], v[84:87]
	v_mfma_f32_16x16x32_bf16 v[80:83], v[174:177], v[198:201], v[80:83]
	v_mfma_f32_16x16x32_bf16 v[68:71], v[156:159], v[206:209], v[68:71]
	v_mfma_f32_16x16x32_bf16 v[64:67], v[174:177], v[206:209], v[64:67]
	v_mfma_f32_16x16x32_bf16 v[116:119], v[170:173], v[186:189], v[116:119]
	v_mfma_f32_16x16x32_bf16 v[112:115], v[178:181], v[186:189], v[112:115]
	v_mfma_f32_16x16x32_bf16 v[100:103], v[170:173], v[194:197], v[100:103]
	v_mfma_f32_16x16x32_bf16 v[96:99], v[178:181], v[194:197], v[96:99]
	v_mfma_f32_16x16x32_bf16 v[84:87], v[170:173], v[202:205], v[84:87]
	v_mfma_f32_16x16x32_bf16 v[80:83], v[178:181], v[202:205], v[80:83]
	v_mfma_f32_16x16x32_bf16 v[68:71], v[170:173], v[210:213], v[68:71]
	v_mfma_f32_16x16x32_bf16 v[64:67], v[178:181], v[210:213], v[64:67]
	s_setprio 0
	s_barrier
	s_add_i32 s72, s59, s33
	s_mov_b32 m0, s72
	ds_read_b128 v[182:185], v168 offset:16384
	ds_read_b128 v[186:189], v168 offset:17408
	ds_read_b128 v[190:193], v168 offset:18432
	ds_read_b128 v[194:197], v168 offset:19456
	ds_read_b128 v[198:201], v168 offset:20480
	ds_read_b128 v[202:205], v168 offset:21504
	ds_read_b128 v[206:209], v168 offset:22528
	ds_read_b128 v[210:213], v168 offset:23552
	global_load_lds_dwordx4 v142, s[42:43]
	s_add_i32 m0, s72, 0x2000
	s_add_u32 s72, s42, 0x160000
	s_addc_u32 s73, s43, 0
	s_add_i32 s74, s60, s33
	global_load_lds_dwordx4 v146, s[42:43]
	s_mov_b32 m0, s74
	s_nop 0
	global_load_lds_dwordx4 v142, s[72:73]
	s_add_i32 m0, s74, 0x2000
	s_nop 0
	global_load_lds_dwordx4 v146, s[72:73]
	s_mov_b32 m0, s50
	s_nop 0
	global_load_lds_dwordx4 v140, s[46:47]
	s_mov_b32 m0, s51
	s_nop 0
	global_load_lds_dwordx4 v144, s[46:47]
	s_waitcnt vmcnt(8)
	s_waitcnt lgkmcnt(0)
	s_barrier
	s_setprio 1
	s_waitcnt lgkmcnt(0)
	v_mfma_f32_16x16x32_bf16 v[60:63], v[128:131], v[182:185], v[60:63]
	v_mfma_f32_16x16x32_bf16 v[56:59], v[136:139], v[182:185], v[56:59]
	v_mfma_f32_16x16x32_bf16 v[44:47], v[128:131], v[190:193], v[44:47]
	v_mfma_f32_16x16x32_bf16 v[40:43], v[136:139], v[190:193], v[40:43]
	v_mfma_f32_16x16x32_bf16 v[28:31], v[128:131], v[198:201], v[28:31]
	v_mfma_f32_16x16x32_bf16 v[24:27], v[136:139], v[198:201], v[24:27]
	v_mfma_f32_16x16x32_bf16 v[12:15], v[128:131], v[206:209], v[12:15]
	v_mfma_f32_16x16x32_bf16 v[8:11], v[136:139], v[206:209], v[8:11]
	v_mfma_f32_16x16x32_bf16 v[60:63], v[132:135], v[186:189], v[60:63]
	v_mfma_f32_16x16x32_bf16 v[56:59], v[152:155], v[186:189], v[56:59]
	v_mfma_f32_16x16x32_bf16 v[44:47], v[132:135], v[194:197], v[44:47]
	v_mfma_f32_16x16x32_bf16 v[40:43], v[152:155], v[194:197], v[40:43]
	v_mfma_f32_16x16x32_bf16 v[28:31], v[132:135], v[202:205], v[28:31]
	v_mfma_f32_16x16x32_bf16 v[24:27], v[152:155], v[202:205], v[24:27]
	v_mfma_f32_16x16x32_bf16 v[12:15], v[132:135], v[210:213], v[12:15]
	v_mfma_f32_16x16x32_bf16 v[8:11], v[152:155], v[210:213], v[8:11]
	s_setprio 0
	s_setprio 1
	v_mfma_f32_16x16x32_bf16 v[52:55], v[156:159], v[182:185], v[52:55]
	v_mfma_f32_16x16x32_bf16 v[48:51], v[174:177], v[182:185], v[48:51]
	v_mfma_f32_16x16x32_bf16 v[36:39], v[156:159], v[190:193], v[36:39]
	v_mfma_f32_16x16x32_bf16 v[32:35], v[174:177], v[190:193], v[32:35]
	v_mfma_f32_16x16x32_bf16 v[20:23], v[156:159], v[198:201], v[20:23]
	v_mfma_f32_16x16x32_bf16 v[16:19], v[174:177], v[198:201], v[16:19]
	v_mfma_f32_16x16x32_bf16 v[4:7], v[156:159], v[206:209], v[4:7]
	v_mfma_f32_16x16x32_bf16 v[0:3], v[174:177], v[206:209], v[0:3]
	v_mfma_f32_16x16x32_bf16 v[52:55], v[170:173], v[186:189], v[52:55]
	v_mfma_f32_16x16x32_bf16 v[48:51], v[178:181], v[186:189], v[48:51]
	v_mfma_f32_16x16x32_bf16 v[36:39], v[170:173], v[194:197], v[36:39]
	v_mfma_f32_16x16x32_bf16 v[32:35], v[178:181], v[194:197], v[32:35]
	v_mfma_f32_16x16x32_bf16 v[20:23], v[170:173], v[202:205], v[20:23]
	v_mfma_f32_16x16x32_bf16 v[16:19], v[178:181], v[202:205], v[16:19]
	v_mfma_f32_16x16x32_bf16 v[4:7], v[170:173], v[210:213], v[4:7]
	v_mfma_f32_16x16x32_bf16 v[0:3], v[178:181], v[210:213], v[0:3]
	s_setprio 0
	s_barrier
; #define PG8_STAGE(bufoff, gbase, voff) do { _Pragma("unroll") for (int _i = 0; _i < 2; ++_i) \
;         __builtin_amdgcn_global_load_lds((const unsigned*)((const char*)(gbase) + (voff)[_i]), (LAS unsigned*)(lds + (bufoff) + ldsw + _i * 8192), 16, 0, 0); } while (0)
; #define PG8_LDA(dst, b, h) do { _Pragma("unroll") for (int m = 0; m < 4; ++m) _Pragma("unroll") for (int k = 0; k < 2; ++k) dst[m][k] = *(const LAS bf16x8*)(lds + PG8_SA(b, h) + aoff + m * 2048 + k * 1024); } while (0)
; #define PG8_LDB(dst, b, h) do { _Pragma("unroll") for (int n = 0; n < 2; ++n) _Pragma("unroll") for (int k = 0; k < 2; ++k) dst[n][k] = *(const LAS bf16x8*)(lds + PG8_SB(b, h) + boff + n * 2048 + k * 1024); } while (0)
; #define PG8_MMA(ai, bj, At, Bt) do { __builtin_amdgcn_s_setprio(1); _Pragma("unroll") for (int m = 0; m < 4; ++m) _Pragma("unroll") for (int n = 0; n < 2; ++n) _Pragma("unroll") for (int k = 0; k < 2; ++k) \
;         acc[ai][bj][m][n] = __builtin_amdgcn_mfma_f32_16x16x32_bf16(Bt[n][k], At[m][k], acc[ai][bj][m][n], 0, 0, 0); __builtin_amdgcn_s_setprio(0); } while (0)
; #define PG8_WAIT_V(n) asm volatile("s_waitcnt vmcnt(" #n ")" ::: "memory")
; #define PG8_WAIT_L(n) asm volatile("s_waitcnt lgkmcnt(" #n ")" ::: "memory")
; #define PG8_BAR __builtin_amdgcn_s_barrier()
; #define PG8_SCHED __builtin_amdgcn_sched_barrier(0)
; template <class Epi>
; __device__ __forceinline__ void gemm_phase(LAS unsigned char* lds, const Gemm g, const StaticOrder S, const Epi E) {
;     ...
;             PG8_LDB(B0, 1, 0); PG8_LDB(B1, 1, 1); PG8_SCHED; PG8_LDA(At, 1, 0); PG8_STAGE(PG8_SA(0, 1), a2 + hstepA, voffA);
;             PG8_WAIT_V(8); PG8_WAIT_L(0); PG8_BAR; PG8_MMA(0, 0, At, B0); PG8_MMA(0, 1, At, B1); PG8_BAR; PG8_SCHED;
;             PG8_LDA(At, 1, 1); PG8_STAGE(PG8_SB(1, 0), b3, voffB); PG8_STAGE(PG8_SB(1, 1), b3 + hstepB, voffB); PG8_STAGE(PG8_SA(1, 0), a3, voffA);
;             PG8_WAIT_V(8); PG8_WAIT_L(0); PG8_BAR; PG8_MMA(1, 0, At, B0); PG8_MMA(1, 1, At, B1); PG8_BAR; PG8_SCHED;
;         }
	s_add_i32 s72, 0, 0x18000
	s_add_i32 s73, 0, 0x1c000
	v_add_u32_e32 v152, s72, v166
	v_add_u32_e32 v178, s73, v166
	ds_read_b128 v[128:131], v152
	ds_read_b128 v[132:135], v152 offset:1024
	ds_read_b128 v[136:139], v152 offset:2048
	ds_read_b128 v[152:155], v152 offset:3072
	ds_read_b128 v[156:159], v178
	ds_read_b128 v[170:173], v178 offset:1024
	ds_read_b128 v[174:177], v178 offset:2048
	ds_read_b128 v[178:181], v178 offset:3072
	s_add_u32 s46, s46, 0x160000
	s_addc_u32 s47, s47, 0
	s_mov_b32 m0, s52
	ds_read_b128 v[182:185], v168 offset:32768
	ds_read_b128 v[186:189], v168 offset:33792
	ds_read_b128 v[190:193], v168 offset:34816
	ds_read_b128 v[194:197], v168 offset:35840
	ds_read_b128 v[198:201], v168 offset:36864
	ds_read_b128 v[202:205], v168 offset:37888
	ds_read_b128 v[206:209], v168 offset:38912
	ds_read_b128 v[210:213], v168 offset:39936
	global_load_lds_dwordx4 v140, s[46:47]
	s_mov_b32 m0, s53
	s_nop 0
	global_load_lds_dwordx4 v144, s[46:47]
	s_waitcnt vmcnt(8)
	s_waitcnt lgkmcnt(0)
	s_barrier
	s_setprio 1
	s_waitcnt lgkmcnt(0)
	v_mfma_f32_16x16x32_bf16 v[124:127], v[128:131], v[182:185], v[124:127]
	v_mfma_f32_16x16x32_bf16 v[120:123], v[136:139], v[182:185], v[120:123]
	v_mfma_f32_16x16x32_bf16 v[108:111], v[128:131], v[190:193], v[108:111]
	v_mfma_f32_16x16x32_bf16 v[104:107], v[136:139], v[190:193], v[104:107]
	v_mfma_f32_16x16x32_bf16 v[92:95], v[128:131], v[198:201], v[92:95]
	v_mfma_f32_16x16x32_bf16 v[88:91], v[136:139], v[198:201], v[88:91]
	v_mfma_f32_16x16x32_bf16 v[76:79], v[128:131], v[206:209], v[76:79]
	v_mfma_f32_16x16x32_bf16 v[72:75], v[136:139], v[206:209], v[72:75]
	v_mfma_f32_16x16x32_bf16 v[124:127], v[132:135], v[186:189], v[124:127]
	v_mfma_f32_16x16x32_bf16 v[120:123], v[152:155], v[186:189], v[120:123]
	v_mfma_f32_16x16x32_bf16 v[108:111], v[132:135], v[194:197], v[108:111]
	v_mfma_f32_16x16x32_bf16 v[104:107], v[152:155], v[194:197], v[104:107]
	v_mfma_f32_16x16x32_bf16 v[92:95], v[132:135], v[202:205], v[92:95]
	v_mfma_f32_16x16x32_bf16 v[88:91], v[152:155], v[202:205], v[88:91]
	v_mfma_f32_16x16x32_bf16 v[76:79], v[132:135], v[210:213], v[76:79]
	v_mfma_f32_16x16x32_bf16 v[72:75], v[152:155], v[210:213], v[72:75]
	s_setprio 0
	s_setprio 1
	v_mfma_f32_16x16x32_bf16 v[116:119], v[156:159], v[182:185], v[116:119]
	v_mfma_f32_16x16x32_bf16 v[112:115], v[174:177], v[182:185], v[112:115]
	v_mfma_f32_16x16x32_bf16 v[100:103], v[156:159], v[190:193], v[100:103]
	v_mfma_f32_16x16x32_bf16 v[96:99], v[174:177], v[190:193], v[96:99]
	v_mfma_f32_16x16x32_bf16 v[84:87], v[156:159], v[198:201], v[84:87]
	v_mfma_f32_16x16x32_bf16 v[80:83], v[174:177], v[198:201], v[80:83]
	v_mfma_f32_16x16x32_bf16 v[68:71], v[156:159], v[206:209], v[68:71]
	v_mfma_f32_16x16x32_bf16 v[64:67], v[174:177], v[206:209], v[64:67]
	v_mfma_f32_16x16x32_bf16 v[116:119], v[170:173], v[186:189], v[116:119]
	v_mfma_f32_16x16x32_bf16 v[112:115], v[178:181], v[186:189], v[112:115]
	v_mfma_f32_16x16x32_bf16 v[100:103], v[170:173], v[194:197], v[100:103]
	v_mfma_f32_16x16x32_bf16 v[96:99], v[178:181], v[194:197], v[96:99]
	v_mfma_f32_16x16x32_bf16 v[84:87], v[170:173], v[202:205], v[84:87]
	v_mfma_f32_16x16x32_bf16 v[80:83], v[178:181], v[202:205], v[80:83]
	v_mfma_f32_16x16x32_bf16 v[68:71], v[170:173], v[210:213], v[68:71]
	v_mfma_f32_16x16x32_bf16 v[64:67], v[178:181], v[210:213], v[64:67]
	s_setprio 0
	s_barrier
	s_add_u32 s42, s42, s44
	s_addc_u32 s43, s43, s45
	s_add_i32 s44, s72, s33
	s_mov_b32 m0, s44
	ds_read_b128 v[182:185], v168 offset:49152
	ds_read_b128 v[186:189], v168 offset:50176
	ds_read_b128 v[190:193], v168 offset:51200
	ds_read_b128 v[194:197], v168 offset:52224
	ds_read_b128 v[198:201], v168 offset:53248
	ds_read_b128 v[202:205], v168 offset:54272
	ds_read_b128 v[206:209], v168 offset:55296
	ds_read_b128 v[210:213], v168 offset:56320
	global_load_lds_dwordx4 v142, s[42:43]
	s_add_i32 m0, s44, 0x2000
	s_nop 0
	global_load_lds_dwordx4 v146, s[42:43]
	s_add_u32 s42, s42, 0x160000
	s_addc_u32 s43, s43, 0
	s_add_i32 s44, s73, s33
	s_mov_b32 m0, s44
	s_nop 0
	global_load_lds_dwordx4 v142, s[42:43]
	s_add_i32 m0, s44, 0x2000
	s_nop 0
	global_load_lds_dwordx4 v146, s[42:43]
	s_mov_b32 m0, s55
	s_nop 0
	global_load_lds_dwordx4 v140, s[48:49]
	s_mov_b32 m0, s56
	s_nop 0
	global_load_lds_dwordx4 v144, s[48:49]
	s_waitcnt vmcnt(8)
	s_waitcnt lgkmcnt(0)
	s_barrier
	s_setprio 1
	s_waitcnt lgkmcnt(0)
	v_mfma_f32_16x16x32_bf16 v[60:63], v[128:131], v[182:185], v[60:63]
	v_mfma_f32_16x16x32_bf16 v[56:59], v[136:139], v[182:185], v[56:59]
	v_mfma_f32_16x16x32_bf16 v[44:47], v[128:131], v[190:193], v[44:47]
	v_mfma_f32_16x16x32_bf16 v[40:43], v[136:139], v[190:193], v[40:43]
	v_mfma_f32_16x16x32_bf16 v[28:31], v[128:131], v[198:201], v[28:31]
	v_mfma_f32_16x16x32_bf16 v[24:27], v[136:139], v[198:201], v[24:27]
	v_mfma_f32_16x16x32_bf16 v[12:15], v[128:131], v[206:209], v[12:15]
	v_mfma_f32_16x16x32_bf16 v[8:11], v[136:139], v[206:209], v[8:11]
	v_mfma_f32_16x16x32_bf16 v[60:63], v[132:135], v[186:189], v[60:63]
	v_mfma_f32_16x16x32_bf16 v[56:59], v[152:155], v[186:189], v[56:59]
	v_mfma_f32_16x16x32_bf16 v[44:47], v[132:135], v[194:197], v[44:47]
	v_mfma_f32_16x16x32_bf16 v[40:43], v[152:155], v[194:197], v[40:43]
	v_mfma_f32_16x16x32_bf16 v[28:31], v[132:135], v[202:205], v[28:31]
	v_mfma_f32_16x16x32_bf16 v[24:27], v[152:155], v[202:205], v[24:27]
	v_mfma_f32_16x16x32_bf16 v[12:15], v[132:135], v[210:213], v[12:15]
	v_mfma_f32_16x16x32_bf16 v[8:11], v[152:155], v[210:213], v[8:11]
	s_setprio 0
	s_setprio 1
	v_mfma_f32_16x16x32_bf16 v[52:55], v[156:159], v[182:185], v[52:55]
	v_mfma_f32_16x16x32_bf16 v[48:51], v[174:177], v[182:185], v[48:51]
	v_mfma_f32_16x16x32_bf16 v[36:39], v[156:159], v[190:193], v[36:39]
	v_mfma_f32_16x16x32_bf16 v[32:35], v[174:177], v[190:193], v[32:35]
	v_mfma_f32_16x16x32_bf16 v[20:23], v[156:159], v[198:201], v[20:23]
	v_mfma_f32_16x16x32_bf16 v[16:19], v[174:177], v[198:201], v[16:19]
	v_mfma_f32_16x16x32_bf16 v[4:7], v[156:159], v[206:209], v[4:7]
	v_mfma_f32_16x16x32_bf16 v[0:3], v[174:177], v[206:209], v[0:3]
	v_mfma_f32_16x16x32_bf16 v[52:55], v[170:173], v[186:189], v[52:55]
	v_mfma_f32_16x16x32_bf16 v[48:51], v[178:181], v[186:189], v[48:51]
	v_mfma_f32_16x16x32_bf16 v[36:39], v[170:173], v[194:197], v[36:39]
	v_mfma_f32_16x16x32_bf16 v[32:35], v[178:181], v[194:197], v[32:35]
	v_mfma_f32_16x16x32_bf16 v[20:23], v[170:173], v[202:205], v[20:23]
	v_mfma_f32_16x16x32_bf16 v[16:19], v[178:181], v[202:205], v[16:19]
	v_mfma_f32_16x16x32_bf16 v[4:7], v[170:173], v[210:213], v[4:7]
	v_mfma_f32_16x16x32_bf16 v[0:3], v[178:181], v[210:213], v[0:3]
	s_setprio 0
	s_barrier
	s_cmpk_gt_u32 s70, 0x55
	s_mov_b32 s70, s71
	s_cbranch_scc1 .LBB0_943

; #define PG8_STAGE(bufoff, gbase, voff) do { _Pragma("unroll") for (int _i = 0; _i < 2; ++_i) \
;         __builtin_amdgcn_global_load_lds((const unsigned*)((const char*)(gbase) + (voff)[_i]), (LAS unsigned*)(lds + (bufoff) + ldsw + _i * 8192), 16, 0, 0); } while (0)
; #define PG8_LDA(dst, b, h) do { _Pragma("unroll") for (int m = 0; m < 4; ++m) _Pragma("unroll") for (int k = 0; k < 2; ++k) dst[m][k] = *(const LAS bf16x8*)(lds + PG8_SA(b, h) + aoff + m * 2048 + k * 1024); } while (0)
; #define PG8_LDB(dst, b, h) do { _Pragma("unroll") for (int n = 0; n < 2; ++n) _Pragma("unroll") for (int k = 0; k < 2; ++k) dst[n][k] = *(const LAS bf16x8*)(lds + PG8_SB(b, h) + boff + n * 2048 + k * 1024); } while (0)
; #define PG8_MMA(ai, bj, At, Bt) do { __builtin_amdgcn_s_setprio(1); _Pragma("unroll") for (int m = 0; m < 4; ++m) _Pragma("unroll") for (int n = 0; n < 2; ++n) _Pragma("unroll") for (int k = 0; k < 2; ++k) \
;         acc[ai][bj][m][n] = __builtin_amdgcn_mfma_f32_16x16x32_bf16(Bt[n][k], At[m][k], acc[ai][bj][m][n], 0, 0, 0); __builtin_amdgcn_s_setprio(0); } while (0)
; #define PG8_WAIT_V(n) asm volatile("s_waitcnt vmcnt(" #n ")" ::: "memory")
; #define PG8_WAIT_L(n) asm volatile("s_waitcnt lgkmcnt(" #n ")" ::: "memory")
; #define PG8_BAR __builtin_amdgcn_s_barrier()
; #define PG8_SCHED __builtin_amdgcn_sched_barrier(0)
; template <class Epi>
; __device__ __forceinline__ void gemm_phase(LAS unsigned char* lds, const Gemm g, const StaticOrder S, const Epi E) {
;     ...
;             const char* a1 = cA + (long)(t + 1) * ksc;
;             const char* a2 = last ? nA : cA + (long)(t + 2) * ksc; const char* b2 = last ? nB : cB + (long)(t + 2) * ksc;
;             const long ks3 = last ? ksn : ksc;
;             const char* a3 = a2 + ks3; const char* b3 = b2 + ks3;
;             PG8_LDB(B0, 0, 0); PG8_LDB(B1, 0, 1); PG8_SCHED; PG8_LDA(At, 0, 0); PG8_STAGE(PG8_SA(1, 1), a1 + hstepA, voffA);
;             PG8_WAIT_V(8); PG8_WAIT_L(0); PG8_BAR; PG8_MMA(0, 0, At, B0); PG8_MMA(0, 1, At, B1); PG8_BAR; PG8_SCHED;
;             PG8_LDA(At, 0, 1); PG8_STAGE(PG8_SB(0, 0), b2, voffB); PG8_STAGE(PG8_SB(0, 1), b2 + hstepB, voffB); PG8_STAGE(PG8_SA(0, 0), a2, voffA);
;             PG8_WAIT_V(8); PG8_WAIT_L(0); PG8_BAR; PG8_MMA(1, 0, At, B0); PG8_MMA(1, 1, At, B1); PG8_BAR; PG8_SCHED;
.LBB0_1032:
	v_add_u32_e32 v140, s59, v227
	v_add_u32_e32 v156, s60, v227
	ds_read_b128 v[128:131], v140
	ds_read_b128 v[132:135], v140 offset:1024
	ds_read_b128 v[136:139], v140 offset:2048
	ds_read_b128 v[140:143], v140 offset:3072
	ds_read_b128 v[144:147], v156
	ds_read_b128 v[148:151], v156 offset:1024
	ds_read_b128 v[152:155], v156 offset:2048
	ds_read_b128 v[156:159], v156 offset:3072
	s_or_b32 s17, s3, 1
	s_mul_i32 s48, s31, s17
	s_mul_hi_u32 s49, s30, s17
	s_add_i32 s49, s49, s48
	s_mul_i32 s17, s30, s17
	s_add_u32 s17, s28, s17
	s_addc_u32 s63, s29, s49
	s_add_u32 s48, s46, s44
	s_addc_u32 s49, s47, s45
	s_add_u32 s64, s17, 0x80000
	s_addc_u32 s65, s63, 0
	s_add_i32 m0, s25, 0xc000
	ds_read_b128 v[160:163], v229
	ds_read_b128 v[164:167], v229 offset:1024
	ds_read_b128 v[168:171], v229 offset:2048
	ds_read_b128 v[172:175], v229 offset:3072
	ds_read_b128 v[176:179], v229 offset:4096
	ds_read_b128 v[180:183], v229 offset:5120
	ds_read_b128 v[184:187], v229 offset:6144
	ds_read_b128 v[188:191], v229 offset:7168
	global_load_lds_dwordx4 v192, s[64:65]
	s_add_i32 m0, s25, 0xe000
	s_nop 0
	global_load_lds_dwordx4 v196, s[64:65]
	s_waitcnt vmcnt(8)
	s_waitcnt lgkmcnt(0)
	s_barrier
	s_setprio 1
	s_waitcnt lgkmcnt(0)
	v_mfma_f32_16x16x32_bf16 v[124:127], v[128:131], v[160:163], v[124:127]
	v_mfma_f32_16x16x32_bf16 v[120:123], v[136:139], v[160:163], v[120:123]
	v_mfma_f32_16x16x32_bf16 v[108:111], v[128:131], v[168:171], v[108:111]
	v_mfma_f32_16x16x32_bf16 v[104:107], v[136:139], v[168:171], v[104:107]
	v_mfma_f32_16x16x32_bf16 v[92:95], v[128:131], v[176:179], v[92:95]
	v_mfma_f32_16x16x32_bf16 v[88:91], v[136:139], v[176:179], v[88:91]
	v_mfma_f32_16x16x32_bf16 v[76:79], v[128:131], v[184:187], v[76:79]
	v_mfma_f32_16x16x32_bf16 v[72:75], v[136:139], v[184:187], v[72:75]
	v_mfma_f32_16x16x32_bf16 v[124:127], v[132:135], v[164:167], v[124:127]
	v_mfma_f32_16x16x32_bf16 v[120:123], v[140:143], v[164:167], v[120:123]
	v_mfma_f32_16x16x32_bf16 v[108:111], v[132:135], v[172:175], v[108:111]
	v_mfma_f32_16x16x32_bf16 v[104:107], v[140:143], v[172:175], v[104:107]
	v_mfma_f32_16x16x32_bf16 v[92:95], v[132:135], v[180:183], v[92:95]
	v_mfma_f32_16x16x32_bf16 v[88:91], v[140:143], v[180:183], v[88:91]
	v_mfma_f32_16x16x32_bf16 v[76:79], v[132:135], v[188:191], v[76:79]
	v_mfma_f32_16x16x32_bf16 v[72:75], v[140:143], v[188:191], v[72:75]
	s_setprio 0
	s_setprio 1
	v_mfma_f32_16x16x32_bf16 v[116:119], v[144:147], v[160:163], v[116:119]
	v_mfma_f32_16x16x32_bf16 v[112:115], v[152:155], v[160:163], v[112:115]
	v_mfma_f32_16x16x32_bf16 v[100:103], v[144:147], v[168:171], v[100:103]
	v_mfma_f32_16x16x32_bf16 v[96:99], v[152:155], v[168:171], v[96:99]
	v_mfma_f32_16x16x32_bf16 v[84:87], v[144:147], v[176:179], v[84:87]
	v_mfma_f32_16x16x32_bf16 v[80:83], v[152:155], v[176:179], v[80:83]
	v_mfma_f32_16x16x32_bf16 v[68:71], v[144:147], v[184:187], v[68:71]
	v_mfma_f32_16x16x32_bf16 v[64:67], v[152:155], v[184:187], v[64:67]
	v_mfma_f32_16x16x32_bf16 v[116:119], v[148:151], v[164:167], v[116:119]
	v_mfma_f32_16x16x32_bf16 v[112:115], v[156:159], v[164:167], v[112:115]
	v_mfma_f32_16x16x32_bf16 v[100:103], v[148:151], v[172:175], v[100:103]
	v_mfma_f32_16x16x32_bf16 v[96:99], v[156:159], v[172:175], v[96:99]
	v_mfma_f32_16x16x32_bf16 v[84:87], v[148:151], v[180:183], v[84:87]
	v_mfma_f32_16x16x32_bf16 v[80:83], v[156:159], v[180:183], v[80:83]
	v_mfma_f32_16x16x32_bf16 v[68:71], v[148:151], v[188:191], v[68:71]
	v_mfma_f32_16x16x32_bf16 v[64:67], v[156:159], v[188:191], v[64:67]
	s_setprio 0
	s_barrier
	s_add_i32 s17, s59, s33
	s_mov_b32 m0, s17
	ds_read_b128 v[160:163], v229 offset:16384
	ds_read_b128 v[164:167], v229 offset:17408
	ds_read_b128 v[168:171], v229 offset:18432
	ds_read_b128 v[172:175], v229 offset:19456
	ds_read_b128 v[176:179], v229 offset:20480
	ds_read_b128 v[180:183], v229 offset:21504
	ds_read_b128 v[184:187], v229 offset:22528
	ds_read_b128 v[188:191], v229 offset:23552
	global_load_lds_dwordx4 v194, s[42:43]
	s_add_i32 m0, s17, 0x2000
	s_add_u32 s64, s42, 0x80000
	s_addc_u32 s65, s43, 0
	s_add_i32 s17, s60, s33
	global_load_lds_dwordx4 v198, s[42:43]
	s_mov_b32 m0, s17
	s_nop 0
	global_load_lds_dwordx4 v194, s[64:65]
	s_add_i32 m0, s17, 0x2000
	s_nop 0
	global_load_lds_dwordx4 v198, s[64:65]
	s_mov_b32 m0, s25
	s_nop 0
	global_load_lds_dwordx4 v192, s[46:47]
	s_mov_b32 m0, s50
	s_nop 0
	global_load_lds_dwordx4 v196, s[46:47]
	s_waitcnt vmcnt(8)
	s_waitcnt lgkmcnt(0)
	s_barrier
	s_setprio 1
	s_waitcnt lgkmcnt(0)
	v_mfma_f32_16x16x32_bf16 v[60:63], v[128:131], v[160:163], v[60:63]
	v_mfma_f32_16x16x32_bf16 v[56:59], v[136:139], v[160:163], v[56:59]
	v_mfma_f32_16x16x32_bf16 v[44:47], v[128:131], v[168:171], v[44:47]
	v_mfma_f32_16x16x32_bf16 v[40:43], v[136:139], v[168:171], v[40:43]
	v_mfma_f32_16x16x32_bf16 v[28:31], v[128:131], v[176:179], v[28:31]
	v_mfma_f32_16x16x32_bf16 v[24:27], v[136:139], v[176:179], v[24:27]
	v_mfma_f32_16x16x32_bf16 v[12:15], v[128:131], v[184:187], v[12:15]
	v_mfma_f32_16x16x32_bf16 v[8:11], v[136:139], v[184:187], v[8:11]
	v_mfma_f32_16x16x32_bf16 v[60:63], v[132:135], v[164:167], v[60:63]
	v_mfma_f32_16x16x32_bf16 v[56:59], v[140:143], v[164:167], v[56:59]
	v_mfma_f32_16x16x32_bf16 v[44:47], v[132:135], v[172:175], v[44:47]
	v_mfma_f32_16x16x32_bf16 v[40:43], v[140:143], v[172:175], v[40:43]
	v_mfma_f32_16x16x32_bf16 v[28:31], v[132:135], v[180:183], v[28:31]
	v_mfma_f32_16x16x32_bf16 v[24:27], v[140:143], v[180:183], v[24:27]
	v_mfma_f32_16x16x32_bf16 v[12:15], v[132:135], v[188:191], v[12:15]
	v_mfma_f32_16x16x32_bf16 v[8:11], v[140:143], v[188:191], v[8:11]
	s_setprio 0
	s_setprio 1
	v_mfma_f32_16x16x32_bf16 v[52:55], v[144:147], v[160:163], v[52:55]
	v_mfma_f32_16x16x32_bf16 v[48:51], v[152:155], v[160:163], v[48:51]
	v_mfma_f32_16x16x32_bf16 v[36:39], v[144:147], v[168:171], v[36:39]
	v_mfma_f32_16x16x32_bf16 v[32:35], v[152:155], v[168:171], v[32:35]
	v_mfma_f32_16x16x32_bf16 v[20:23], v[144:147], v[176:179], v[20:23]
	v_mfma_f32_16x16x32_bf16 v[16:19], v[152:155], v[176:179], v[16:19]
	v_mfma_f32_16x16x32_bf16 v[4:7], v[144:147], v[184:187], v[4:7]
	v_mfma_f32_16x16x32_bf16 v[0:3], v[152:155], v[184:187], v[0:3]
	v_mfma_f32_16x16x32_bf16 v[52:55], v[148:151], v[164:167], v[52:55]
	v_mfma_f32_16x16x32_bf16 v[48:51], v[156:159], v[164:167], v[48:51]
	v_mfma_f32_16x16x32_bf16 v[36:39], v[148:151], v[172:175], v[36:39]
	v_mfma_f32_16x16x32_bf16 v[32:35], v[156:159], v[172:175], v[32:35]
	v_mfma_f32_16x16x32_bf16 v[20:23], v[148:151], v[180:183], v[20:23]
	v_mfma_f32_16x16x32_bf16 v[16:19], v[156:159], v[180:183], v[16:19]
	v_mfma_f32_16x16x32_bf16 v[4:7], v[148:151], v[188:191], v[4:7]
	v_mfma_f32_16x16x32_bf16 v[0:3], v[156:159], v[188:191], v[0:3]
	s_setprio 0
	s_barrier
; #define PG8_STAGE(bufoff, gbase, voff) do { _Pragma("unroll") for (int _i = 0; _i < 2; ++_i) \
;         __builtin_amdgcn_global_load_lds((const unsigned*)((const char*)(gbase) + (voff)[_i]), (LAS unsigned*)(lds + (bufoff) + ldsw + _i * 8192), 16, 0, 0); } while (0)
; #define PG8_LDA(dst, b, h) do { _Pragma("unroll") for (int m = 0; m < 4; ++m) _Pragma("unroll") for (int k = 0; k < 2; ++k) dst[m][k] = *(const LAS bf16x8*)(lds + PG8_SA(b, h) + aoff + m * 2048 + k * 1024); } while (0)
; #define PG8_LDB(dst, b, h) do { _Pragma("unroll") for (int n = 0; n < 2; ++n) _Pragma("unroll") for (int k = 0; k < 2; ++k) dst[n][k] = *(const LAS bf16x8*)(lds + PG8_SB(b, h) + boff + n * 2048 + k * 1024); } while (0)
; #define PG8_MMA(ai, bj, At, Bt) do { __builtin_amdgcn_s_setprio(1); _Pragma("unroll") for (int m = 0; m < 4; ++m) _Pragma("unroll") for (int n = 0; n < 2; ++n) _Pragma("unroll") for (int k = 0; k < 2; ++k) \
;         acc[ai][bj][m][n] = __builtin_amdgcn_mfma_f32_16x16x32_bf16(Bt[n][k], At[m][k], acc[ai][bj][m][n], 0, 0, 0); __builtin_amdgcn_s_setprio(0); } while (0)
; #define PG8_WAIT_V(n) asm volatile("s_waitcnt vmcnt(" #n ")" ::: "memory")
; #define PG8_WAIT_L(n) asm volatile("s_waitcnt lgkmcnt(" #n ")" ::: "memory")
; #define PG8_BAR __builtin_amdgcn_s_barrier()
; #define PG8_SCHED __builtin_amdgcn_sched_barrier(0)
; template <class Epi>
; __device__ __forceinline__ void gemm_phase(LAS unsigned char* lds, const Gemm g, const StaticOrder S, const Epi E) {
;     ...
;             PG8_LDB(B0, 1, 0); PG8_LDB(B1, 1, 1); PG8_SCHED; PG8_LDA(At, 1, 0); PG8_STAGE(PG8_SA(0, 1), a2 + hstepA, voffA);
;             PG8_WAIT_V(8); PG8_WAIT_L(0); PG8_BAR; PG8_MMA(0, 0, At, B0); PG8_MMA(0, 1, At, B1); PG8_BAR; PG8_SCHED;
;             PG8_LDA(At, 1, 1); PG8_STAGE(PG8_SB(1, 0), b3, voffB); PG8_STAGE(PG8_SB(1, 1), b3 + hstepB, voffB); PG8_STAGE(PG8_SA(1, 0), a3, voffA);
;             PG8_WAIT_V(8); PG8_WAIT_L(0); PG8_BAR; PG8_MMA(1, 0, At, B0); PG8_MMA(1, 1, At, B1); PG8_BAR; PG8_SCHED;
;         }
	s_add_i32 s17, 0, 0x18000
	s_add_i32 s63, 0, 0x1c000
	v_add_u32_e32 v140, s17, v227
	v_add_u32_e32 v156, s63, v227
	ds_read_b128 v[128:131], v140
	ds_read_b128 v[132:135], v140 offset:1024
	ds_read_b128 v[136:139], v140 offset:2048
	ds_read_b128 v[140:143], v140 offset:3072
	ds_read_b128 v[144:147], v156
	ds_read_b128 v[148:151], v156 offset:1024
	ds_read_b128 v[152:155], v156 offset:2048
	ds_read_b128 v[156:159], v156 offset:3072
	s_add_u32 s46, s46, 0x80000
	s_addc_u32 s47, s47, 0
	s_mov_b32 m0, s51
	ds_read_b128 v[160:163], v229 offset:32768
	ds_read_b128 v[164:167], v229 offset:33792
	ds_read_b128 v[168:171], v229 offset:34816
	ds_read_b128 v[172:175], v229 offset:35840
	ds_read_b128 v[176:179], v229 offset:36864
	ds_read_b128 v[180:183], v229 offset:37888
	ds_read_b128 v[184:187], v229 offset:38912
	ds_read_b128 v[188:191], v229 offset:39936
	global_load_lds_dwordx4 v192, s[46:47]
	s_mov_b32 m0, s52
	s_nop 0
	global_load_lds_dwordx4 v196, s[46:47]
	s_waitcnt vmcnt(8)
	s_waitcnt lgkmcnt(0)
	s_barrier
	s_setprio 1
	s_waitcnt lgkmcnt(0)
	v_mfma_f32_16x16x32_bf16 v[124:127], v[128:131], v[160:163], v[124:127]
	v_mfma_f32_16x16x32_bf16 v[120:123], v[136:139], v[160:163], v[120:123]
	v_mfma_f32_16x16x32_bf16 v[108:111], v[128:131], v[168:171], v[108:111]
	v_mfma_f32_16x16x32_bf16 v[104:107], v[136:139], v[168:171], v[104:107]
	v_mfma_f32_16x16x32_bf16 v[92:95], v[128:131], v[176:179], v[92:95]
	v_mfma_f32_16x16x32_bf16 v[88:91], v[136:139], v[176:179], v[88:91]
	v_mfma_f32_16x16x32_bf16 v[76:79], v[128:131], v[184:187], v[76:79]
	v_mfma_f32_16x16x32_bf16 v[72:75], v[136:139], v[184:187], v[72:75]
	v_mfma_f32_16x16x32_bf16 v[124:127], v[132:135], v[164:167], v[124:127]
	v_mfma_f32_16x16x32_bf16 v[120:123], v[140:143], v[164:167], v[120:123]
	v_mfma_f32_16x16x32_bf16 v[108:111], v[132:135], v[172:175], v[108:111]
	v_mfma_f32_16x16x32_bf16 v[104:107], v[140:143], v[172:175], v[104:107]
	v_mfma_f32_16x16x32_bf16 v[92:95], v[132:135], v[180:183], v[92:95]
	v_mfma_f32_16x16x32_bf16 v[88:91], v[140:143], v[180:183], v[88:91]
	v_mfma_f32_16x16x32_bf16 v[76:79], v[132:135], v[188:191], v[76:79]
	v_mfma_f32_16x16x32_bf16 v[72:75], v[140:143], v[188:191], v[72:75]
	s_setprio 0
	s_setprio 1
	v_mfma_f32_16x16x32_bf16 v[116:119], v[144:147], v[160:163], v[116:119]
	v_mfma_f32_16x16x32_bf16 v[112:115], v[152:155], v[160:163], v[112:115]
	v_mfma_f32_16x16x32_bf16 v[100:103], v[144:147], v[168:171], v[100:103]
	v_mfma_f32_16x16x32_bf16 v[96:99], v[152:155], v[168:171], v[96:99]
	v_mfma_f32_16x16x32_bf16 v[84:87], v[144:147], v[176:179], v[84:87]
	v_mfma_f32_16x16x32_bf16 v[80:83], v[152:155], v[176:179], v[80:83]
	v_mfma_f32_16x16x32_bf16 v[68:71], v[144:147], v[184:187], v[68:71]
	v_mfma_f32_16x16x32_bf16 v[64:67], v[152:155], v[184:187], v[64:67]
	v_mfma_f32_16x16x32_bf16 v[116:119], v[148:151], v[164:167], v[116:119]
	v_mfma_f32_16x16x32_bf16 v[112:115], v[156:159], v[164:167], v[112:115]
	v_mfma_f32_16x16x32_bf16 v[100:103], v[148:151], v[172:175], v[100:103]
	v_mfma_f32_16x16x32_bf16 v[96:99], v[156:159], v[172:175], v[96:99]
	v_mfma_f32_16x16x32_bf16 v[84:87], v[148:151], v[180:183], v[84:87]
	v_mfma_f32_16x16x32_bf16 v[80:83], v[156:159], v[180:183], v[80:83]
	v_mfma_f32_16x16x32_bf16 v[68:71], v[148:151], v[188:191], v[68:71]
	v_mfma_f32_16x16x32_bf16 v[64:67], v[156:159], v[188:191], v[64:67]
	s_setprio 0
	s_barrier
	s_add_u32 s42, s42, s44
	s_addc_u32 s43, s43, s45
	s_add_i32 s17, s17, s33
	s_mov_b32 m0, s17
	ds_read_b128 v[160:163], v229 offset:49152
	ds_read_b128 v[164:167], v229 offset:50176
	ds_read_b128 v[168:171], v229 offset:51200
	ds_read_b128 v[172:175], v229 offset:52224
	ds_read_b128 v[176:179], v229 offset:53248
	ds_read_b128 v[180:183], v229 offset:54272
	ds_read_b128 v[184:187], v229 offset:55296
	ds_read_b128 v[188:191], v229 offset:56320
	global_load_lds_dwordx4 v194, s[42:43]
	s_add_i32 m0, s17, 0x2000
	s_nop 0
	global_load_lds_dwordx4 v198, s[42:43]
	s_add_u32 s42, s42, 0x80000
	s_addc_u32 s43, s43, 0
	s_add_i32 s17, s63, s33
	s_mov_b32 m0, s17
	s_nop 0
	global_load_lds_dwordx4 v194, s[42:43]
	s_add_i32 m0, s17, 0x2000
	s_nop 0
	global_load_lds_dwordx4 v198, s[42:43]
	s_mov_b32 m0, s54
	s_nop 0
	global_load_lds_dwordx4 v192, s[48:49]
	s_mov_b32 m0, s55
	s_nop 0
	global_load_lds_dwordx4 v196, s[48:49]
	s_waitcnt vmcnt(8)
	s_waitcnt lgkmcnt(0)
	s_barrier
	s_setprio 1
	s_waitcnt lgkmcnt(0)
	v_mfma_f32_16x16x32_bf16 v[60:63], v[128:131], v[160:163], v[60:63]
	v_mfma_f32_16x16x32_bf16 v[56:59], v[136:139], v[160:163], v[56:59]
	v_mfma_f32_16x16x32_bf16 v[44:47], v[128:131], v[168:171], v[44:47]
	v_mfma_f32_16x16x32_bf16 v[40:43], v[136:139], v[168:171], v[40:43]
	v_mfma_f32_16x16x32_bf16 v[28:31], v[128:131], v[176:179], v[28:31]
	v_mfma_f32_16x16x32_bf16 v[24:27], v[136:139], v[176:179], v[24:27]
	v_mfma_f32_16x16x32_bf16 v[12:15], v[128:131], v[184:187], v[12:15]
	v_mfma_f32_16x16x32_bf16 v[8:11], v[136:139], v[184:187], v[8:11]
	v_mfma_f32_16x16x32_bf16 v[60:63], v[132:135], v[164:167], v[60:63]
	v_mfma_f32_16x16x32_bf16 v[56:59], v[140:143], v[164:167], v[56:59]
	v_mfma_f32_16x16x32_bf16 v[44:47], v[132:135], v[172:175], v[44:47]
	v_mfma_f32_16x16x32_bf16 v[40:43], v[140:143], v[172:175], v[40:43]
	v_mfma_f32_16x16x32_bf16 v[28:31], v[132:135], v[180:183], v[28:31]
	v_mfma_f32_16x16x32_bf16 v[24:27], v[140:143], v[180:183], v[24:27]
	v_mfma_f32_16x16x32_bf16 v[12:15], v[132:135], v[188:191], v[12:15]
	v_mfma_f32_16x16x32_bf16 v[8:11], v[140:143], v[188:191], v[8:11]
	s_setprio 0
	s_setprio 1
	v_mfma_f32_16x16x32_bf16 v[52:55], v[144:147], v[160:163], v[52:55]
	v_mfma_f32_16x16x32_bf16 v[48:51], v[152:155], v[160:163], v[48:51]
	v_mfma_f32_16x16x32_bf16 v[36:39], v[144:147], v[168:171], v[36:39]
	v_mfma_f32_16x16x32_bf16 v[32:35], v[152:155], v[168:171], v[32:35]
	v_mfma_f32_16x16x32_bf16 v[20:23], v[144:147], v[176:179], v[20:23]
	v_mfma_f32_16x16x32_bf16 v[16:19], v[152:155], v[176:179], v[16:19]
	v_mfma_f32_16x16x32_bf16 v[4:7], v[144:147], v[184:187], v[4:7]
	v_mfma_f32_16x16x32_bf16 v[0:3], v[152:155], v[184:187], v[0:3]
	v_mfma_f32_16x16x32_bf16 v[52:55], v[148:151], v[164:167], v[52:55]
	v_mfma_f32_16x16x32_bf16 v[48:51], v[156:159], v[164:167], v[48:51]
	v_mfma_f32_16x16x32_bf16 v[36:39], v[148:151], v[172:175], v[36:39]
	v_mfma_f32_16x16x32_bf16 v[32:35], v[156:159], v[172:175], v[32:35]
	v_mfma_f32_16x16x32_bf16 v[20:23], v[148:151], v[180:183], v[20:23]
	v_mfma_f32_16x16x32_bf16 v[16:19], v[156:159], v[180:183], v[16:19]
	v_mfma_f32_16x16x32_bf16 v[4:7], v[148:151], v[188:191], v[4:7]
	v_mfma_f32_16x16x32_bf16 v[0:3], v[156:159], v[188:191], v[0:3]
	s_setprio 0
	s_barrier
	s_cmp_gt_u32 s3, 29
	s_mov_b32 s3, s15
	s_cbranch_scc1 .LBB0_1037

; #define PG8_STAGE(bufoff, gbase, voff) do { _Pragma("unroll") for (int _i = 0; _i < 2; ++_i) \
;         __builtin_amdgcn_global_load_lds((const unsigned*)((const char*)(gbase) + (voff)[_i]), (LAS unsigned*)(lds + (bufoff) + ldsw + _i * 8192), 16, 0, 0); } while (0)
; #define PG8_LDA(dst, b, h) do { _Pragma("unroll") for (int m = 0; m < 4; ++m) _Pragma("unroll") for (int k = 0; k < 2; ++k) dst[m][k] = *(const LAS bf16x8*)(lds + PG8_SA(b, h) + aoff + m * 2048 + k * 1024); } while (0)
; #define PG8_LDB(dst, b, h) do { _Pragma("unroll") for (int n = 0; n < 2; ++n) _Pragma("unroll") for (int k = 0; k < 2; ++k) dst[n][k] = *(const LAS bf16x8*)(lds + PG8_SB(b, h) + boff + n * 2048 + k * 1024); } while (0)
; #define PG8_MMA(ai, bj, At, Bt) do { __builtin_amdgcn_s_setprio(1); _Pragma("unroll") for (int m = 0; m < 4; ++m) _Pragma("unroll") for (int n = 0; n < 2; ++n) _Pragma("unroll") for (int k = 0; k < 2; ++k) \
;         acc[ai][bj][m][n] = __builtin_amdgcn_mfma_f32_16x16x32_bf16(Bt[n][k], At[m][k], acc[ai][bj][m][n], 0, 0, 0); __builtin_amdgcn_s_setprio(0); } while (0)
; #define PG8_WAIT_V(n) asm volatile("s_waitcnt vmcnt(" #n ")" ::: "memory")
; #define PG8_WAIT_L(n) asm volatile("s_waitcnt lgkmcnt(" #n ")" ::: "memory")
; #define PG8_BAR __builtin_amdgcn_s_barrier()
; #define PG8_SCHED __builtin_amdgcn_sched_barrier(0)
; template <class Epi>
; __device__ __forceinline__ void gemm_phase(LAS unsigned char* lds, const Gemm g, const StaticOrder S, const Epi E) {
;     ...
;             const char* a1 = cA + (long)(t + 1) * ksc;
;             const char* a2 = last ? nA : cA + (long)(t + 2) * ksc; const char* b2 = last ? nB : cB + (long)(t + 2) * ksc;
;             const long ks3 = last ? ksn : ksc;
;             const char* a3 = a2 + ks3; const char* b3 = b2 + ks3;
;             PG8_LDB(B0, 0, 0); PG8_LDB(B1, 0, 1); PG8_SCHED; PG8_LDA(At, 0, 0); PG8_STAGE(PG8_SA(1, 1), a1 + hstepA, voffA);
;             PG8_WAIT_V(8); PG8_WAIT_L(0); PG8_BAR; PG8_MMA(0, 0, At, B0); PG8_MMA(0, 1, At, B1); PG8_BAR; PG8_SCHED;
;             PG8_LDA(At, 0, 1); PG8_STAGE(PG8_SB(0, 0), b2, voffB); PG8_STAGE(PG8_SB(0, 1), b2 + hstepB, voffB); PG8_STAGE(PG8_SA(0, 0), a2, voffA);
;             PG8_WAIT_V(8); PG8_WAIT_L(0); PG8_BAR; PG8_MMA(1, 0, At, B0); PG8_MMA(1, 1, At, B1); PG8_BAR; PG8_SCHED;
.LBB0_1373:
	v_add_u32_e32 v152, s64, v164
	v_add_u32_e32 v176, s65, v164
	ds_read_b128 v[128:131], v152
	ds_read_b128 v[132:135], v152 offset:1024
	ds_read_b128 v[136:139], v152 offset:2048
	ds_read_b128 v[152:155], v152 offset:3072
	ds_read_b128 v[156:159], v176
	ds_read_b128 v[168:171], v176 offset:1024
	ds_read_b128 v[172:175], v176 offset:2048
	ds_read_b128 v[176:179], v176 offset:3072
	s_or_b32 s23, s31, 1
	s_mul_i32 s54, s41, s23
	s_mul_hi_u32 s55, s40, s23
	s_add_i32 s55, s55, s54
	s_mul_i32 s23, s40, s23
	s_add_u32 s23, s38, s23
	s_addc_u32 s71, s39, s55
	s_add_u32 s54, s52, s50
	s_addc_u32 s55, s53, s51
	s_add_u32 s72, s23, 0x80000
	s_addc_u32 s73, s71, 0
	s_add_i32 m0, s35, 0xc000
	ds_read_b128 v[180:183], v166
	ds_read_b128 v[184:187], v166 offset:1024
	ds_read_b128 v[188:191], v166 offset:2048
	ds_read_b128 v[192:195], v166 offset:3072
	ds_read_b128 v[196:199], v166 offset:4096
	ds_read_b128 v[200:203], v166 offset:5120
	ds_read_b128 v[204:207], v166 offset:6144
	ds_read_b128 v[208:211], v166 offset:7168
	global_load_lds_dwordx4 v140, s[72:73]
	s_add_i32 m0, s35, 0xe000
	s_nop 0
	global_load_lds_dwordx4 v144, s[72:73]
	s_waitcnt vmcnt(8)
	s_waitcnt lgkmcnt(0)
	s_barrier
	s_setprio 1
	s_waitcnt lgkmcnt(0)
	v_mfma_f32_16x16x32_bf16 v[124:127], v[128:131], v[180:183], v[124:127]
	v_mfma_f32_16x16x32_bf16 v[120:123], v[136:139], v[180:183], v[120:123]
	v_mfma_f32_16x16x32_bf16 v[108:111], v[128:131], v[188:191], v[108:111]
	v_mfma_f32_16x16x32_bf16 v[104:107], v[136:139], v[188:191], v[104:107]
	v_mfma_f32_16x16x32_bf16 v[92:95], v[128:131], v[196:199], v[92:95]
	v_mfma_f32_16x16x32_bf16 v[88:91], v[136:139], v[196:199], v[88:91]
	v_mfma_f32_16x16x32_bf16 v[76:79], v[128:131], v[204:207], v[76:79]
	v_mfma_f32_16x16x32_bf16 v[72:75], v[136:139], v[204:207], v[72:75]
	v_mfma_f32_16x16x32_bf16 v[124:127], v[132:135], v[184:187], v[124:127]
	v_mfma_f32_16x16x32_bf16 v[120:123], v[152:155], v[184:187], v[120:123]
	v_mfma_f32_16x16x32_bf16 v[108:111], v[132:135], v[192:195], v[108:111]
	v_mfma_f32_16x16x32_bf16 v[104:107], v[152:155], v[192:195], v[104:107]
	v_mfma_f32_16x16x32_bf16 v[92:95], v[132:135], v[200:203], v[92:95]
	v_mfma_f32_16x16x32_bf16 v[88:91], v[152:155], v[200:203], v[88:91]
	v_mfma_f32_16x16x32_bf16 v[76:79], v[132:135], v[208:211], v[76:79]
	v_mfma_f32_16x16x32_bf16 v[72:75], v[152:155], v[208:211], v[72:75]
	s_setprio 0
	s_setprio 1
	v_mfma_f32_16x16x32_bf16 v[116:119], v[156:159], v[180:183], v[116:119]
	v_mfma_f32_16x16x32_bf16 v[112:115], v[172:175], v[180:183], v[112:115]
	v_mfma_f32_16x16x32_bf16 v[100:103], v[156:159], v[188:191], v[100:103]
	v_mfma_f32_16x16x32_bf16 v[96:99], v[172:175], v[188:191], v[96:99]
	v_mfma_f32_16x16x32_bf16 v[84:87], v[156:159], v[196:199], v[84:87]
	v_mfma_f32_16x16x32_bf16 v[80:83], v[172:175], v[196:199], v[80:83]
	v_mfma_f32_16x16x32_bf16 v[68:71], v[156:159], v[204:207], v[68:71]
	v_mfma_f32_16x16x32_bf16 v[64:67], v[172:175], v[204:207], v[64:67]
	v_mfma_f32_16x16x32_bf16 v[116:119], v[168:171], v[184:187], v[116:119]
	v_mfma_f32_16x16x32_bf16 v[112:115], v[176:179], v[184:187], v[112:115]
	v_mfma_f32_16x16x32_bf16 v[100:103], v[168:171], v[192:195], v[100:103]
	v_mfma_f32_16x16x32_bf16 v[96:99], v[176:179], v[192:195], v[96:99]
	v_mfma_f32_16x16x32_bf16 v[84:87], v[168:171], v[200:203], v[84:87]
	v_mfma_f32_16x16x32_bf16 v[80:83], v[176:179], v[200:203], v[80:83]
	v_mfma_f32_16x16x32_bf16 v[68:71], v[168:171], v[208:211], v[68:71]
	v_mfma_f32_16x16x32_bf16 v[64:67], v[176:179], v[208:211], v[64:67]
	s_setprio 0
	s_barrier
	s_add_i32 s23, s64, s33
	s_mov_b32 m0, s23
	ds_read_b128 v[180:183], v166 offset:16384
	ds_read_b128 v[184:187], v166 offset:17408
	ds_read_b128 v[188:191], v166 offset:18432
	ds_read_b128 v[192:195], v166 offset:19456
	ds_read_b128 v[196:199], v166 offset:20480
	ds_read_b128 v[200:203], v166 offset:21504
	ds_read_b128 v[204:207], v166 offset:22528
	ds_read_b128 v[208:211], v166 offset:23552
	global_load_lds_dwordx4 v142, s[48:49]
	s_add_i32 m0, s23, 0x2000
	s_add_u32 s72, s48, 0x80000
	s_addc_u32 s73, s49, 0
	s_add_i32 s23, s65, s33
	global_load_lds_dwordx4 v146, s[48:49]
	s_mov_b32 m0, s23
	s_nop 0
	global_load_lds_dwordx4 v142, s[72:73]
	s_add_i32 m0, s23, 0x2000
	s_nop 0
	global_load_lds_dwordx4 v146, s[72:73]
	s_mov_b32 m0, s35
	s_nop 0
	global_load_lds_dwordx4 v140, s[52:53]
	s_mov_b32 m0, s56
	s_nop 0
	global_load_lds_dwordx4 v144, s[52:53]
	s_waitcnt vmcnt(8)
	s_waitcnt lgkmcnt(0)
	s_barrier
	s_setprio 1
	s_waitcnt lgkmcnt(0)
	v_mfma_f32_16x16x32_bf16 v[60:63], v[128:131], v[180:183], v[60:63]
	v_mfma_f32_16x16x32_bf16 v[56:59], v[136:139], v[180:183], v[56:59]
	v_mfma_f32_16x16x32_bf16 v[44:47], v[128:131], v[188:191], v[44:47]
	v_mfma_f32_16x16x32_bf16 v[40:43], v[136:139], v[188:191], v[40:43]
	v_mfma_f32_16x16x32_bf16 v[28:31], v[128:131], v[196:199], v[28:31]
	v_mfma_f32_16x16x32_bf16 v[24:27], v[136:139], v[196:199], v[24:27]
	v_mfma_f32_16x16x32_bf16 v[12:15], v[128:131], v[204:207], v[12:15]
	v_mfma_f32_16x16x32_bf16 v[8:11], v[136:139], v[204:207], v[8:11]
	v_mfma_f32_16x16x32_bf16 v[60:63], v[132:135], v[184:187], v[60:63]
	v_mfma_f32_16x16x32_bf16 v[56:59], v[152:155], v[184:187], v[56:59]
	v_mfma_f32_16x16x32_bf16 v[44:47], v[132:135], v[192:195], v[44:47]
	v_mfma_f32_16x16x32_bf16 v[40:43], v[152:155], v[192:195], v[40:43]
	v_mfma_f32_16x16x32_bf16 v[28:31], v[132:135], v[200:203], v[28:31]
	v_mfma_f32_16x16x32_bf16 v[24:27], v[152:155], v[200:203], v[24:27]
	v_mfma_f32_16x16x32_bf16 v[12:15], v[132:135], v[208:211], v[12:15]
	v_mfma_f32_16x16x32_bf16 v[8:11], v[152:155], v[208:211], v[8:11]
	s_setprio 0
	s_setprio 1
	v_mfma_f32_16x16x32_bf16 v[52:55], v[156:159], v[180:183], v[52:55]
	v_mfma_f32_16x16x32_bf16 v[48:51], v[172:175], v[180:183], v[48:51]
	v_mfma_f32_16x16x32_bf16 v[36:39], v[156:159], v[188:191], v[36:39]
	v_mfma_f32_16x16x32_bf16 v[32:35], v[172:175], v[188:191], v[32:35]
	v_mfma_f32_16x16x32_bf16 v[20:23], v[156:159], v[196:199], v[20:23]
	v_mfma_f32_16x16x32_bf16 v[16:19], v[172:175], v[196:199], v[16:19]
	v_mfma_f32_16x16x32_bf16 v[4:7], v[156:159], v[204:207], v[4:7]
	v_mfma_f32_16x16x32_bf16 v[0:3], v[172:175], v[204:207], v[0:3]
	v_mfma_f32_16x16x32_bf16 v[52:55], v[168:171], v[184:187], v[52:55]
	v_mfma_f32_16x16x32_bf16 v[48:51], v[176:179], v[184:187], v[48:51]
	v_mfma_f32_16x16x32_bf16 v[36:39], v[168:171], v[192:195], v[36:39]
	v_mfma_f32_16x16x32_bf16 v[32:35], v[176:179], v[192:195], v[32:35]
	v_mfma_f32_16x16x32_bf16 v[20:23], v[168:171], v[200:203], v[20:23]
	v_mfma_f32_16x16x32_bf16 v[16:19], v[176:179], v[200:203], v[16:19]
	v_mfma_f32_16x16x32_bf16 v[4:7], v[168:171], v[208:211], v[4:7]
	v_mfma_f32_16x16x32_bf16 v[0:3], v[176:179], v[208:211], v[0:3]
	s_setprio 0
	s_barrier
; #define PG8_STAGE(bufoff, gbase, voff) do { _Pragma("unroll") for (int _i = 0; _i < 2; ++_i) \
;         __builtin_amdgcn_global_load_lds((const unsigned*)((const char*)(gbase) + (voff)[_i]), (LAS unsigned*)(lds + (bufoff) + ldsw + _i * 8192), 16, 0, 0); } while (0)
; #define PG8_LDA(dst, b, h) do { _Pragma("unroll") for (int m = 0; m < 4; ++m) _Pragma("unroll") for (int k = 0; k < 2; ++k) dst[m][k] = *(const LAS bf16x8*)(lds + PG8_SA(b, h) + aoff + m * 2048 + k * 1024); } while (0)
; #define PG8_LDB(dst, b, h) do { _Pragma("unroll") for (int n = 0; n < 2; ++n) _Pragma("unroll") for (int k = 0; k < 2; ++k) dst[n][k] = *(const LAS bf16x8*)(lds + PG8_SB(b, h) + boff + n * 2048 + k * 1024); } while (0)
; #define PG8_MMA(ai, bj, At, Bt) do { __builtin_amdgcn_s_setprio(1); _Pragma("unroll") for (int m = 0; m < 4; ++m) _Pragma("unroll") for (int n = 0; n < 2; ++n) _Pragma("unroll") for (int k = 0; k < 2; ++k) \
;         acc[ai][bj][m][n] = __builtin_amdgcn_mfma_f32_16x16x32_bf16(Bt[n][k], At[m][k], acc[ai][bj][m][n], 0, 0, 0); __builtin_amdgcn_s_setprio(0); } while (0)
; #define PG8_WAIT_V(n) asm volatile("s_waitcnt vmcnt(" #n ")" ::: "memory")
; #define PG8_WAIT_L(n) asm volatile("s_waitcnt lgkmcnt(" #n ")" ::: "memory")
; #define PG8_BAR __builtin_amdgcn_s_barrier()
; #define PG8_SCHED __builtin_amdgcn_sched_barrier(0)
; template <class Epi>
; __device__ __forceinline__ void gemm_phase(LAS unsigned char* lds, const Gemm g, const StaticOrder S, const Epi E) {
;     ...
;             PG8_LDB(B0, 1, 0); PG8_LDB(B1, 1, 1); PG8_SCHED; PG8_LDA(At, 1, 0); PG8_STAGE(PG8_SA(0, 1), a2 + hstepA, voffA);
;             PG8_WAIT_V(8); PG8_WAIT_L(0); PG8_BAR; PG8_MMA(0, 0, At, B0); PG8_MMA(0, 1, At, B1); PG8_BAR; PG8_SCHED;
;             PG8_LDA(At, 1, 1); PG8_STAGE(PG8_SB(1, 0), b3, voffB); PG8_STAGE(PG8_SB(1, 1), b3 + hstepB, voffB); PG8_STAGE(PG8_SA(1, 0), a3, voffA);
;             PG8_WAIT_V(8); PG8_WAIT_L(0); PG8_BAR; PG8_MMA(1, 0, At, B0); PG8_MMA(1, 1, At, B1); PG8_BAR; PG8_SCHED;
;         }
	s_add_i32 s23, 0, 0x18000
	s_add_i32 s71, 0, 0x1c000
	v_add_u32_e32 v152, s23, v164
	v_add_u32_e32 v176, s71, v164
	ds_read_b128 v[128:131], v152
	ds_read_b128 v[132:135], v152 offset:1024
	ds_read_b128 v[136:139], v152 offset:2048
	ds_read_b128 v[152:155], v152 offset:3072
	ds_read_b128 v[156:159], v176
	ds_read_b128 v[168:171], v176 offset:1024
	ds_read_b128 v[172:175], v176 offset:2048
	ds_read_b128 v[176:179], v176 offset:3072
	s_add_u32 s52, s52, 0x80000
	s_addc_u32 s53, s53, 0
	s_mov_b32 m0, s57
	ds_read_b128 v[180:183], v166 offset:32768
	ds_read_b128 v[184:187], v166 offset:33792
	ds_read_b128 v[188:191], v166 offset:34816
	ds_read_b128 v[192:195], v166 offset:35840
	ds_read_b128 v[196:199], v166 offset:36864
	ds_read_b128 v[200:203], v166 offset:37888
	ds_read_b128 v[204:207], v166 offset:38912
	ds_read_b128 v[208:211], v166 offset:39936
	global_load_lds_dwordx4 v140, s[52:53]
	s_mov_b32 m0, s58
	s_nop 0
	global_load_lds_dwordx4 v144, s[52:53]
	s_waitcnt vmcnt(8)
	s_waitcnt lgkmcnt(0)
	s_barrier
	s_setprio 1
	s_waitcnt lgkmcnt(0)
	v_mfma_f32_16x16x32_bf16 v[124:127], v[128:131], v[180:183], v[124:127]
	v_mfma_f32_16x16x32_bf16 v[120:123], v[136:139], v[180:183], v[120:123]
	v_mfma_f32_16x16x32_bf16 v[108:111], v[128:131], v[188:191], v[108:111]
	v_mfma_f32_16x16x32_bf16 v[104:107], v[136:139], v[188:191], v[104:107]
	v_mfma_f32_16x16x32_bf16 v[92:95], v[128:131], v[196:199], v[92:95]
	v_mfma_f32_16x16x32_bf16 v[88:91], v[136:139], v[196:199], v[88:91]
	v_mfma_f32_16x16x32_bf16 v[76:79], v[128:131], v[204:207], v[76:79]
	v_mfma_f32_16x16x32_bf16 v[72:75], v[136:139], v[204:207], v[72:75]
	v_mfma_f32_16x16x32_bf16 v[124:127], v[132:135], v[184:187], v[124:127]
	v_mfma_f32_16x16x32_bf16 v[120:123], v[152:155], v[184:187], v[120:123]
	v_mfma_f32_16x16x32_bf16 v[108:111], v[132:135], v[192:195], v[108:111]
	v_mfma_f32_16x16x32_bf16 v[104:107], v[152:155], v[192:195], v[104:107]
	v_mfma_f32_16x16x32_bf16 v[92:95], v[132:135], v[200:203], v[92:95]
	v_mfma_f32_16x16x32_bf16 v[88:91], v[152:155], v[200:203], v[88:91]
	v_mfma_f32_16x16x32_bf16 v[76:79], v[132:135], v[208:211], v[76:79]
	v_mfma_f32_16x16x32_bf16 v[72:75], v[152:155], v[208:211], v[72:75]
	s_setprio 0
	s_setprio 1
	v_mfma_f32_16x16x32_bf16 v[116:119], v[156:159], v[180:183], v[116:119]
	v_mfma_f32_16x16x32_bf16 v[112:115], v[172:175], v[180:183], v[112:115]
	v_mfma_f32_16x16x32_bf16 v[100:103], v[156:159], v[188:191], v[100:103]
	v_mfma_f32_16x16x32_bf16 v[96:99], v[172:175], v[188:191], v[96:99]
	v_mfma_f32_16x16x32_bf16 v[84:87], v[156:159], v[196:199], v[84:87]
	v_mfma_f32_16x16x32_bf16 v[80:83], v[172:175], v[196:199], v[80:83]
	v_mfma_f32_16x16x32_bf16 v[68:71], v[156:159], v[204:207], v[68:71]
	v_mfma_f32_16x16x32_bf16 v[64:67], v[172:175], v[204:207], v[64:67]
	v_mfma_f32_16x16x32_bf16 v[116:119], v[168:171], v[184:187], v[116:119]
	v_mfma_f32_16x16x32_bf16 v[112:115], v[176:179], v[184:187], v[112:115]
	v_mfma_f32_16x16x32_bf16 v[100:103], v[168:171], v[192:195], v[100:103]
	v_mfma_f32_16x16x32_bf16 v[96:99], v[176:179], v[192:195], v[96:99]
	v_mfma_f32_16x16x32_bf16 v[84:87], v[168:171], v[200:203], v[84:87]
	v_mfma_f32_16x16x32_bf16 v[80:83], v[176:179], v[200:203], v[80:83]
	v_mfma_f32_16x16x32_bf16 v[68:71], v[168:171], v[208:211], v[68:71]
	v_mfma_f32_16x16x32_bf16 v[64:67], v[176:179], v[208:211], v[64:67]
	s_setprio 0
	s_barrier
	s_add_u32 s48, s48, s50
	s_addc_u32 s49, s49, s51
	s_add_i32 s23, s23, s33
	s_mov_b32 m0, s23
	ds_read_b128 v[180:183], v166 offset:49152
	ds_read_b128 v[184:187], v166 offset:50176
	ds_read_b128 v[188:191], v166 offset:51200
	ds_read_b128 v[192:195], v166 offset:52224
	ds_read_b128 v[196:199], v166 offset:53248
	ds_read_b128 v[200:203], v166 offset:54272
	ds_read_b128 v[204:207], v166 offset:55296
	ds_read_b128 v[208:211], v166 offset:56320
	global_load_lds_dwordx4 v142, s[48:49]
	s_add_i32 m0, s23, 0x2000
	s_nop 0
	global_load_lds_dwordx4 v146, s[48:49]
	s_add_u32 s48, s48, 0x80000
	s_addc_u32 s49, s49, 0
	s_add_i32 s23, s71, s33
	s_mov_b32 m0, s23
	s_nop 0
	global_load_lds_dwordx4 v142, s[48:49]
	s_add_i32 m0, s23, 0x2000
	s_nop 0
	global_load_lds_dwordx4 v146, s[48:49]
	s_mov_b32 m0, s60
	s_nop 0
	global_load_lds_dwordx4 v140, s[54:55]
	s_mov_b32 m0, s61
	s_nop 0
	global_load_lds_dwordx4 v144, s[54:55]
	s_waitcnt vmcnt(8)
	s_waitcnt lgkmcnt(0)
	s_barrier
	s_setprio 1
	s_waitcnt lgkmcnt(0)
	v_mfma_f32_16x16x32_bf16 v[60:63], v[128:131], v[180:183], v[60:63]
	v_mfma_f32_16x16x32_bf16 v[56:59], v[136:139], v[180:183], v[56:59]
	v_mfma_f32_16x16x32_bf16 v[44:47], v[128:131], v[188:191], v[44:47]
	v_mfma_f32_16x16x32_bf16 v[40:43], v[136:139], v[188:191], v[40:43]
	v_mfma_f32_16x16x32_bf16 v[28:31], v[128:131], v[196:199], v[28:31]
	v_mfma_f32_16x16x32_bf16 v[24:27], v[136:139], v[196:199], v[24:27]
	v_mfma_f32_16x16x32_bf16 v[12:15], v[128:131], v[204:207], v[12:15]
	v_mfma_f32_16x16x32_bf16 v[8:11], v[136:139], v[204:207], v[8:11]
	v_mfma_f32_16x16x32_bf16 v[60:63], v[132:135], v[184:187], v[60:63]
	v_mfma_f32_16x16x32_bf16 v[56:59], v[152:155], v[184:187], v[56:59]
	v_mfma_f32_16x16x32_bf16 v[44:47], v[132:135], v[192:195], v[44:47]
	v_mfma_f32_16x16x32_bf16 v[40:43], v[152:155], v[192:195], v[40:43]
	v_mfma_f32_16x16x32_bf16 v[28:31], v[132:135], v[200:203], v[28:31]
	v_mfma_f32_16x16x32_bf16 v[24:27], v[152:155], v[200:203], v[24:27]
	v_mfma_f32_16x16x32_bf16 v[12:15], v[132:135], v[208:211], v[12:15]
	v_mfma_f32_16x16x32_bf16 v[8:11], v[152:155], v[208:211], v[8:11]
	s_setprio 0
	s_setprio 1
	v_mfma_f32_16x16x32_bf16 v[52:55], v[156:159], v[180:183], v[52:55]
	v_mfma_f32_16x16x32_bf16 v[48:51], v[172:175], v[180:183], v[48:51]
	v_mfma_f32_16x16x32_bf16 v[36:39], v[156:159], v[188:191], v[36:39]
	v_mfma_f32_16x16x32_bf16 v[32:35], v[172:175], v[188:191], v[32:35]
	v_mfma_f32_16x16x32_bf16 v[20:23], v[156:159], v[196:199], v[20:23]
	v_mfma_f32_16x16x32_bf16 v[16:19], v[172:175], v[196:199], v[16:19]
	v_mfma_f32_16x16x32_bf16 v[4:7], v[156:159], v[204:207], v[4:7]
	v_mfma_f32_16x16x32_bf16 v[0:3], v[172:175], v[204:207], v[0:3]
	v_mfma_f32_16x16x32_bf16 v[52:55], v[168:171], v[184:187], v[52:55]
	v_mfma_f32_16x16x32_bf16 v[48:51], v[176:179], v[184:187], v[48:51]
	v_mfma_f32_16x16x32_bf16 v[36:39], v[168:171], v[192:195], v[36:39]
	v_mfma_f32_16x16x32_bf16 v[32:35], v[176:179], v[192:195], v[32:35]
	v_mfma_f32_16x16x32_bf16 v[20:23], v[168:171], v[200:203], v[20:23]
	v_mfma_f32_16x16x32_bf16 v[16:19], v[176:179], v[200:203], v[16:19]
	v_mfma_f32_16x16x32_bf16 v[4:7], v[168:171], v[208:211], v[4:7]
	v_mfma_f32_16x16x32_bf16 v[0:3], v[176:179], v[208:211], v[0:3]
	s_setprio 0
	s_barrier
	s_cmp_gt_u32 s31, 29
	s_mov_b32 s31, s21
	s_cbranch_scc1 .LBB0_1378

; #define PG8_STAGE(bufoff, gbase, voff) do { _Pragma("unroll") for (int _i = 0; _i < 2; ++_i) \
;         __builtin_amdgcn_global_load_lds((const unsigned*)((const char*)(gbase) + (voff)[_i]), (LAS unsigned*)(lds + (bufoff) + ldsw + _i * 8192), 16, 0, 0); } while (0)
; #define PG8_WAIT_V(n) asm volatile("s_waitcnt vmcnt(" #n ")" ::: "memory")
; #define PG8_BAR __builtin_amdgcn_s_barrier()
; template <class Epi>
; __device__ __forceinline__ void gemm_phase(LAS unsigned char* lds, const Gemm g, const StaticOrder S, const Epi E) {
;     ...
;     for (int i = 0; i < 2; ++i) { int R, C; stage_rc(tid * 16 + i * 8192, R, C); const int Rb = Epi::PERM ? ((R & ~31) + perm32(R & 31)) : R;
;         voffA[i] = (unsigned)(R * g.lda + C) * 2u; voffB[i] = (unsigned)(Rb * g.ldb + C) * 2u; }
;     const size_t kstep = (size_t)(BK * 2);
;     const size_t hstepA = (size_t)HALF * g.lda * 2, hstepB = (size_t)HALF * g.ldb * 2;
;     const size_t tstepA = 2 * hstepA, tstepB = 2 * hstepB;
;     const unsigned ldsw = (unsigned)wid * 1024u;
;     const int aoff = lds_byte(wr * 64 + fr, fq * 8), boff = lds_byte(wc * 32 + fr, fq * 8);
;     ...
;     PG8_STAGE(PG8_SB(1, 0), cB + ksc, voffB); PG8_STAGE(PG8_SA(1, 0), cA + ksc, voffA); PG8_STAGE(PG8_SB(1, 1), cB + hstepB + ksc, voffB);
;     PG8_WAIT_V(6); PG8_BAR;
.LBB0_1467:
	s_add_u32 s6, s82, 0x2a9d0000
	s_addc_u32 s7, s83, 0
	s_lshl_b32 s9, s9, 5
	s_mov_b64 s[26:27], 0x80
	s_and_b32 s14, s9, 0x60
	s_add_i32 m0, s21, 0x18000
	v_lshl_add_u64 v[6:7], v[6:7], 0, s[26:27]
	s_lshl_b32 s10, s8, 13
	s_lshl_b32 s9, s14, 7
	s_waitcnt vmcnt(2)
	s_barrier
	global_load_lds_dwordx4 v[6:7], off
	v_lshl_add_u64 v[4:5], v[4:5], 0, s[26:27]
	s_add_i32 m0, s21, 0x1a000
	s_add_i32 s51, s21, 0x8000
	s_add_i32 s52, s21, 0xa000
	global_load_lds_dwordx4 v[4:5], off
	v_lshl_add_u64 v[0:1], v[0:1], 0, s[26:27]
	s_mov_b32 m0, s51
	s_add_u32 s12, s22, 0x80080
	global_load_lds_dwordx4 v[0:1], off
	v_lshl_add_u64 v[0:1], v[2:3], 0, s[26:27]
	s_mov_b32 m0, s52
	s_addc_u32 s13, s23, 0
	global_load_lds_dwordx4 v[0:1], off
	s_add_i32 m0, s21, 0x1c000
	s_nop 0
	global_load_lds_dwordx4 v132, s[12:13]
	s_add_i32 m0, s21, 0x1e000
	v_lshlrev_b32_e32 v2, 2, v224
	global_load_lds_dwordx4 v128, s[12:13]
	v_and_b32_e32 v0, 15, v224
	v_lshlrev_b32_e32 v1, 1, v8
	s_sext_i32_i16 s59, s0
	v_lshl_or_b32 v142, s8, 6, v0
	v_lshl_or_b32 v0, v0, 6, v1
	v_and_b32_e32 v2, 32, v2
	v_lshlrev_b32_e32 v3, 6, v224
	s_movk_i32 s0, 0x3c0
	s_waitcnt vmcnt(6)
	s_ashr_i32 s53, s78, 31
	v_bitop3_b32 v0, v0, s10, v2 bitop3:0xde
	v_and_or_b32 v1, v3, s0, v1
	s_cmpk_lt_u32 s1, 0x100
	v_bitop3_b32 v143, s9, v1, v2 bitop3:0xf6
	v_add_u32_e32 v254, 0x10000, v143
	s_cselect_b64 s[8:9], -1, 0
	v_or_b32_e32 v144, s14, v8
	v_mov_b64_e32 v[136:137], 0xb00
	v_mov_b64_e32 v[138:139], 0xaff
	s_movk_i32 s54, 0xff80
	s_add_i32 s55, 0, 0x10000
	s_add_i32 s56, 0, 0x14000
	v_add_u32_e32 v145, 0, v0
	s_movk_i32 s57, 0x2c00
	v_mov_b32_e32 v146, 0x358637bd
	s_barrier
	s_branch .LBB0_1470

; #define PG8_STAGE(bufoff, gbase, voff) do { _Pragma("unroll") for (int _i = 0; _i < 2; ++_i) \
;         __builtin_amdgcn_global_load_lds((const unsigned*)((const char*)(gbase) + (voff)[_i]), (LAS unsigned*)(lds + (bufoff) + ldsw + _i * 8192), 16, 0, 0); } while (0)
; #define PG8_LDA(dst, b, h) do { _Pragma("unroll") for (int m = 0; m < 4; ++m) _Pragma("unroll") for (int k = 0; k < 2; ++k) dst[m][k] = *(const LAS bf16x8*)(lds + PG8_SA(b, h) + aoff + m * 2048 + k * 1024); } while (0)
; #define PG8_LDB(dst, b, h) do { _Pragma("unroll") for (int n = 0; n < 2; ++n) _Pragma("unroll") for (int k = 0; k < 2; ++k) dst[n][k] = *(const LAS bf16x8*)(lds + PG8_SB(b, h) + boff + n * 2048 + k * 1024); } while (0)
; #define PG8_MMA(ai, bj, At, Bt) do { __builtin_amdgcn_s_setprio(1); _Pragma("unroll") for (int m = 0; m < 4; ++m) _Pragma("unroll") for (int n = 0; n < 2; ++n) _Pragma("unroll") for (int k = 0; k < 2; ++k) \
;         acc[ai][bj][m][n] = __builtin_amdgcn_mfma_f32_16x16x32_bf16(Bt[n][k], At[m][k], acc[ai][bj][m][n], 0, 0, 0); __builtin_amdgcn_s_setprio(0); } while (0)
; #define PG8_WAIT_V(n) asm volatile("s_waitcnt vmcnt(" #n ")" ::: "memory")
; #define PG8_WAIT_L(n) asm volatile("s_waitcnt lgkmcnt(" #n ")" ::: "memory")
; #define PG8_BAR __builtin_amdgcn_s_barrier()
; #define PG8_SCHED __builtin_amdgcn_sched_barrier(0)
; template <class Epi>
; __device__ __forceinline__ void gemm_phase(LAS unsigned char* lds, const Gemm g, const StaticOrder S, const Epi E) {
;     ...
;             const char* a1 = cA + (long)(t + 1) * ksc;
;             const char* a2 = last ? nA : cA + (long)(t + 2) * ksc; const char* b2 = last ? nB : cB + (long)(t + 2) * ksc;
;             const long ks3 = last ? ksn : ksc;
;             const char* a3 = a2 + ks3; const char* b3 = b2 + ks3;
;             PG8_LDB(B0, 0, 0); PG8_LDB(B1, 0, 1); PG8_SCHED; PG8_LDA(At, 0, 0); PG8_STAGE(PG8_SA(1, 1), a1 + hstepA, voffA);
;             PG8_WAIT_V(8); PG8_WAIT_L(0); PG8_BAR; PG8_MMA(0, 0, At, B0); PG8_MMA(0, 1, At, B1); PG8_BAR; PG8_SCHED;
;             PG8_LDA(At, 0, 1); PG8_STAGE(PG8_SB(0, 0), b2, voffB); PG8_STAGE(PG8_SB(0, 1), b2 + hstepB, voffB); PG8_STAGE(PG8_SA(0, 0), a2, voffA);
;             PG8_WAIT_V(8); PG8_WAIT_L(0); PG8_BAR; PG8_MMA(1, 0, At, B0); PG8_MMA(1, 1, At, B1); PG8_BAR; PG8_SCHED;
.LBB0_1473:
	ds_read_b128 v[148:151], v254
	ds_read_b128 v[152:155], v254 offset:1024
	ds_read_b128 v[156:159], v254 offset:2048
	ds_read_b128 v[160:163], v254 offset:3072
	ds_read_b128 v[164:167], v254 offset:16384
	ds_read_b128 v[168:171], v254 offset:17408
	ds_read_b128 v[172:175], v254 offset:18432
	ds_read_b128 v[176:179], v254 offset:19456
	s_or_b32 s13, s60, 1
	s_mul_i32 s42, s27, s13
	s_mul_hi_u32 s43, s26, s13
	s_add_i32 s43, s43, s42
	s_mul_i32 s13, s26, s13
	s_add_u32 s13, s24, s13
	s_addc_u32 s61, s25, s43
	s_add_u32 s42, s40, s38
	s_addc_u32 s43, s41, s39
	s_add_u32 s62, s13, 0x80000
	s_addc_u32 s63, s61, 0
	s_add_i32 m0, s21, 0xc000
	ds_read_b128 v[180:183], v145
	ds_read_b128 v[184:187], v145 offset:1024
	ds_read_b128 v[188:191], v145 offset:2048
	ds_read_b128 v[192:195], v145 offset:3072
	ds_read_b128 v[196:199], v145 offset:4096
	ds_read_b128 v[200:203], v145 offset:5120
	ds_read_b128 v[204:207], v145 offset:6144
	ds_read_b128 v[208:211], v145 offset:7168
	global_load_lds_dwordx4 v134, s[62:63]
	s_add_i32 m0, s21, 0xe000
	s_nop 0
	global_load_lds_dwordx4 v130, s[62:63]
	s_waitcnt vmcnt(8)
	s_waitcnt lgkmcnt(0)
	s_barrier
	s_setprio 1
	s_waitcnt lgkmcnt(0)
	v_mfma_f32_16x16x32_bf16 v[116:119], v[148:151], v[180:183], v[116:119]
	v_mfma_f32_16x16x32_bf16 v[112:115], v[156:159], v[180:183], v[112:115]
	v_mfma_f32_16x16x32_bf16 v[108:111], v[148:151], v[188:191], v[108:111]
	v_mfma_f32_16x16x32_bf16 v[104:107], v[156:159], v[188:191], v[104:107]
	v_mfma_f32_16x16x32_bf16 v[92:95], v[148:151], v[196:199], v[92:95]
	v_mfma_f32_16x16x32_bf16 v[88:91], v[156:159], v[196:199], v[88:91]
	v_mfma_f32_16x16x32_bf16 v[76:79], v[148:151], v[204:207], v[76:79]
	v_mfma_f32_16x16x32_bf16 v[72:75], v[156:159], v[204:207], v[72:75]
	v_mfma_f32_16x16x32_bf16 v[116:119], v[152:155], v[184:187], v[116:119]
	v_mfma_f32_16x16x32_bf16 v[112:115], v[160:163], v[184:187], v[112:115]
	v_mfma_f32_16x16x32_bf16 v[108:111], v[152:155], v[192:195], v[108:111]
	v_mfma_f32_16x16x32_bf16 v[104:107], v[160:163], v[192:195], v[104:107]
	v_mfma_f32_16x16x32_bf16 v[92:95], v[152:155], v[200:203], v[92:95]
	v_mfma_f32_16x16x32_bf16 v[88:91], v[160:163], v[200:203], v[88:91]
	v_mfma_f32_16x16x32_bf16 v[76:79], v[152:155], v[208:211], v[76:79]
	v_mfma_f32_16x16x32_bf16 v[72:75], v[160:163], v[208:211], v[72:75]
	s_setprio 0
	s_setprio 1
	v_mfma_f32_16x16x32_bf16 v[124:127], v[164:167], v[180:183], v[124:127]
	v_mfma_f32_16x16x32_bf16 v[120:123], v[172:175], v[180:183], v[120:123]
	v_mfma_f32_16x16x32_bf16 v[100:103], v[164:167], v[188:191], v[100:103]
	v_mfma_f32_16x16x32_bf16 v[96:99], v[172:175], v[188:191], v[96:99]
	v_mfma_f32_16x16x32_bf16 v[84:87], v[164:167], v[196:199], v[84:87]
	v_mfma_f32_16x16x32_bf16 v[80:83], v[172:175], v[196:199], v[80:83]
	v_mfma_f32_16x16x32_bf16 v[68:71], v[164:167], v[204:207], v[68:71]
	v_mfma_f32_16x16x32_bf16 v[64:67], v[172:175], v[204:207], v[64:67]
	v_mfma_f32_16x16x32_bf16 v[124:127], v[168:171], v[184:187], v[124:127]
	v_mfma_f32_16x16x32_bf16 v[120:123], v[176:179], v[184:187], v[120:123]
	v_mfma_f32_16x16x32_bf16 v[100:103], v[168:171], v[192:195], v[100:103]
	v_mfma_f32_16x16x32_bf16 v[96:99], v[176:179], v[192:195], v[96:99]
	v_mfma_f32_16x16x32_bf16 v[84:87], v[168:171], v[200:203], v[84:87]
	v_mfma_f32_16x16x32_bf16 v[80:83], v[176:179], v[200:203], v[80:83]
	v_mfma_f32_16x16x32_bf16 v[68:71], v[168:171], v[208:211], v[68:71]
	v_mfma_f32_16x16x32_bf16 v[64:67], v[176:179], v[208:211], v[64:67]
	s_setprio 0
	s_barrier
	s_add_i32 s13, s55, s45
	s_mov_b32 m0, s13
	ds_read_b128 v[180:183], v145 offset:16384
	ds_read_b128 v[184:187], v145 offset:17408
	ds_read_b128 v[188:191], v145 offset:18432
	ds_read_b128 v[192:195], v145 offset:19456
	ds_read_b128 v[196:199], v145 offset:20480
	ds_read_b128 v[200:203], v145 offset:21504
	ds_read_b128 v[204:207], v145 offset:22528
	ds_read_b128 v[208:211], v145 offset:23552
	global_load_lds_dwordx4 v132, s[36:37]
	s_add_i32 m0, s13, 0x2000
	s_add_u32 s62, s36, 0x80000
	s_addc_u32 s63, s37, 0
	s_add_i32 s13, s56, s45
	global_load_lds_dwordx4 v128, s[36:37]
	s_mov_b32 m0, s13
	s_nop 0
	global_load_lds_dwordx4 v132, s[62:63]
	s_add_i32 m0, s13, 0x2000
	s_nop 0
	global_load_lds_dwordx4 v128, s[62:63]
	s_mov_b32 m0, s21
	s_nop 0
	global_load_lds_dwordx4 v134, s[40:41]
	s_mov_b32 m0, s48
	s_nop 0
	global_load_lds_dwordx4 v130, s[40:41]
	s_waitcnt vmcnt(8)
	s_waitcnt lgkmcnt(0)
	s_barrier
	s_setprio 1
	s_waitcnt lgkmcnt(0)
	v_mfma_f32_16x16x32_bf16 v[60:63], v[148:151], v[180:183], v[60:63]
	v_mfma_f32_16x16x32_bf16 v[56:59], v[156:159], v[180:183], v[56:59]
	v_mfma_f32_16x16x32_bf16 v[44:47], v[148:151], v[188:191], v[44:47]
	v_mfma_f32_16x16x32_bf16 v[40:43], v[156:159], v[188:191], v[40:43]
	v_mfma_f32_16x16x32_bf16 v[28:31], v[148:151], v[196:199], v[28:31]
	v_mfma_f32_16x16x32_bf16 v[24:27], v[156:159], v[196:199], v[24:27]
	v_mfma_f32_16x16x32_bf16 v[12:15], v[148:151], v[204:207], v[12:15]
	v_mfma_f32_16x16x32_bf16 v[8:11], v[156:159], v[204:207], v[8:11]
	v_mfma_f32_16x16x32_bf16 v[60:63], v[152:155], v[184:187], v[60:63]
	v_mfma_f32_16x16x32_bf16 v[56:59], v[160:163], v[184:187], v[56:59]
	v_mfma_f32_16x16x32_bf16 v[44:47], v[152:155], v[192:195], v[44:47]
	v_mfma_f32_16x16x32_bf16 v[40:43], v[160:163], v[192:195], v[40:43]
	v_mfma_f32_16x16x32_bf16 v[28:31], v[152:155], v[200:203], v[28:31]
	v_mfma_f32_16x16x32_bf16 v[24:27], v[160:163], v[200:203], v[24:27]
	v_mfma_f32_16x16x32_bf16 v[12:15], v[152:155], v[208:211], v[12:15]
	v_mfma_f32_16x16x32_bf16 v[8:11], v[160:163], v[208:211], v[8:11]
	s_setprio 0
	s_setprio 1
	v_mfma_f32_16x16x32_bf16 v[52:55], v[164:167], v[180:183], v[52:55]
	v_mfma_f32_16x16x32_bf16 v[48:51], v[172:175], v[180:183], v[48:51]
	v_mfma_f32_16x16x32_bf16 v[36:39], v[164:167], v[188:191], v[36:39]
	v_mfma_f32_16x16x32_bf16 v[32:35], v[172:175], v[188:191], v[32:35]
	v_mfma_f32_16x16x32_bf16 v[20:23], v[164:167], v[196:199], v[20:23]
	v_mfma_f32_16x16x32_bf16 v[16:19], v[172:175], v[196:199], v[16:19]
	v_mfma_f32_16x16x32_bf16 v[4:7], v[164:167], v[204:207], v[4:7]
	v_mfma_f32_16x16x32_bf16 v[0:3], v[172:175], v[204:207], v[0:3]
	v_mfma_f32_16x16x32_bf16 v[52:55], v[168:171], v[184:187], v[52:55]
	v_mfma_f32_16x16x32_bf16 v[48:51], v[176:179], v[184:187], v[48:51]
	v_mfma_f32_16x16x32_bf16 v[36:39], v[168:171], v[192:195], v[36:39]
	v_mfma_f32_16x16x32_bf16 v[32:35], v[176:179], v[192:195], v[32:35]
	v_mfma_f32_16x16x32_bf16 v[20:23], v[168:171], v[200:203], v[20:23]
	v_mfma_f32_16x16x32_bf16 v[16:19], v[176:179], v[200:203], v[16:19]
	v_mfma_f32_16x16x32_bf16 v[4:7], v[168:171], v[208:211], v[4:7]
	v_mfma_f32_16x16x32_bf16 v[0:3], v[176:179], v[208:211], v[0:3]
	s_setprio 0
	s_barrier
; #define PG8_STAGE(bufoff, gbase, voff) do { _Pragma("unroll") for (int _i = 0; _i < 2; ++_i) \
;         __builtin_amdgcn_global_load_lds((const unsigned*)((const char*)(gbase) + (voff)[_i]), (LAS unsigned*)(lds + (bufoff) + ldsw + _i * 8192), 16, 0, 0); } while (0)
; #define PG8_LDA(dst, b, h) do { _Pragma("unroll") for (int m = 0; m < 4; ++m) _Pragma("unroll") for (int k = 0; k < 2; ++k) dst[m][k] = *(const LAS bf16x8*)(lds + PG8_SA(b, h) + aoff + m * 2048 + k * 1024); } while (0)
; #define PG8_LDB(dst, b, h) do { _Pragma("unroll") for (int n = 0; n < 2; ++n) _Pragma("unroll") for (int k = 0; k < 2; ++k) dst[n][k] = *(const LAS bf16x8*)(lds + PG8_SB(b, h) + boff + n * 2048 + k * 1024); } while (0)
; #define PG8_MMA(ai, bj, At, Bt) do { __builtin_amdgcn_s_setprio(1); _Pragma("unroll") for (int m = 0; m < 4; ++m) _Pragma("unroll") for (int n = 0; n < 2; ++n) _Pragma("unroll") for (int k = 0; k < 2; ++k) \
;         acc[ai][bj][m][n] = __builtin_amdgcn_mfma_f32_16x16x32_bf16(Bt[n][k], At[m][k], acc[ai][bj][m][n], 0, 0, 0); __builtin_amdgcn_s_setprio(0); } while (0)
; #define PG8_WAIT_V(n) asm volatile("s_waitcnt vmcnt(" #n ")" ::: "memory")
; #define PG8_WAIT_L(n) asm volatile("s_waitcnt lgkmcnt(" #n ")" ::: "memory")
; #define PG8_BAR __builtin_amdgcn_s_barrier()
; #define PG8_SCHED __builtin_amdgcn_sched_barrier(0)
; template <class Epi>
; __device__ __forceinline__ void gemm_phase(LAS unsigned char* lds, const Gemm g, const StaticOrder S, const Epi E) {
;     ...
;             PG8_LDB(B0, 1, 0); PG8_LDB(B1, 1, 1); PG8_SCHED; PG8_LDA(At, 1, 0); PG8_STAGE(PG8_SA(0, 1), a2 + hstepA, voffA);
;             PG8_WAIT_V(8); PG8_WAIT_L(0); PG8_BAR; PG8_MMA(0, 0, At, B0); PG8_MMA(0, 1, At, B1); PG8_BAR; PG8_SCHED;
;             PG8_LDA(At, 1, 1); PG8_STAGE(PG8_SB(1, 0), b3, voffB); PG8_STAGE(PG8_SB(1, 1), b3 + hstepB, voffB); PG8_STAGE(PG8_SA(1, 0), a3, voffA);
;             PG8_WAIT_V(8); PG8_WAIT_L(0); PG8_BAR; PG8_MMA(1, 0, At, B0); PG8_MMA(1, 1, At, B1); PG8_BAR; PG8_SCHED;
;         }
	s_add_i32 s13, 0, 0x18000
	s_add_i32 s61, 0, 0x1c000
	ds_read_b128 v[148:151], v254 offset:32768
	ds_read_b128 v[152:155], v254 offset:33792
	ds_read_b128 v[156:159], v254 offset:34816
	ds_read_b128 v[160:163], v254 offset:35840
	ds_read_b128 v[164:167], v254 offset:49152
	ds_read_b128 v[168:171], v254 offset:50176
	ds_read_b128 v[172:175], v254 offset:51200
	ds_read_b128 v[176:179], v254 offset:52224
	s_add_u32 s40, s40, 0x80000
	s_addc_u32 s41, s41, 0
	s_mov_b32 m0, s49
	ds_read_b128 v[180:183], v145 offset:32768
	ds_read_b128 v[184:187], v145 offset:33792
	ds_read_b128 v[188:191], v145 offset:34816
	ds_read_b128 v[192:195], v145 offset:35840
	ds_read_b128 v[196:199], v145 offset:36864
	ds_read_b128 v[200:203], v145 offset:37888
	ds_read_b128 v[204:207], v145 offset:38912
	ds_read_b128 v[208:211], v145 offset:39936
	global_load_lds_dwordx4 v134, s[40:41]
	s_mov_b32 m0, s50
	s_nop 0
	global_load_lds_dwordx4 v130, s[40:41]
	s_waitcnt vmcnt(8)
	s_waitcnt lgkmcnt(0)
	s_barrier
	s_setprio 1
	s_waitcnt lgkmcnt(0)
	v_mfma_f32_16x16x32_bf16 v[116:119], v[148:151], v[180:183], v[116:119]
	v_mfma_f32_16x16x32_bf16 v[112:115], v[156:159], v[180:183], v[112:115]
	v_mfma_f32_16x16x32_bf16 v[108:111], v[148:151], v[188:191], v[108:111]
	v_mfma_f32_16x16x32_bf16 v[104:107], v[156:159], v[188:191], v[104:107]
	v_mfma_f32_16x16x32_bf16 v[92:95], v[148:151], v[196:199], v[92:95]
	v_mfma_f32_16x16x32_bf16 v[88:91], v[156:159], v[196:199], v[88:91]
	v_mfma_f32_16x16x32_bf16 v[76:79], v[148:151], v[204:207], v[76:79]
	v_mfma_f32_16x16x32_bf16 v[72:75], v[156:159], v[204:207], v[72:75]
	v_mfma_f32_16x16x32_bf16 v[116:119], v[152:155], v[184:187], v[116:119]
	v_mfma_f32_16x16x32_bf16 v[112:115], v[160:163], v[184:187], v[112:115]
	v_mfma_f32_16x16x32_bf16 v[108:111], v[152:155], v[192:195], v[108:111]
	v_mfma_f32_16x16x32_bf16 v[104:107], v[160:163], v[192:195], v[104:107]
	v_mfma_f32_16x16x32_bf16 v[92:95], v[152:155], v[200:203], v[92:95]
	v_mfma_f32_16x16x32_bf16 v[88:91], v[160:163], v[200:203], v[88:91]
	v_mfma_f32_16x16x32_bf16 v[76:79], v[152:155], v[208:211], v[76:79]
	v_mfma_f32_16x16x32_bf16 v[72:75], v[160:163], v[208:211], v[72:75]
	s_setprio 0
	s_setprio 1
	v_mfma_f32_16x16x32_bf16 v[124:127], v[164:167], v[180:183], v[124:127]
	v_mfma_f32_16x16x32_bf16 v[120:123], v[172:175], v[180:183], v[120:123]
	v_mfma_f32_16x16x32_bf16 v[100:103], v[164:167], v[188:191], v[100:103]
	v_mfma_f32_16x16x32_bf16 v[96:99], v[172:175], v[188:191], v[96:99]
	v_mfma_f32_16x16x32_bf16 v[84:87], v[164:167], v[196:199], v[84:87]
	v_mfma_f32_16x16x32_bf16 v[80:83], v[172:175], v[196:199], v[80:83]
	v_mfma_f32_16x16x32_bf16 v[68:71], v[164:167], v[204:207], v[68:71]
	v_mfma_f32_16x16x32_bf16 v[64:67], v[172:175], v[204:207], v[64:67]
	v_mfma_f32_16x16x32_bf16 v[124:127], v[168:171], v[184:187], v[124:127]
	v_mfma_f32_16x16x32_bf16 v[120:123], v[176:179], v[184:187], v[120:123]
	v_mfma_f32_16x16x32_bf16 v[100:103], v[168:171], v[192:195], v[100:103]
	v_mfma_f32_16x16x32_bf16 v[96:99], v[176:179], v[192:195], v[96:99]
	v_mfma_f32_16x16x32_bf16 v[84:87], v[168:171], v[200:203], v[84:87]
	v_mfma_f32_16x16x32_bf16 v[80:83], v[176:179], v[200:203], v[80:83]
	v_mfma_f32_16x16x32_bf16 v[68:71], v[168:171], v[208:211], v[68:71]
	v_mfma_f32_16x16x32_bf16 v[64:67], v[176:179], v[208:211], v[64:67]
	s_setprio 0
	s_barrier
	s_add_u32 s36, s36, s38
	s_addc_u32 s37, s37, s39
	s_add_i32 s13, s13, s45
	s_mov_b32 m0, s13
	ds_read_b128 v[180:183], v145 offset:49152
	ds_read_b128 v[184:187], v145 offset:50176
	ds_read_b128 v[188:191], v145 offset:51200
	ds_read_b128 v[192:195], v145 offset:52224
	ds_read_b128 v[196:199], v145 offset:53248
	ds_read_b128 v[200:203], v145 offset:54272
	ds_read_b128 v[204:207], v145 offset:55296
	ds_read_b128 v[208:211], v145 offset:56320
	global_load_lds_dwordx4 v132, s[36:37]
	s_add_i32 m0, s13, 0x2000
	s_nop 0
	global_load_lds_dwordx4 v128, s[36:37]
	s_add_u32 s36, s36, 0x80000
	s_addc_u32 s37, s37, 0
	s_add_i32 s13, s61, s45
	s_mov_b32 m0, s13
	s_nop 0
	global_load_lds_dwordx4 v132, s[36:37]
	s_add_i32 m0, s13, 0x2000
	s_nop 0
	global_load_lds_dwordx4 v128, s[36:37]
	s_mov_b32 m0, s51
	s_nop 0
	global_load_lds_dwordx4 v134, s[42:43]
	s_mov_b32 m0, s52
	s_nop 0
	global_load_lds_dwordx4 v130, s[42:43]
	s_waitcnt vmcnt(8)
	s_waitcnt lgkmcnt(0)
	s_barrier
	s_setprio 1
	s_waitcnt lgkmcnt(0)
	v_mfma_f32_16x16x32_bf16 v[60:63], v[148:151], v[180:183], v[60:63]
	v_mfma_f32_16x16x32_bf16 v[56:59], v[156:159], v[180:183], v[56:59]
	v_mfma_f32_16x16x32_bf16 v[44:47], v[148:151], v[188:191], v[44:47]
	v_mfma_f32_16x16x32_bf16 v[40:43], v[156:159], v[188:191], v[40:43]
	v_mfma_f32_16x16x32_bf16 v[28:31], v[148:151], v[196:199], v[28:31]
	v_mfma_f32_16x16x32_bf16 v[24:27], v[156:159], v[196:199], v[24:27]
	v_mfma_f32_16x16x32_bf16 v[12:15], v[148:151], v[204:207], v[12:15]
	v_mfma_f32_16x16x32_bf16 v[8:11], v[156:159], v[204:207], v[8:11]
	v_mfma_f32_16x16x32_bf16 v[60:63], v[152:155], v[184:187], v[60:63]
	v_mfma_f32_16x16x32_bf16 v[56:59], v[160:163], v[184:187], v[56:59]
	v_mfma_f32_16x16x32_bf16 v[44:47], v[152:155], v[192:195], v[44:47]
	v_mfma_f32_16x16x32_bf16 v[40:43], v[160:163], v[192:195], v[40:43]
	v_mfma_f32_16x16x32_bf16 v[28:31], v[152:155], v[200:203], v[28:31]
	v_mfma_f32_16x16x32_bf16 v[24:27], v[160:163], v[200:203], v[24:27]
	v_mfma_f32_16x16x32_bf16 v[12:15], v[152:155], v[208:211], v[12:15]
	v_mfma_f32_16x16x32_bf16 v[8:11], v[160:163], v[208:211], v[8:11]
	s_setprio 0
	s_setprio 1
	v_mfma_f32_16x16x32_bf16 v[52:55], v[164:167], v[180:183], v[52:55]
	v_mfma_f32_16x16x32_bf16 v[48:51], v[172:175], v[180:183], v[48:51]
	v_mfma_f32_16x16x32_bf16 v[36:39], v[164:167], v[188:191], v[36:39]
	v_mfma_f32_16x16x32_bf16 v[32:35], v[172:175], v[188:191], v[32:35]
	v_mfma_f32_16x16x32_bf16 v[20:23], v[164:167], v[196:199], v[20:23]
	v_mfma_f32_16x16x32_bf16 v[16:19], v[172:175], v[196:199], v[16:19]
	v_mfma_f32_16x16x32_bf16 v[4:7], v[164:167], v[204:207], v[4:7]
	v_mfma_f32_16x16x32_bf16 v[0:3], v[172:175], v[204:207], v[0:3]
	v_mfma_f32_16x16x32_bf16 v[52:55], v[168:171], v[184:187], v[52:55]
	v_mfma_f32_16x16x32_bf16 v[48:51], v[176:179], v[184:187], v[48:51]
	v_mfma_f32_16x16x32_bf16 v[36:39], v[168:171], v[192:195], v[36:39]
	v_mfma_f32_16x16x32_bf16 v[32:35], v[176:179], v[192:195], v[32:35]
	v_mfma_f32_16x16x32_bf16 v[20:23], v[168:171], v[200:203], v[20:23]
	v_mfma_f32_16x16x32_bf16 v[16:19], v[176:179], v[200:203], v[16:19]
	v_mfma_f32_16x16x32_bf16 v[4:7], v[168:171], v[208:211], v[4:7]
	v_mfma_f32_16x16x32_bf16 v[0:3], v[176:179], v[208:211], v[0:3]
	s_setprio 0
	s_barrier
	s_cmp_gt_u32 s60, 29
	s_mov_b32 s60, s11
	s_cbranch_scc1 .LBB0_1478

; #define PG8_STAGE(bufoff, gbase, voff) do { _Pragma("unroll") for (int _i = 0; _i < 2; ++_i) \
;         __builtin_amdgcn_global_load_lds((const unsigned*)((const char*)(gbase) + (voff)[_i]), (LAS unsigned*)(lds + (bufoff) + ldsw + _i * 8192), 16, 0, 0); } while (0)
; #define PG8_WAIT_V(n) asm volatile("s_waitcnt vmcnt(" #n ")" ::: "memory")
; #define PG8_BAR __builtin_amdgcn_s_barrier()
; template <class Epi>
; __device__ __forceinline__ void gemm_phase(LAS unsigned char* lds, const Gemm g, const StaticOrder S, const Epi E) {
;     ...
;     for (int i = 0; i < 2; ++i) { int R, C; stage_rc(tid * 16 + i * 8192, R, C); const int Rb = Epi::PERM ? ((R & ~31) + perm32(R & 31)) : R;
;         voffA[i] = (unsigned)(R * g.lda + C) * 2u; voffB[i] = (unsigned)(Rb * g.ldb + C) * 2u; }
;     const size_t kstep = (size_t)(BK * 2);
;     const size_t hstepA = (size_t)HALF * g.lda * 2, hstepB = (size_t)HALF * g.ldb * 2;
;     const size_t tstepA = 2 * hstepA, tstepB = 2 * hstepB;
;     const unsigned ldsw = (unsigned)wid * 1024u;
;     const int aoff = lds_byte(wr * 64 + fr, fq * 8), boff = lds_byte(wc * 32 + fr, fq * 8);
;     ...
;     PG8_STAGE(PG8_SB(1, 0), cB + ksc, voffB); PG8_STAGE(PG8_SA(1, 0), cA + ksc, voffA); PG8_STAGE(PG8_SB(1, 1), cB + hstepB + ksc, voffB);
;     PG8_WAIT_V(6); PG8_BAR;
.LBB0_1544:
	s_lshl_b32 s3, s3, 5
	s_and_b32 s3, s3, 0x60
	s_lshl_b32 s14, s0, 13
	s_lshl_b32 s15, s3, 7
	s_ashr_i32 s50, s79, 31
	s_add_u32 s12, s1, 0x2b00
	s_addc_u32 s13, s2, 0
	s_add_i32 m0, s46, 0x18000
	s_waitcnt vmcnt(2)
	s_barrier
	global_load_lds_dwordx4 v142, s[12:13]
	s_add_i32 m0, s46, 0x1a000
	v_lshl_add_u64 v[0:1], s[12:13], 0, v[146:147]
	s_add_u32 s12, s5, 0x2b00
	s_addc_u32 s13, s10, 0
	s_add_i32 s51, s46, 0x8000
	s_add_i32 s52, s46, 0xa000
	global_load_lds_dwordx4 v[0:1], off
	s_mov_b32 m0, s51
	s_add_u32 s10, s1, 0x162b00
	global_load_lds_dwordx4 v140, s[12:13]
	s_mov_b32 m0, s52
	s_addc_u32 s11, s2, 0
	global_load_lds_dwordx4 v144, s[12:13]
	s_add_i32 m0, s46, 0x1c000
	s_nop 0
	global_load_lds_dwordx4 v142, s[10:11]
	s_add_i32 m0, s46, 0x1e000
	v_lshlrev_b32_e32 v3, 2, v224
	global_load_lds_dwordx4 v146, s[10:11]
	v_bfe_u32 v1, v224, 4, 2
	v_and_b32_e32 v0, 15, v224
	v_lshlrev_b32_e32 v2, 4, v1
	v_lshl_or_b32 v160, s0, 6, v0
	v_lshl_or_b32 v0, v0, 6, v2
	v_and_b32_e32 v3, 32, v3
	s_ashr_i32 s53, s78, 31
	v_bitop3_b32 v0, v0, s14, v3 bitop3:0xde
	v_lshlrev_b32_e32 v4, 6, v224
	s_movk_i32 s0, 0x3c0
	s_waitcnt vmcnt(6)
	s_cmpk_lt_u32 s4, 0x100
	v_and_or_b32 v2, v4, s0, v2
	s_cselect_b64 s[10:11], -1, 0
	s_add_u32 s12, s82, 0x2a9e0000
	s_movk_i32 s34, 0xff80
	v_add_u32_e32 v163, 0, v0
	v_mbcnt_lo_u32_b32 v0, -1, 0
	v_bitop3_b32 v161, s15, v2, v3 bitop3:0xf6
	v_add_u32_e32 v254, 0x10000, v161
	s_addc_u32 s13, s83, 0
	v_cmp_eq_u32_e64 s[0:1], 0, v1
	v_lshl_or_b32 v162, v1, 3, s3
	s_mov_b32 s35, -1
	v_mov_b64_e32 v[148:149], 0x200
	v_mov_b64_e32 v[150:151], 0x1ff
	s_movk_i32 s54, 0x80
	s_add_i32 s55, 0, 0x10000
	s_add_i32 s56, 0, 0x14000
	s_mov_b64 s[14:15], 0x80000
	s_mov_b32 s57, 0x80000
	s_mov_b64 s[16:17], 0x90000
	s_mov_b32 s58, 0x90000
	s_mov_b64 s[18:19], 0xa0000
	s_mov_b32 s59, 0xa0000
	s_mov_b64 s[20:21], 0xb0000
	s_mov_b32 s60, 0xb0000
	v_mbcnt_hi_u32_b32 v164, -1, v0
	s_barrier
	s_branch .LBB0_1547

; #define PG8_STAGE(bufoff, gbase, voff) do { _Pragma("unroll") for (int _i = 0; _i < 2; ++_i) \
;         __builtin_amdgcn_global_load_lds((const unsigned*)((const char*)(gbase) + (voff)[_i]), (LAS unsigned*)(lds + (bufoff) + ldsw + _i * 8192), 16, 0, 0); } while (0)
; #define PG8_LDA(dst, b, h) do { _Pragma("unroll") for (int m = 0; m < 4; ++m) _Pragma("unroll") for (int k = 0; k < 2; ++k) dst[m][k] = *(const LAS bf16x8*)(lds + PG8_SA(b, h) + aoff + m * 2048 + k * 1024); } while (0)
; #define PG8_LDB(dst, b, h) do { _Pragma("unroll") for (int n = 0; n < 2; ++n) _Pragma("unroll") for (int k = 0; k < 2; ++k) dst[n][k] = *(const LAS bf16x8*)(lds + PG8_SB(b, h) + boff + n * 2048 + k * 1024); } while (0)
; #define PG8_MMA(ai, bj, At, Bt) do { __builtin_amdgcn_s_setprio(1); _Pragma("unroll") for (int m = 0; m < 4; ++m) _Pragma("unroll") for (int n = 0; n < 2; ++n) _Pragma("unroll") for (int k = 0; k < 2; ++k) \
;         acc[ai][bj][m][n] = __builtin_amdgcn_mfma_f32_16x16x32_bf16(Bt[n][k], At[m][k], acc[ai][bj][m][n], 0, 0, 0); __builtin_amdgcn_s_setprio(0); } while (0)
; #define PG8_WAIT_V(n) asm volatile("s_waitcnt vmcnt(" #n ")" ::: "memory")
; #define PG8_WAIT_L(n) asm volatile("s_waitcnt lgkmcnt(" #n ")" ::: "memory")
; #define PG8_BAR __builtin_amdgcn_s_barrier()
; #define PG8_SCHED __builtin_amdgcn_sched_barrier(0)
; template <class Epi>
; __device__ __forceinline__ void gemm_phase(LAS unsigned char* lds, const Gemm g, const StaticOrder S, const Epi E) {
;     ...
;             const char* a1 = cA + (long)(t + 1) * ksc;
;             const char* a2 = last ? nA : cA + (long)(t + 2) * ksc; const char* b2 = last ? nB : cB + (long)(t + 2) * ksc;
;             const long ks3 = last ? ksn : ksc;
;             const char* a3 = a2 + ks3; const char* b3 = b2 + ks3;
;             PG8_LDB(B0, 0, 0); PG8_LDB(B1, 0, 1); PG8_SCHED; PG8_LDA(At, 0, 0); PG8_STAGE(PG8_SA(1, 1), a1 + hstepA, voffA);
;             PG8_WAIT_V(8); PG8_WAIT_L(0); PG8_BAR; PG8_MMA(0, 0, At, B0); PG8_MMA(0, 1, At, B1); PG8_BAR; PG8_SCHED;
;             PG8_LDA(At, 0, 1); PG8_STAGE(PG8_SB(0, 0), b2, voffB); PG8_STAGE(PG8_SB(0, 1), b2 + hstepB, voffB); PG8_STAGE(PG8_SA(0, 0), a2, voffA);
;             PG8_WAIT_V(8); PG8_WAIT_L(0); PG8_BAR; PG8_MMA(1, 0, At, B0); PG8_MMA(1, 1, At, B1); PG8_BAR; PG8_SCHED;
.LBB0_1558:
	v_add_u32_e32 v152, s55, v161
	ds_read_b128 v[128:131], v152
	ds_read_b128 v[132:135], v152 offset:1024
	ds_read_b128 v[136:139], v152 offset:2048
	ds_read_b128 v[152:155], v152 offset:3072
	ds_read_b128 v[156:159], v254 offset:16384
	ds_read_b128 v[166:169], v254 offset:17408
	ds_read_b128 v[170:173], v254 offset:18432
	ds_read_b128 v[174:177], v254 offset:19456
	s_or_b32 s42, s66, 1
	s_mul_i32 s43, s35, s42
	s_mul_hi_u32 s68, s34, s42
	s_add_i32 s68, s68, s43
	s_mul_i32 s42, s34, s42
	s_add_u32 s69, s30, s42
	s_addc_u32 s70, s31, s68
	s_add_u32 s42, s40, s38
	s_addc_u32 s43, s41, s39
	s_add_u32 s68, s69, 0x160000
	s_addc_u32 s69, s70, 0
	s_add_i32 m0, s46, 0xc000
	ds_read_b128 v[178:181], v163
	ds_read_b128 v[182:185], v163 offset:1024
	ds_read_b128 v[186:189], v163 offset:2048
	ds_read_b128 v[190:193], v163 offset:3072
	ds_read_b128 v[194:197], v163 offset:4096
	ds_read_b128 v[198:201], v163 offset:5120
	ds_read_b128 v[202:205], v163 offset:6144
	ds_read_b128 v[206:209], v163 offset:7168
	global_load_lds_dwordx4 v140, s[68:69]
	s_add_i32 m0, s46, 0xe000
	s_nop 0
	global_load_lds_dwordx4 v144, s[68:69]
	s_waitcnt vmcnt(8)
	s_waitcnt lgkmcnt(0)
	s_barrier
	s_setprio 1
	s_waitcnt lgkmcnt(0)
	v_mfma_f32_16x16x32_bf16 v[124:127], v[128:131], v[178:181], v[124:127]
	v_mfma_f32_16x16x32_bf16 v[120:123], v[136:139], v[178:181], v[120:123]
	v_mfma_f32_16x16x32_bf16 v[108:111], v[128:131], v[186:189], v[108:111]
	v_mfma_f32_16x16x32_bf16 v[104:107], v[136:139], v[186:189], v[104:107]
	v_mfma_f32_16x16x32_bf16 v[92:95], v[128:131], v[194:197], v[92:95]
	v_mfma_f32_16x16x32_bf16 v[88:91], v[136:139], v[194:197], v[88:91]
	v_mfma_f32_16x16x32_bf16 v[76:79], v[128:131], v[202:205], v[76:79]
	v_mfma_f32_16x16x32_bf16 v[72:75], v[136:139], v[202:205], v[72:75]
	v_mfma_f32_16x16x32_bf16 v[124:127], v[132:135], v[182:185], v[124:127]
	v_mfma_f32_16x16x32_bf16 v[120:123], v[152:155], v[182:185], v[120:123]
	v_mfma_f32_16x16x32_bf16 v[108:111], v[132:135], v[190:193], v[108:111]
	v_mfma_f32_16x16x32_bf16 v[104:107], v[152:155], v[190:193], v[104:107]
	v_mfma_f32_16x16x32_bf16 v[92:95], v[132:135], v[198:201], v[92:95]
	v_mfma_f32_16x16x32_bf16 v[88:91], v[152:155], v[198:201], v[88:91]
	v_mfma_f32_16x16x32_bf16 v[76:79], v[132:135], v[206:209], v[76:79]
	v_mfma_f32_16x16x32_bf16 v[72:75], v[152:155], v[206:209], v[72:75]
	s_setprio 0
	s_setprio 1
	v_mfma_f32_16x16x32_bf16 v[116:119], v[156:159], v[178:181], v[116:119]
	v_mfma_f32_16x16x32_bf16 v[112:115], v[170:173], v[178:181], v[112:115]
	v_mfma_f32_16x16x32_bf16 v[100:103], v[156:159], v[186:189], v[100:103]
	v_mfma_f32_16x16x32_bf16 v[96:99], v[170:173], v[186:189], v[96:99]
	v_mfma_f32_16x16x32_bf16 v[84:87], v[156:159], v[194:197], v[84:87]
	v_mfma_f32_16x16x32_bf16 v[80:83], v[170:173], v[194:197], v[80:83]
	v_mfma_f32_16x16x32_bf16 v[68:71], v[156:159], v[202:205], v[68:71]
	v_mfma_f32_16x16x32_bf16 v[64:67], v[170:173], v[202:205], v[64:67]
	v_mfma_f32_16x16x32_bf16 v[116:119], v[166:169], v[182:185], v[116:119]
	v_mfma_f32_16x16x32_bf16 v[112:115], v[174:177], v[182:185], v[112:115]
	v_mfma_f32_16x16x32_bf16 v[100:103], v[166:169], v[190:193], v[100:103]
	v_mfma_f32_16x16x32_bf16 v[96:99], v[174:177], v[190:193], v[96:99]
	v_mfma_f32_16x16x32_bf16 v[84:87], v[166:169], v[198:201], v[84:87]
	v_mfma_f32_16x16x32_bf16 v[80:83], v[174:177], v[198:201], v[80:83]
	v_mfma_f32_16x16x32_bf16 v[68:71], v[166:169], v[206:209], v[68:71]
	v_mfma_f32_16x16x32_bf16 v[64:67], v[174:177], v[206:209], v[64:67]
	s_setprio 0
	s_barrier
	s_add_i32 s68, s55, s45
	s_mov_b32 m0, s68
	ds_read_b128 v[178:181], v163 offset:16384
	ds_read_b128 v[182:185], v163 offset:17408
	ds_read_b128 v[186:189], v163 offset:18432
	ds_read_b128 v[190:193], v163 offset:19456
	ds_read_b128 v[194:197], v163 offset:20480
	ds_read_b128 v[198:201], v163 offset:21504
	ds_read_b128 v[202:205], v163 offset:22528
	ds_read_b128 v[206:209], v163 offset:23552
	global_load_lds_dwordx4 v142, s[36:37]
	s_add_i32 m0, s68, 0x2000
	s_add_u32 s68, s36, 0x160000
	s_addc_u32 s69, s37, 0
	s_add_i32 s70, s56, s45
	global_load_lds_dwordx4 v146, s[36:37]
	s_mov_b32 m0, s70
	s_nop 0
	global_load_lds_dwordx4 v142, s[68:69]
	s_add_i32 m0, s70, 0x2000
	s_nop 0
	global_load_lds_dwordx4 v146, s[68:69]
	s_mov_b32 m0, s46
	s_nop 0
	global_load_lds_dwordx4 v140, s[40:41]
	s_mov_b32 m0, s47
	s_nop 0
	global_load_lds_dwordx4 v144, s[40:41]
	s_waitcnt vmcnt(8)
	s_waitcnt lgkmcnt(0)
	s_barrier
	s_setprio 1
	s_waitcnt lgkmcnt(0)
	v_mfma_f32_16x16x32_bf16 v[60:63], v[128:131], v[178:181], v[60:63]
	v_mfma_f32_16x16x32_bf16 v[56:59], v[136:139], v[178:181], v[56:59]
	v_mfma_f32_16x16x32_bf16 v[44:47], v[128:131], v[186:189], v[44:47]
	v_mfma_f32_16x16x32_bf16 v[40:43], v[136:139], v[186:189], v[40:43]
	v_mfma_f32_16x16x32_bf16 v[28:31], v[128:131], v[194:197], v[28:31]
	v_mfma_f32_16x16x32_bf16 v[24:27], v[136:139], v[194:197], v[24:27]
	v_mfma_f32_16x16x32_bf16 v[12:15], v[128:131], v[202:205], v[12:15]
	v_mfma_f32_16x16x32_bf16 v[8:11], v[136:139], v[202:205], v[8:11]
	v_mfma_f32_16x16x32_bf16 v[60:63], v[132:135], v[182:185], v[60:63]
	v_mfma_f32_16x16x32_bf16 v[56:59], v[152:155], v[182:185], v[56:59]
	v_mfma_f32_16x16x32_bf16 v[44:47], v[132:135], v[190:193], v[44:47]
	v_mfma_f32_16x16x32_bf16 v[40:43], v[152:155], v[190:193], v[40:43]
	v_mfma_f32_16x16x32_bf16 v[28:31], v[132:135], v[198:201], v[28:31]
	v_mfma_f32_16x16x32_bf16 v[24:27], v[152:155], v[198:201], v[24:27]
	v_mfma_f32_16x16x32_bf16 v[12:15], v[132:135], v[206:209], v[12:15]
	v_mfma_f32_16x16x32_bf16 v[8:11], v[152:155], v[206:209], v[8:11]
	s_setprio 0
	s_setprio 1
	v_mfma_f32_16x16x32_bf16 v[52:55], v[156:159], v[178:181], v[52:55]
	v_mfma_f32_16x16x32_bf16 v[48:51], v[170:173], v[178:181], v[48:51]
	v_mfma_f32_16x16x32_bf16 v[36:39], v[156:159], v[186:189], v[36:39]
	v_mfma_f32_16x16x32_bf16 v[32:35], v[170:173], v[186:189], v[32:35]
	v_mfma_f32_16x16x32_bf16 v[20:23], v[156:159], v[194:197], v[20:23]
	v_mfma_f32_16x16x32_bf16 v[16:19], v[170:173], v[194:197], v[16:19]
	v_mfma_f32_16x16x32_bf16 v[4:7], v[156:159], v[202:205], v[4:7]
	v_mfma_f32_16x16x32_bf16 v[0:3], v[170:173], v[202:205], v[0:3]
	v_mfma_f32_16x16x32_bf16 v[52:55], v[166:169], v[182:185], v[52:55]
	v_mfma_f32_16x16x32_bf16 v[48:51], v[174:177], v[182:185], v[48:51]
	v_mfma_f32_16x16x32_bf16 v[36:39], v[166:169], v[190:193], v[36:39]
	v_mfma_f32_16x16x32_bf16 v[32:35], v[174:177], v[190:193], v[32:35]
	v_mfma_f32_16x16x32_bf16 v[20:23], v[166:169], v[198:201], v[20:23]
	v_mfma_f32_16x16x32_bf16 v[16:19], v[174:177], v[198:201], v[16:19]
	v_mfma_f32_16x16x32_bf16 v[4:7], v[166:169], v[206:209], v[4:7]
	v_mfma_f32_16x16x32_bf16 v[0:3], v[174:177], v[206:209], v[0:3]
	s_setprio 0
	s_barrier
; #define PG8_STAGE(bufoff, gbase, voff) do { _Pragma("unroll") for (int _i = 0; _i < 2; ++_i) \
;         __builtin_amdgcn_global_load_lds((const unsigned*)((const char*)(gbase) + (voff)[_i]), (LAS unsigned*)(lds + (bufoff) + ldsw + _i * 8192), 16, 0, 0); } while (0)
; #define PG8_LDA(dst, b, h) do { _Pragma("unroll") for (int m = 0; m < 4; ++m) _Pragma("unroll") for (int k = 0; k < 2; ++k) dst[m][k] = *(const LAS bf16x8*)(lds + PG8_SA(b, h) + aoff + m * 2048 + k * 1024); } while (0)
; #define PG8_LDB(dst, b, h) do { _Pragma("unroll") for (int n = 0; n < 2; ++n) _Pragma("unroll") for (int k = 0; k < 2; ++k) dst[n][k] = *(const LAS bf16x8*)(lds + PG8_SB(b, h) + boff + n * 2048 + k * 1024); } while (0)
; #define PG8_MMA(ai, bj, At, Bt) do { __builtin_amdgcn_s_setprio(1); _Pragma("unroll") for (int m = 0; m < 4; ++m) _Pragma("unroll") for (int n = 0; n < 2; ++n) _Pragma("unroll") for (int k = 0; k < 2; ++k) \
;         acc[ai][bj][m][n] = __builtin_amdgcn_mfma_f32_16x16x32_bf16(Bt[n][k], At[m][k], acc[ai][bj][m][n], 0, 0, 0); __builtin_amdgcn_s_setprio(0); } while (0)
; #define PG8_WAIT_V(n) asm volatile("s_waitcnt vmcnt(" #n ")" ::: "memory")
; #define PG8_WAIT_L(n) asm volatile("s_waitcnt lgkmcnt(" #n ")" ::: "memory")
; #define PG8_BAR __builtin_amdgcn_s_barrier()
; #define PG8_SCHED __builtin_amdgcn_sched_barrier(0)
; template <class Epi>
; __device__ __forceinline__ void gemm_phase(LAS unsigned char* lds, const Gemm g, const StaticOrder S, const Epi E) {
;     ...
;             PG8_LDB(B0, 1, 0); PG8_LDB(B1, 1, 1); PG8_SCHED; PG8_LDA(At, 1, 0); PG8_STAGE(PG8_SA(0, 1), a2 + hstepA, voffA);
;             PG8_WAIT_V(8); PG8_WAIT_L(0); PG8_BAR; PG8_MMA(0, 0, At, B0); PG8_MMA(0, 1, At, B1); PG8_BAR; PG8_SCHED;
;             PG8_LDA(At, 1, 1); PG8_STAGE(PG8_SB(1, 0), b3, voffB); PG8_STAGE(PG8_SB(1, 1), b3 + hstepB, voffB); PG8_STAGE(PG8_SA(1, 0), a3, voffA);
;             PG8_WAIT_V(8); PG8_WAIT_L(0); PG8_BAR; PG8_MMA(1, 0, At, B0); PG8_MMA(1, 1, At, B1); PG8_BAR; PG8_SCHED;
;         }
	s_add_i32 s68, 0, 0x18000
	s_add_i32 s69, 0, 0x1c000
	v_add_u32_e32 v152, s68, v161
	ds_read_b128 v[128:131], v152
	ds_read_b128 v[132:135], v152 offset:1024
	ds_read_b128 v[136:139], v152 offset:2048
	ds_read_b128 v[152:155], v152 offset:3072
	ds_read_b128 v[156:159], v254 offset:49152
	ds_read_b128 v[166:169], v254 offset:50176
	ds_read_b128 v[170:173], v254 offset:51200
	ds_read_b128 v[174:177], v254 offset:52224
	s_add_u32 s40, s40, 0x160000
	s_addc_u32 s41, s41, 0
	s_mov_b32 m0, s48
	ds_read_b128 v[178:181], v163 offset:32768
	ds_read_b128 v[182:185], v163 offset:33792
	ds_read_b128 v[186:189], v163 offset:34816
	ds_read_b128 v[190:193], v163 offset:35840
	ds_read_b128 v[194:197], v163 offset:36864
	ds_read_b128 v[198:201], v163 offset:37888
	ds_read_b128 v[202:205], v163 offset:38912
	ds_read_b128 v[206:209], v163 offset:39936
	global_load_lds_dwordx4 v140, s[40:41]
	s_mov_b32 m0, s49
	s_nop 0
	global_load_lds_dwordx4 v144, s[40:41]
	s_waitcnt vmcnt(8)
	s_waitcnt lgkmcnt(0)
	s_barrier
	s_setprio 1
	s_waitcnt lgkmcnt(0)
	v_mfma_f32_16x16x32_bf16 v[124:127], v[128:131], v[178:181], v[124:127]
	v_mfma_f32_16x16x32_bf16 v[120:123], v[136:139], v[178:181], v[120:123]
	v_mfma_f32_16x16x32_bf16 v[108:111], v[128:131], v[186:189], v[108:111]
	v_mfma_f32_16x16x32_bf16 v[104:107], v[136:139], v[186:189], v[104:107]
	v_mfma_f32_16x16x32_bf16 v[92:95], v[128:131], v[194:197], v[92:95]
	v_mfma_f32_16x16x32_bf16 v[88:91], v[136:139], v[194:197], v[88:91]
	v_mfma_f32_16x16x32_bf16 v[76:79], v[128:131], v[202:205], v[76:79]
	v_mfma_f32_16x16x32_bf16 v[72:75], v[136:139], v[202:205], v[72:75]
	v_mfma_f32_16x16x32_bf16 v[124:127], v[132:135], v[182:185], v[124:127]
	v_mfma_f32_16x16x32_bf16 v[120:123], v[152:155], v[182:185], v[120:123]
	v_mfma_f32_16x16x32_bf16 v[108:111], v[132:135], v[190:193], v[108:111]
	v_mfma_f32_16x16x32_bf16 v[104:107], v[152:155], v[190:193], v[104:107]
	v_mfma_f32_16x16x32_bf16 v[92:95], v[132:135], v[198:201], v[92:95]
	v_mfma_f32_16x16x32_bf16 v[88:91], v[152:155], v[198:201], v[88:91]
	v_mfma_f32_16x16x32_bf16 v[76:79], v[132:135], v[206:209], v[76:79]
	v_mfma_f32_16x16x32_bf16 v[72:75], v[152:155], v[206:209], v[72:75]
	s_setprio 0
	s_setprio 1
	v_mfma_f32_16x16x32_bf16 v[116:119], v[156:159], v[178:181], v[116:119]
	v_mfma_f32_16x16x32_bf16 v[112:115], v[170:173], v[178:181], v[112:115]
	v_mfma_f32_16x16x32_bf16 v[100:103], v[156:159], v[186:189], v[100:103]
	v_mfma_f32_16x16x32_bf16 v[96:99], v[170:173], v[186:189], v[96:99]
	v_mfma_f32_16x16x32_bf16 v[84:87], v[156:159], v[194:197], v[84:87]
	v_mfma_f32_16x16x32_bf16 v[80:83], v[170:173], v[194:197], v[80:83]
	v_mfma_f32_16x16x32_bf16 v[68:71], v[156:159], v[202:205], v[68:71]
	v_mfma_f32_16x16x32_bf16 v[64:67], v[170:173], v[202:205], v[64:67]
	v_mfma_f32_16x16x32_bf16 v[116:119], v[166:169], v[182:185], v[116:119]
	v_mfma_f32_16x16x32_bf16 v[112:115], v[174:177], v[182:185], v[112:115]
	v_mfma_f32_16x16x32_bf16 v[100:103], v[166:169], v[190:193], v[100:103]
	v_mfma_f32_16x16x32_bf16 v[96:99], v[174:177], v[190:193], v[96:99]
	v_mfma_f32_16x16x32_bf16 v[84:87], v[166:169], v[198:201], v[84:87]
	v_mfma_f32_16x16x32_bf16 v[80:83], v[174:177], v[198:201], v[80:83]
	v_mfma_f32_16x16x32_bf16 v[68:71], v[166:169], v[206:209], v[68:71]
	v_mfma_f32_16x16x32_bf16 v[64:67], v[174:177], v[206:209], v[64:67]
	s_setprio 0
	s_barrier
	s_add_u32 s36, s36, s38
	s_addc_u32 s37, s37, s39
	s_add_i32 s38, s68, s45
	s_mov_b32 m0, s38
	ds_read_b128 v[178:181], v163 offset:49152
	ds_read_b128 v[182:185], v163 offset:50176
	ds_read_b128 v[186:189], v163 offset:51200
	ds_read_b128 v[190:193], v163 offset:52224
	ds_read_b128 v[194:197], v163 offset:53248
	ds_read_b128 v[198:201], v163 offset:54272
	ds_read_b128 v[202:205], v163 offset:55296
	ds_read_b128 v[206:209], v163 offset:56320
	global_load_lds_dwordx4 v142, s[36:37]
	s_add_i32 m0, s38, 0x2000
	s_nop 0
	global_load_lds_dwordx4 v146, s[36:37]
	s_add_u32 s36, s36, 0x160000
	s_addc_u32 s37, s37, 0
	s_add_i32 s38, s69, s45
	s_mov_b32 m0, s38
	s_nop 0
	global_load_lds_dwordx4 v142, s[36:37]
	s_add_i32 m0, s38, 0x2000
	s_nop 0
	global_load_lds_dwordx4 v146, s[36:37]
	s_mov_b32 m0, s51
	s_nop 0
	global_load_lds_dwordx4 v140, s[42:43]
	s_mov_b32 m0, s52
	s_nop 0
	global_load_lds_dwordx4 v144, s[42:43]
	s_waitcnt vmcnt(8)
	s_waitcnt lgkmcnt(0)
	s_barrier
	s_setprio 1
	s_waitcnt lgkmcnt(0)
	v_mfma_f32_16x16x32_bf16 v[60:63], v[128:131], v[178:181], v[60:63]
	v_mfma_f32_16x16x32_bf16 v[56:59], v[136:139], v[178:181], v[56:59]
	v_mfma_f32_16x16x32_bf16 v[44:47], v[128:131], v[186:189], v[44:47]
	v_mfma_f32_16x16x32_bf16 v[40:43], v[136:139], v[186:189], v[40:43]
	v_mfma_f32_16x16x32_bf16 v[28:31], v[128:131], v[194:197], v[28:31]
	v_mfma_f32_16x16x32_bf16 v[24:27], v[136:139], v[194:197], v[24:27]
	v_mfma_f32_16x16x32_bf16 v[12:15], v[128:131], v[202:205], v[12:15]
	v_mfma_f32_16x16x32_bf16 v[8:11], v[136:139], v[202:205], v[8:11]
	v_mfma_f32_16x16x32_bf16 v[60:63], v[132:135], v[182:185], v[60:63]
	v_mfma_f32_16x16x32_bf16 v[56:59], v[152:155], v[182:185], v[56:59]
	v_mfma_f32_16x16x32_bf16 v[44:47], v[132:135], v[190:193], v[44:47]
	v_mfma_f32_16x16x32_bf16 v[40:43], v[152:155], v[190:193], v[40:43]
	v_mfma_f32_16x16x32_bf16 v[28:31], v[132:135], v[198:201], v[28:31]
	v_mfma_f32_16x16x32_bf16 v[24:27], v[152:155], v[198:201], v[24:27]
	v_mfma_f32_16x16x32_bf16 v[12:15], v[132:135], v[206:209], v[12:15]
	v_mfma_f32_16x16x32_bf16 v[8:11], v[152:155], v[206:209], v[8:11]
	s_setprio 0
	s_setprio 1
	v_mfma_f32_16x16x32_bf16 v[52:55], v[156:159], v[178:181], v[52:55]
	v_mfma_f32_16x16x32_bf16 v[48:51], v[170:173], v[178:181], v[48:51]
	v_mfma_f32_16x16x32_bf16 v[36:39], v[156:159], v[186:189], v[36:39]
	v_mfma_f32_16x16x32_bf16 v[32:35], v[170:173], v[186:189], v[32:35]
	v_mfma_f32_16x16x32_bf16 v[20:23], v[156:159], v[194:197], v[20:23]
	v_mfma_f32_16x16x32_bf16 v[16:19], v[170:173], v[194:197], v[16:19]
	v_mfma_f32_16x16x32_bf16 v[4:7], v[156:159], v[202:205], v[4:7]
	v_mfma_f32_16x16x32_bf16 v[0:3], v[170:173], v[202:205], v[0:3]
	v_mfma_f32_16x16x32_bf16 v[52:55], v[166:169], v[182:185], v[52:55]
	v_mfma_f32_16x16x32_bf16 v[48:51], v[174:177], v[182:185], v[48:51]
	v_mfma_f32_16x16x32_bf16 v[36:39], v[166:169], v[190:193], v[36:39]
	v_mfma_f32_16x16x32_bf16 v[32:35], v[174:177], v[190:193], v[32:35]
	v_mfma_f32_16x16x32_bf16 v[20:23], v[166:169], v[198:201], v[20:23]
	v_mfma_f32_16x16x32_bf16 v[16:19], v[174:177], v[198:201], v[16:19]
	v_mfma_f32_16x16x32_bf16 v[4:7], v[166:169], v[206:209], v[4:7]
	v_mfma_f32_16x16x32_bf16 v[0:3], v[174:177], v[206:209], v[0:3]
	s_setprio 0
	s_barrier
	s_cmpk_gt_u32 s66, 0x55
	s_mov_b32 s66, s67
	s_cbranch_scc1 .LBB0_1563

; __global__ void __launch_bounds__(NTHR, 2) mega_fwd(Params p) {
	.amdhsa_kernel _Z8mega_fwd6Params
		.amdhsa_group_segment_fixed_size 0
		.amdhsa_private_segment_fixed_size 0
		.amdhsa_kernarg_size 456
		.amdhsa_user_sgpr_count 2
		.amdhsa_user_sgpr_dispatch_ptr 0
		.amdhsa_user_sgpr_queue_ptr 0
		.amdhsa_user_sgpr_kernarg_segment_ptr 1
		.amdhsa_user_sgpr_dispatch_id 0
		.amdhsa_user_sgpr_kernarg_preload_length 0
		.amdhsa_user_sgpr_kernarg_preload_offset 0
		.amdhsa_user_sgpr_private_segment_size 0
		.amdhsa_uses_dynamic_stack 0
		.amdhsa_enable_private_segment 0
		.amdhsa_system_sgpr_workgroup_id_x 1
		.amdhsa_system_sgpr_workgroup_id_y 0
		.amdhsa_system_sgpr_workgroup_id_z 0
		.amdhsa_system_sgpr_workgroup_info 0
		.amdhsa_system_vgpr_workitem_id 2
		.amdhsa_next_free_vgpr 255
		.amdhsa_next_free_sgpr 100
		.amdhsa_accum_offset 256
		.amdhsa_reserve_vcc 1
		.amdhsa_float_round_mode_32 0
		.amdhsa_float_round_mode_16_64 0
		.amdhsa_float_denorm_mode_32 3
		.amdhsa_float_denorm_mode_16_64 3
		.amdhsa_dx10_clamp 1
		.amdhsa_ieee_mode 1
		.amdhsa_fp16_overflow 0
		.amdhsa_tg_split 0
		.amdhsa_exception_fp_ieee_invalid_op 0
		.amdhsa_exception_fp_denorm_src 0
		.amdhsa_exception_fp_ieee_div_zero 0
		.amdhsa_exception_fp_ieee_overflow 0
		.amdhsa_exception_fp_ieee_underflow 0
		.amdhsa_exception_fp_ieee_inexact 0
		.amdhsa_exception_int_div_zero 0
	.end_amdhsa_kernel

; __global__ void __launch_bounds__(NTHR, 2) mega_fwd(Params p) {
amdhsa.kernels:
  - .agpr_count:     0
    .args:
      - .offset:         0
        .size:           200
        .value_kind:     by_value
      - .offset:         200
        .size:           4
        .value_kind:     hidden_block_count_x
      - .offset:         204
        .size:           4
        .value_kind:     hidden_block_count_y
      - .offset:         208
        .size:           4
        .value_kind:     hidden_block_count_z
      - .offset:         212
        .size:           2
        .value_kind:     hidden_group_size_x
      - .offset:         214
        .size:           2
        .value_kind:     hidden_group_size_y
      - .offset:         216
        .size:           2
        .value_kind:     hidden_group_size_z
      - .offset:         218
        .size:           2
        .value_kind:     hidden_remainder_x
      - .offset:         220
        .size:           2
        .value_kind:     hidden_remainder_y
      - .offset:         222
        .size:           2
        .value_kind:     hidden_remainder_z
      - .offset:         240
        .size:           8
        .value_kind:     hidden_global_offset_x
      - .offset:         248
        .size:           8
        .value_kind:     hidden_global_offset_y
      - .offset:         256
        .size:           8
        .value_kind:     hidden_global_offset_z
      - .offset:         264
        .size:           2
        .value_kind:     hidden_grid_dims
      - .offset:         288
        .size:           8
        .value_kind:     hidden_multigrid_sync_arg
      - .offset:         320
        .size:           4
        .value_kind:     hidden_dynamic_lds_size
    .group_segment_fixed_size: 0
    .kernarg_segment_align: 8
    .kernarg_segment_size: 456
    .language:       OpenCL C
    .language_version:
      - 2
      - 0
    .max_flat_workgroup_size: 512
    .name:           _Z8mega_fwd6Params
    .private_segment_fixed_size: 0
    .sgpr_count:     106
    .sgpr_spill_count: 148
    .symbol:         _Z8mega_fwd6Params.kd
    .uniform_work_group_size: 1
    .uses_dynamic_stack: false
    .vgpr_count:     255
    .vgpr_spill_count: 0
    .wavefront_size: 64
